# attention loops: on has-next path wait vmcnt(N+12) for gain loads so the next-unit K/V prefetch stays in flight during the unit math (was drained by vmcnt(0))
# speedup vs baseline: 1.0192x; 1.0147x over previous
; #define LAS __attribute__((address_space(3)))
; __device__ __forceinline__ unsigned pk2(float lo, float hi) { f32x2_t v = {lo, hi}; bf16x2_t b = __builtin_convertvector(v, bf16x2_t); return __builtin_bit_cast(unsigned, b); }
; template <int CTRL> __device__ __forceinline__ float dpp_movf(float v) { return __builtin_bit_cast(float, dpp_mov<CTRL>(__builtin_bit_cast(unsigned, v))); }
; template <bool FUSED> __device__ __forceinline__ void attn_phase(const Args& a, LAS unsigned char* lds, int tid, int lane, int wave) {
;     ...
;         {
;             const int ch = tid & 7;
;             const f32x4 g0 = *(const f32x4*)(a.kw + hd * 64 + ch * 8), g1 = *(const f32x4*)(a.kw + hd * 64 + ch * 8 + 4);
; #pragma unroll
;             for (int i = 0; i < 6; ++i) { const int row = (tid + 512 * i) >> 3;
;                 const float e0 = bflo(kv[i].x), e1 = bfhi(kv[i].x), e2 = bflo(kv[i].y), e3 = bfhi(kv[i].y), e4 = bflo(kv[i].z), e5 = bfhi(kv[i].z), e6 = bflo(kv[i].w), e7 = bfhi(kv[i].w);
;                 float ss = (e0 * e0 + e1 * e1) + (e2 * e2 + e3 * e3) + (e4 * e4 + e5 * e5) + (e6 * e6 + e7 * e7);
;                 ss += dpp_movf<0xB1>(ss); ss += dpp_movf<0x4E>(ss); ss += dpp_movf<0x141>(ss);
;                 const float rk = __builtin_amdgcn_rsqf(ss * (1.f / 64.f) + 1e-6f);
;                 u32x4 wv; wv.x = pk2(e0 * rk * g0.x, e1 * rk * g0.y); wv.y = pk2(e2 * rk * g0.z, e3 * rk * g0.w); wv.z = pk2(e4 * rk * g1.x, e5 * rk * g1.y); wv.w = pk2(e6 * rk * g1.z, e7 * rk * g1.w);
;                 *(LAS u32x4*)(lds + row * KP + ch * 16) = wv;
;                 *(LAS u32x4*)(lds + LDS_VOFF + row * VP + ch * 16) = vv[i];
;                 if (i & 1) __builtin_amdgcn_sched_barrier(0); }
;         }
.LBB0_280:
	s_ashr_i32 s6, s67, 5
	s_lshr_b32 s7, s6, 28
	s_add_i32 s7, s6, s7
	s_and_b32 s7, s7, -16
	s_sub_i32 s66, s6, s7
	s_add_i32 s68, s66, 8
	s_lshl_b32 s6, s68, 6
	s_ashr_i32 s7, s6, 31
	s_lshl_b64 s[6:7], s[6:7], 2
	v_lshl_add_u64 v[0:1], v[164:165], 0, s[6:7]
	global_load_dwordx4 v[4:7], v[0:1], off
	s_nop 0
	global_load_dwordx4 v[0:3], v[0:1], off offset:16
	s_waitcnt vmcnt(17)
	v_and_b32_e32 v9, 0xffff0000, v67
	v_and_b32_e32 v11, 0xffff0000, v66
	v_and_b32_e32 v13, 0xffff0000, v65
	v_and_b32_e32 v15, 0xffff0000, v64
	s_waitcnt vmcnt(15)
	v_and_b32_e32 v21, 0xffff0000, v73
	v_and_b32_e32 v23, 0xffff0000, v72
	v_lshlrev_b32_e32 v8, 16, v67
	v_lshlrev_b32_e32 v10, 16, v66
	v_lshlrev_b32_e32 v12, 16, v65
	v_lshlrev_b32_e32 v14, 16, v64
	v_and_b32_e32 v17, 0xffff0000, v75
	v_and_b32_e32 v19, 0xffff0000, v74
	v_lshlrev_b32_e32 v20, 16, v73
	v_lshlrev_b32_e32 v22, 16, v72
	v_mov_b32_e32 v26, v9
	v_mov_b32_e32 v27, v11
	v_mov_b32_e32 v30, v15
	v_mov_b32_e32 v31, v13
	v_mov_b32_e32 v38, v23
	v_mov_b32_e32 v39, v21
	v_lshlrev_b32_e32 v16, 16, v75
	v_lshlrev_b32_e32 v18, 16, v74
	v_mov_b32_e32 v24, v8
	v_mov_b32_e32 v25, v10
	v_mov_b32_e32 v28, v14
	v_mov_b32_e32 v29, v12
	v_mov_b32_e32 v34, v17
	v_mov_b32_e32 v35, v19
	v_mov_b32_e32 v36, v22
	v_mov_b32_e32 v37, v20
	v_pk_mul_f32 v[26:27], v[26:27], v[26:27]
	v_pk_mul_f32 v[30:31], v[30:31], v[30:31]
	v_pk_mul_f32 v[38:39], v[38:39], v[38:39]
	v_mov_b32_e32 v32, v16
	v_mov_b32_e32 v33, v18
	v_pk_mul_f32 v[34:35], v[34:35], v[34:35]
	v_pk_fma_f32 v[24:25], v[24:25], v[24:25], v[26:27]
	v_pk_fma_f32 v[26:27], v[28:29], v[28:29], v[30:31]
	v_pk_fma_f32 v[30:31], v[36:37], v[36:37], v[38:39]
	v_pk_fma_f32 v[28:29], v[32:33], v[32:33], v[34:35]
	v_add_f32_e32 v26, v26, v27
	v_add_f32_e32 v27, v30, v31
	v_add_f32_e32 v25, v25, v26
	v_add_f32_e32 v26, v29, v27
	v_add_f32_e32 v24, v24, v25
	v_add_f32_e32 v25, v28, v26
	s_nop 0
	v_add_f32_dpp v24, v24, v24 quad_perm:[1,0,3,2] row_mask:0xf bank_mask:0xf bound_ctrl:1
	v_add_f32_dpp v25, v25, v25 quad_perm:[1,0,3,2] row_mask:0xf bank_mask:0xf bound_ctrl:1
	s_nop 0
	v_add_f32_dpp v24, v24, v24 quad_perm:[2,3,0,1] row_mask:0xf bank_mask:0xf bound_ctrl:1
	v_add_f32_dpp v25, v25, v25 quad_perm:[2,3,0,1] row_mask:0xf bank_mask:0xf bound_ctrl:1
	s_nop 0
	v_add_f32_dpp v24, v24, v24 row_half_mirror row_mask:0xf bank_mask:0xf bound_ctrl:1
	v_add_f32_dpp v25, v25, v25 row_half_mirror row_mask:0xf bank_mask:0xf bound_ctrl:1
	v_fmamk_f32 v24, v24, 0x3c800000, v176
	v_fmamk_f32 v25, v25, 0x3c800000, v176
	v_rsq_f32_e32 v24, v24
	v_rsq_f32_e32 v26, v25
	v_pk_mul_f32 v[14:15], v[24:25], v[14:15] op_sel_hi:[0,1]
	v_pk_mul_f32 v[12:13], v[24:25], v[12:13] op_sel_hi:[0,1]
	v_pk_mul_f32 v[10:11], v[24:25], v[10:11] op_sel_hi:[0,1]
	v_pk_mul_f32 v[8:9], v[24:25], v[8:9] op_sel_hi:[0,1]
	v_pk_mul_f32 v[22:23], v[26:27], v[22:23] op_sel_hi:[0,1]
	v_pk_mul_f32 v[20:21], v[26:27], v[20:21] op_sel_hi:[0,1]
	v_pk_mul_f32 v[18:19], v[26:27], v[18:19] op_sel_hi:[0,1]
	v_pk_mul_f32 v[16:17], v[26:27], v[16:17] op_sel_hi:[0,1]
	s_waitcnt vmcnt(1)
	v_pk_mul_f32 v[14:15], v[4:5], v[14:15]
	v_pk_mul_f32 v[12:13], v[6:7], v[12:13]
	s_waitcnt vmcnt(0)
	v_pk_mul_f32 v[10:11], v[0:1], v[10:11]
	v_pk_mul_f32 v[24:25], v[2:3], v[8:9]
	v_pk_mul_f32 v[22:23], v[4:5], v[22:23]
	v_pk_mul_f32 v[20:21], v[6:7], v[20:21]
	v_pk_mul_f32 v[18:19], v[0:1], v[18:19]
	v_pk_mul_f32 v[16:17], v[2:3], v[16:17]
	v_cvt_pk_bf16_f32 v8, v14, v15
	v_cvt_pk_bf16_f32 v9, v12, v13
	v_cvt_pk_bf16_f32 v10, v10, v11
	v_cvt_pk_bf16_f32 v11, v24, v25
	v_cvt_pk_bf16_f32 v12, v22, v23
	v_cvt_pk_bf16_f32 v13, v20, v21
	v_cvt_pk_bf16_f32 v14, v18, v19
	v_cvt_pk_bf16_f32 v15, v16, v17
	ds_write_b128 v177, v[8:11]
	ds_write_b128 v188, v[68:71] offset:55296
	ds_write_b128 v189, v[12:15]
	ds_write_b128 v190, v[76:79] offset:55296
	v_and_b32_e32 v13, 0xffff0000, v83
	v_and_b32_e32 v11, 0xffff0000, v82
	v_lshlrev_b32_e32 v12, 16, v83
	v_lshlrev_b32_e32 v10, 16, v82
	v_mov_b32_e32 v14, v13
	v_mov_b32_e32 v15, v11
	v_mov_b32_e32 v8, v12
	v_mov_b32_e32 v9, v10
	v_pk_mul_f32 v[14:15], v[14:15], v[14:15]
	v_and_b32_e32 v17, 0xffff0000, v80
	v_pk_fma_f32 v[8:9], v[8:9], v[8:9], v[14:15]
	v_and_b32_e32 v15, 0xffff0000, v81
	v_lshlrev_b32_e32 v14, 16, v81
	v_lshlrev_b32_e32 v16, 16, v80
	v_mov_b32_e32 v20, v17
	v_mov_b32_e32 v21, v15
	v_mov_b32_e32 v18, v16
	v_mov_b32_e32 v19, v14
	v_pk_mul_f32 v[20:21], v[20:21], v[20:21]
	v_and_b32_e32 v23, 0xffff0000, v96
	v_pk_fma_f32 v[18:19], v[18:19], v[18:19], v[20:21]
	v_lshlrev_b32_e32 v22, 16, v96
	v_add_f32_e32 v18, v18, v19
	v_add_f32_e32 v9, v9, v18
	v_add_f32_e32 v8, v8, v9
	v_mov_b32_e32 v26, v23
	v_mov_b32_e32 v24, v22
	v_add_f32_dpp v8, v8, v8 quad_perm:[1,0,3,2] row_mask:0xf bank_mask:0xf bound_ctrl:1
	s_nop 1
	v_add_f32_dpp v8, v8, v8 quad_perm:[2,3,0,1] row_mask:0xf bank_mask:0xf bound_ctrl:1
	s_nop 1
	v_add_f32_dpp v8, v8, v8 row_half_mirror row_mask:0xf bank_mask:0xf bound_ctrl:1
	v_fmamk_f32 v8, v8, 0x3c800000, v176
	v_rsq_f32_e32 v18, v8
	s_nop 0
	v_pk_mul_f32 v[8:9], v[18:19], v[16:17] op_sel_hi:[0,1]
	v_pk_mul_f32 v[14:15], v[18:19], v[14:15] op_sel_hi:[0,1]
	v_pk_mul_f32 v[8:9], v[4:5], v[8:9]
	v_pk_mul_f32 v[14:15], v[6:7], v[14:15]
	v_cvt_pk_bf16_f32 v8, v8, v9
	v_cvt_pk_bf16_f32 v9, v14, v15
	v_and_b32_e32 v15, 0xffff0000, v99
	v_and_b32_e32 v17, 0xffff0000, v98
	v_lshlrev_b32_e32 v14, 16, v99
	v_lshlrev_b32_e32 v16, 16, v98
	v_mov_b32_e32 v20, v15
	v_mov_b32_e32 v21, v17
	v_pk_mul_f32 v[10:11], v[18:19], v[10:11] op_sel_hi:[0,1]
	v_pk_mul_f32 v[12:13], v[18:19], v[12:13] op_sel_hi:[0,1]
	v_mov_b32_e32 v18, v14
	v_mov_b32_e32 v19, v16
	v_pk_mul_f32 v[20:21], v[20:21], v[20:21]
; #define LAS __attribute__((address_space(3)))
; template <int CTRL> __device__ __forceinline__ float dpp_movf(float v) { return __builtin_bit_cast(float, dpp_mov<CTRL>(__builtin_bit_cast(unsigned, v))); }
; template <bool FUSED> __device__ __forceinline__ void attn_phase(const Args& a, LAS unsigned char* lds, int tid, int lane, int wave) {
;     ...
;             for (int i = 0; i < 6; ++i) { const int row = (tid + 512 * i) >> 3;
;                 const float e0 = bflo(kv[i].x), e1 = bfhi(kv[i].x), e2 = bflo(kv[i].y), e3 = bfhi(kv[i].y), e4 = bflo(kv[i].z), e5 = bfhi(kv[i].z), e6 = bflo(kv[i].w), e7 = bfhi(kv[i].w);
;                 float ss = (e0 * e0 + e1 * e1) + (e2 * e2 + e3 * e3) + (e4 * e4 + e5 * e5) + (e6 * e6 + e7 * e7);
;                 ss += dpp_movf<0xB1>(ss); ss += dpp_movf<0x4E>(ss); ss += dpp_movf<0x141>(ss);
;                 const float rk = __builtin_amdgcn_rsqf(ss * (1.f / 64.f) + 1e-6f);
;                 u32x4 wv; wv.x = pk2(e0 * rk * g0.x, e1 * rk * g0.y); wv.y = pk2(e2 * rk * g0.z, e3 * rk * g0.w); wv.z = pk2(e4 * rk * g1.x, e5 * rk * g1.y); wv.w = pk2(e6 * rk * g1.z, e7 * rk * g1.w);
;                 *(LAS u32x4*)(lds + row * KP + ch * 16) = wv;
;                 *(LAS u32x4*)(lds + LDS_VOFF + row * VP + ch * 16) = vv[i];
;                 if (i & 1) __builtin_amdgcn_sched_barrier(0); }
;         }
;         bf16x8 qf[4];
;         {
;             float ss = 0.f;
; #pragma unroll
;             for (int ks = 0; ks < 4; ++ks)
; #pragma unroll
;                 for (int e = 0; e < 4; ++e) { const float lo = bflo(qv[ks][e]), hi = bfhi(qv[ks][e]); ss += lo * lo + hi * hi; }
;             ss += __shfl_xor(ss, 32);
;             const float rq = 0.125f * LOG2E * __builtin_amdgcn_rsqf(ss * (1.f / 64.f) + 1e-6f);
; #pragma unroll
;             for (int ks = 0; ks < 4; ++ks) { const f32x4 g0 = *(const f32x4*)(a.qw + hd * 64 + 16 * ks + 8 * h), g1 = *(const f32x4*)(a.qw + hd * 64 + 16 * ks + 8 * h + 4); u32x4 wv;
;                 wv.x = pk2(bflo(qv[ks].x) * rq * g0.x, bfhi(qv[ks].x) * rq * g0.y); wv.y = pk2(bflo(qv[ks].y) * rq * g0.z, bfhi(qv[ks].y) * rq * g0.w);
;                 wv.z = pk2(bflo(qv[ks].z) * rq * g1.x, bfhi(qv[ks].z) * rq * g1.y); wv.w = pk2(bflo(qv[ks].w) * rq * g1.z, bfhi(qv[ks].w) * rq * g1.w);
;                 qf[ks] = __builtin_bit_cast(bf16x8, wv); }
;         }
;         const float mb = ((const float*)(a.ws + WS_RS))[hd];
	v_pk_mul_f32 v[10:11], v[0:1], v[10:11]
	v_pk_fma_f32 v[18:19], v[18:19], v[18:19], v[20:21]
	v_and_b32_e32 v21, 0xffff0000, v97
	v_lshlrev_b32_e32 v20, 16, v97
	v_mov_b32_e32 v27, v21
	v_mov_b32_e32 v25, v20
	v_pk_mul_f32 v[26:27], v[26:27], v[26:27]
	v_cvt_pk_bf16_f32 v10, v10, v11
	v_pk_fma_f32 v[24:25], v[24:25], v[24:25], v[26:27]
	v_pk_mul_f32 v[12:13], v[2:3], v[12:13]
	v_add_f32_e32 v11, v24, v25
	v_add_f32_e32 v11, v19, v11
	v_add_f32_e32 v11, v18, v11
	s_nop 1
	v_add_f32_dpp v11, v11, v11 quad_perm:[1,0,3,2] row_mask:0xf bank_mask:0xf bound_ctrl:1
	s_nop 1
	v_add_f32_dpp v11, v11, v11 quad_perm:[2,3,0,1] row_mask:0xf bank_mask:0xf bound_ctrl:1
	s_nop 1
	v_add_f32_dpp v11, v11, v11 row_half_mirror row_mask:0xf bank_mask:0xf bound_ctrl:1
	v_fmamk_f32 v11, v11, 0x3c800000, v176
	v_rsq_f32_e32 v18, v11
	v_cvt_pk_bf16_f32 v11, v12, v13
	ds_write_b128 v191, v[8:11]
	ds_write_b128 v192, v[84:87] offset:55296
	v_pk_mul_f32 v[8:9], v[18:19], v[22:23] op_sel_hi:[0,1]
	v_pk_mul_f32 v[10:11], v[18:19], v[20:21] op_sel_hi:[0,1]
	v_pk_mul_f32 v[8:9], v[4:5], v[8:9]
	v_pk_mul_f32 v[10:11], v[6:7], v[10:11]
	v_cvt_pk_bf16_f32 v8, v8, v9
	v_cvt_pk_bf16_f32 v9, v10, v11
	v_pk_mul_f32 v[10:11], v[18:19], v[16:17] op_sel_hi:[0,1]
	v_pk_mul_f32 v[12:13], v[18:19], v[14:15] op_sel_hi:[0,1]
	v_pk_mul_f32 v[10:11], v[0:1], v[10:11]
	v_pk_mul_f32 v[12:13], v[2:3], v[12:13]
	v_cvt_pk_bf16_f32 v10, v10, v11
	v_cvt_pk_bf16_f32 v11, v12, v13
	ds_write_b128 v193, v[8:11]
	ds_write_b128 v194, v[104:107] offset:55296
	v_and_b32_e32 v13, 0xffff0000, v115
	v_and_b32_e32 v11, 0xffff0000, v114
	v_lshlrev_b32_e32 v12, 16, v115
	v_lshlrev_b32_e32 v10, 16, v114
	v_mov_b32_e32 v14, v13
	v_mov_b32_e32 v15, v11
	v_mov_b32_e32 v8, v12
	v_mov_b32_e32 v9, v10
	v_pk_mul_f32 v[14:15], v[14:15], v[14:15]
	v_and_b32_e32 v17, 0xffff0000, v112
	v_pk_fma_f32 v[8:9], v[8:9], v[8:9], v[14:15]
	v_and_b32_e32 v15, 0xffff0000, v113
	v_lshlrev_b32_e32 v14, 16, v113
	v_lshlrev_b32_e32 v16, 16, v112
	v_mov_b32_e32 v20, v17
	v_mov_b32_e32 v21, v15
	v_mov_b32_e32 v18, v16
	v_mov_b32_e32 v19, v14
	v_pk_mul_f32 v[20:21], v[20:21], v[20:21]
	v_and_b32_e32 v23, 0xffff0000, v120
	v_pk_fma_f32 v[18:19], v[18:19], v[18:19], v[20:21]
	v_lshlrev_b32_e32 v22, 16, v120
	v_add_f32_e32 v18, v18, v19
	v_add_f32_e32 v9, v9, v18
	v_add_f32_e32 v8, v8, v9
	v_mov_b32_e32 v26, v23
	v_mov_b32_e32 v24, v22
	v_add_f32_dpp v8, v8, v8 quad_perm:[1,0,3,2] row_mask:0xf bank_mask:0xf bound_ctrl:1
	s_nop 1
	v_add_f32_dpp v8, v8, v8 quad_perm:[2,3,0,1] row_mask:0xf bank_mask:0xf bound_ctrl:1
	s_nop 1
	v_add_f32_dpp v8, v8, v8 row_half_mirror row_mask:0xf bank_mask:0xf bound_ctrl:1
	v_fmamk_f32 v8, v8, 0x3c800000, v176
	v_rsq_f32_e32 v18, v8
	s_nop 0
	v_pk_mul_f32 v[8:9], v[18:19], v[16:17] op_sel_hi:[0,1]
	v_pk_mul_f32 v[14:15], v[18:19], v[14:15] op_sel_hi:[0,1]
	v_pk_mul_f32 v[8:9], v[4:5], v[8:9]
	v_pk_mul_f32 v[14:15], v[6:7], v[14:15]
	v_cvt_pk_bf16_f32 v8, v8, v9
	v_cvt_pk_bf16_f32 v9, v14, v15
	v_and_b32_e32 v15, 0xffff0000, v123
	v_and_b32_e32 v17, 0xffff0000, v122
	v_lshlrev_b32_e32 v14, 16, v123
	v_lshlrev_b32_e32 v16, 16, v122
	v_mov_b32_e32 v20, v15
	v_mov_b32_e32 v21, v17
	v_pk_mul_f32 v[10:11], v[18:19], v[10:11] op_sel_hi:[0,1]
	v_pk_mul_f32 v[12:13], v[18:19], v[12:13] op_sel_hi:[0,1]
	v_mov_b32_e32 v18, v14
	v_mov_b32_e32 v19, v16
	v_pk_mul_f32 v[20:21], v[20:21], v[20:21]
	v_pk_mul_f32 v[10:11], v[0:1], v[10:11]
	v_pk_fma_f32 v[18:19], v[18:19], v[18:19], v[20:21]
	v_and_b32_e32 v21, 0xffff0000, v121
	v_lshlrev_b32_e32 v20, 16, v121
	v_mov_b32_e32 v27, v21
	v_mov_b32_e32 v25, v20
	v_pk_mul_f32 v[26:27], v[26:27], v[26:27]
	v_cvt_pk_bf16_f32 v10, v10, v11
	v_pk_fma_f32 v[24:25], v[24:25], v[24:25], v[26:27]
	v_pk_mul_f32 v[12:13], v[2:3], v[12:13]
	v_add_f32_e32 v11, v24, v25
	v_add_f32_e32 v11, v19, v11
	v_add_f32_e32 v11, v18, v11
	s_nop 1
	v_add_f32_dpp v11, v11, v11 quad_perm:[1,0,3,2] row_mask:0xf bank_mask:0xf bound_ctrl:1
	s_nop 1
	v_add_f32_dpp v11, v11, v11 quad_perm:[2,3,0,1] row_mask:0xf bank_mask:0xf bound_ctrl:1
	s_nop 1
	v_add_f32_dpp v11, v11, v11 row_half_mirror row_mask:0xf bank_mask:0xf bound_ctrl:1
	v_fmamk_f32 v11, v11, 0x3c800000, v176
	v_rsq_f32_e32 v18, v11
	v_cvt_pk_bf16_f32 v11, v12, v13
	ds_write_b128 v195, v[8:11]
	ds_write_b128 v196, v[116:119] offset:55296
	v_pk_mul_f32 v[8:9], v[18:19], v[22:23] op_sel_hi:[0,1]
	v_pk_mul_f32 v[4:5], v[4:5], v[8:9]
	v_pk_mul_f32 v[8:9], v[18:19], v[20:21] op_sel_hi:[0,1]
	v_pk_mul_f32 v[6:7], v[6:7], v[8:9]
	v_cvt_pk_bf16_f32 v4, v4, v5
	v_cvt_pk_bf16_f32 v5, v6, v7
	v_pk_mul_f32 v[6:7], v[18:19], v[16:17] op_sel_hi:[0,1]
	v_pk_mul_f32 v[0:1], v[0:1], v[6:7]
	s_nop 0
	v_cvt_pk_bf16_f32 v6, v0, v1
	v_pk_mul_f32 v[0:1], v[18:19], v[14:15] op_sel_hi:[0,1]
	v_pk_mul_f32 v[0:1], v[2:3], v[0:1]
	s_nop 0
	v_cvt_pk_bf16_f32 v7, v0, v1
	ds_write_b128 v197, v[4:7]
	ds_write_b128 v198, v[124:127] offset:55296
	v_lshl_add_u64 v[0:1], v[166:167], 0, s[6:7]
	global_load_dwordx4 v[20:23], v[0:1], off offset:16
	global_load_dwordx4 v[24:27], v[0:1], off
	global_load_dwordx4 v[12:15], v[0:1], off offset:80
	global_load_dwordx4 v[16:19], v[0:1], off offset:64
	global_load_dwordx4 v[4:7], v[0:1], off offset:144
	global_load_dwordx4 v[8:11], v[0:1], off offset:128
	global_load_dwordx4 v[32:35], v[0:1], off offset:208
	s_nop 0
	global_load_dwordx4 v[0:3], v[0:1], off offset:192
	s_ashr_i32 s69, s68, 31
	s_lshl_b64 s[6:7], s[68:69], 2
	s_add_u32 s6, s87, s6
	s_addc_u32 s7, s88, s7
	global_load_dword v222, v147, s[6:7]
	v_and_b32_e32 v29, 0xffff0000, v111
	v_lshlrev_b32_e32 v28, 16, v110
	v_and_b32_e32 v39, 0xffff0000, v110
	v_mov_b32_e32 v38, v29
; __device__ __forceinline__ unsigned pk2(float lo, float hi) { f32x2_t v = {lo, hi}; bf16x2_t b = __builtin_convertvector(v, bf16x2_t); return __builtin_bit_cast(unsigned, b); }
; template <bool FUSED> __device__ __forceinline__ void attn_phase(const Args& a, LAS unsigned char* lds, int tid, int lane, int wave) {
;     ...
;             float ss = 0.f;
; #pragma unroll
;             for (int ks = 0; ks < 4; ++ks)
; #pragma unroll
;                 for (int e = 0; e < 4; ++e) { const float lo = bflo(qv[ks][e]), hi = bfhi(qv[ks][e]); ss += lo * lo + hi * hi; }
;             ss += __shfl_xor(ss, 32);
;             const float rq = 0.125f * LOG2E * __builtin_amdgcn_rsqf(ss * (1.f / 64.f) + 1e-6f);
; #pragma unroll
;             for (int ks = 0; ks < 4; ++ks) { const f32x4 g0 = *(const f32x4*)(a.qw + hd * 64 + 16 * ks + 8 * h), g1 = *(const f32x4*)(a.qw + hd * 64 + 16 * ks + 8 * h + 4); u32x4 wv;
;                 wv.x = pk2(bflo(qv[ks].x) * rq * g0.x, bfhi(qv[ks].x) * rq * g0.y); wv.y = pk2(bflo(qv[ks].y) * rq * g0.z, bfhi(qv[ks].y) * rq * g0.w);
;                 wv.z = pk2(bflo(qv[ks].z) * rq * g1.x, bfhi(qv[ks].z) * rq * g1.y); wv.w = pk2(bflo(qv[ks].w) * rq * g1.z, bfhi(qv[ks].w) * rq * g1.w);
;                 qf[ks] = __builtin_bit_cast(bf16x8, wv); }
;         }
;         const float mb = ((const float*)(a.ws + WS_RS))[hd];
;         __syncthreads();
;         const int un = u + gridDim.x;
;         if (un < NU) { const AUnit wn = attn_decode(un, HD0, NH); attn_issue(wn, Qb, Kb, Vb, tid, wave, lane, kv, vv); }
	v_and_b32_e32 v41, 0xffff0000, v109
	v_lshlrev_b32_e32 v130, 16, v89
	v_and_b32_e32 v131, 0xffff0000, v89
	v_lshlrev_b32_e32 v132, 16, v88
	v_and_b32_e32 v133, 0xffff0000, v88
	v_lshlrev_b32_e32 v36, 16, v111
	v_mov_b32_e32 v37, v28
	v_pk_mul_f32 v[30:31], v[38:39], v[38:39]
	v_and_b32_e32 v43, 0xffff0000, v108
	v_mov_b32_e32 v42, v41
	v_lshlrev_b32_e32 v128, 16, v90
	v_and_b32_e32 v129, 0xffff0000, v90
	v_pk_mul_f32 v[234:235], v[130:131], v[130:131]
	v_pk_mul_f32 v[236:237], v[132:133], v[132:133]
	v_pk_fma_f32 v[134:135], v[36:37], v[36:37], v[30:31]
	v_lshlrev_b32_e32 v38, 16, v108
	v_pk_mul_f32 v[44:45], v[42:43], v[42:43]
	v_lshlrev_b32_e32 v62, 16, v91
	v_and_b32_e32 v63, 0xffff0000, v91
	v_pk_mul_f32 v[232:233], v[128:129], v[128:129]
	v_add_f32_e32 v37, v234, v235
	v_add_f32_e32 v42, v236, v237
	v_lshlrev_b32_e32 v30, 16, v109
	v_mov_b32_e32 v31, v38
	v_lshlrev_b32_e32 v56, 16, v92
	v_and_b32_e32 v57, 0xffff0000, v92
	v_pk_mul_f32 v[230:231], v[62:63], v[62:63]
	v_add_f32_e32 v37, v42, v37
	v_add_f32_e32 v42, v232, v233
	v_pk_fma_f32 v[136:137], v[30:31], v[30:31], v[44:45]
	v_lshlrev_b32_e32 v54, 16, v93
	v_and_b32_e32 v55, 0xffff0000, v93
	v_pk_mul_f32 v[228:229], v[56:57], v[56:57]
	v_add_f32_e32 v31, v230, v231
	v_add_f32_e32 v37, v42, v37
	v_and_b32_e32 v59, 0xffff0000, v103
	v_lshlrev_b32_e32 v52, 16, v94
	v_and_b32_e32 v53, 0xffff0000, v94
	v_pk_mul_f32 v[226:227], v[54:55], v[54:55]
	v_add_f32_e32 v31, v31, v37
	v_add_f32_e32 v37, v228, v229
	v_lshlrev_b32_e32 v40, 16, v102
	v_and_b32_e32 v61, 0xffff0000, v102
	v_mov_b32_e32 v60, v59
	v_lshlrev_b32_e32 v50, 16, v95
	v_and_b32_e32 v51, 0xffff0000, v95
	v_pk_mul_f32 v[224:225], v[52:53], v[52:53]
	v_add_f32_e32 v31, v37, v31
	v_add_f32_e32 v37, v226, v227
	v_lshlrev_b32_e32 v44, 16, v103
	v_mov_b32_e32 v45, v40
	v_pk_mul_f32 v[46:47], v[60:61], v[60:61]
	v_lshlrev_b32_e32 v48, 16, v100
	v_and_b32_e32 v49, 0xffff0000, v100
	v_pk_mul_f32 v[168:169], v[50:51], v[50:51]
	v_add_f32_e32 v31, v37, v31
	v_add_f32_e32 v37, v224, v225
	v_pk_fma_f32 v[138:139], v[44:45], v[44:45], v[46:47]
	v_lshlrev_b32_e32 v46, 16, v101
	v_and_b32_e32 v47, 0xffff0000, v101
	v_pk_mul_f32 v[142:143], v[48:49], v[48:49]
	v_add_f32_e32 v31, v37, v31
	v_add_f32_e32 v37, v168, v169
	v_pk_mul_f32 v[140:141], v[46:47], v[46:47]
	v_add_f32_e32 v31, v37, v31
	v_add_f32_e32 v37, v142, v143
	v_add_f32_e32 v31, v37, v31
	v_add_f32_e32 v37, v140, v141
	v_add_f32_e32 v31, v37, v31
	v_add_f32_e32 v31, v139, v31
	v_add_f32_e32 v31, v138, v31
	v_add_f32_e32 v31, v137, v31
	v_add_f32_e32 v31, v136, v31
	v_add_f32_e32 v31, v135, v31
	v_add_f32_e32 v31, v134, v31
	ds_bpermute_b32 v37, v153, v31
	s_add_i32 s69, s67, s54
	s_cmpk_lt_i32 s69, 0x1000
	s_cselect_b64 s[72:73], -1, 0
	s_cmpk_gt_i32 s69, 0xfff
	s_cselect_b64 s[70:71], -1, 0
	s_and_b64 vcc, exec, s[70:71]
	s_waitcnt lgkmcnt(0)
	s_barrier
	s_cbranch_vccnz .LBB0_282
; __device__ __forceinline__ unsigned pk2(float lo, float hi) { f32x2_t v = {lo, hi}; bf16x2_t b = __builtin_convertvector(v, bf16x2_t); return __builtin_bit_cast(unsigned, b); }
; template <bool FUSED> __device__ __forceinline__ void attn_phase(const Args& a, LAS unsigned char* lds, int tid, int lane, int wave) {
;     ...
;             for (int ks = 0; ks < 4; ++ks)
; #pragma unroll
;                 for (int e = 0; e < 4; ++e) { const float lo = bflo(qv[ks][e]), hi = bfhi(qv[ks][e]); ss += lo * lo + hi * hi; }
;             ss += __shfl_xor(ss, 32);
;             const float rq = 0.125f * LOG2E * __builtin_amdgcn_rsqf(ss * (1.f / 64.f) + 1e-6f);
; #pragma unroll
;             for (int ks = 0; ks < 4; ++ks) { const f32x4 g0 = *(const f32x4*)(a.qw + hd * 64 + 16 * ks + 8 * h), g1 = *(const f32x4*)(a.qw + hd * 64 + 16 * ks + 8 * h + 4); u32x4 wv;
;                 wv.x = pk2(bflo(qv[ks].x) * rq * g0.x, bfhi(qv[ks].x) * rq * g0.y); wv.y = pk2(bflo(qv[ks].y) * rq * g0.z, bfhi(qv[ks].y) * rq * g0.w);
;                 wv.z = pk2(bflo(qv[ks].z) * rq * g1.x, bfhi(qv[ks].z) * rq * g1.y); wv.w = pk2(bflo(qv[ks].w) * rq * g1.z, bfhi(qv[ks].w) * rq * g1.w);
;                 qf[ks] = __builtin_bit_cast(bf16x8, wv); }
;         }
;         const float mb = ((const float*)(a.ws + WS_RS))[hd];
;         __syncthreads();
;         const int un = u + gridDim.x;
;         if (un < NU) { const AUnit wn = attn_decode(un, HD0, NH); attn_issue(wn, Qb, Kb, Vb, tid, wave, lane, kv, vv); }
;         const float bsl = __builtin_amdgcn_exp2f(-(float)(slot + 1)) * (float)w.dil * LOG2E;
	s_ashr_i32 s7, s69, 5
	s_lshr_b32 s8, s7, 28
	s_add_i32 s8, s7, s8
	s_and_b32 s8, s8, -16
	s_sub_i32 s7, s7, s8
	s_add_i32 s7, s7, 8
	s_ashr_i32 s9, s7, 2
	s_and_b32 s9, s9, -2
	s_lshr_b32 s10, 32, s9
	s_and_b32 s6, s69, 31
	s_lshr_b32 s11, 0x2000, s9
	s_sub_i32 s9, 5, s9
	s_add_i32 s10, s10, -1
	s_lshr_b32 s9, s6, s9
	s_and_b32 s6, s10, s6
	s_lshl_b32 s10, s6, 8
	v_add_u32_e32 v42, s10, v155
	s_add_i32 s12, s11, -1
	v_min_i32_e32 v45, s12, v42
	v_cmp_lt_i32_e32 vcc, -1, v42
	s_mul_i32 s9, s9, s11
	s_ashr_i32 s8, s69, 31
	v_cndmask_b32_e32 v42, 0, v45, vcc
	v_add_u32_e32 v64, s9, v42
	v_add_u32_e32 v42, s10, v170
	v_min_i32_e32 v45, s12, v42
	v_cmp_lt_i32_e32 vcc, -1, v42
	s_lshr_b32 s8, s8, 23
	s_add_i32 s8, s69, s8
	v_cndmask_b32_e32 v42, 0, v45, vcc
	v_add_u32_e32 v72, s9, v42
	v_add_u32_e32 v42, s10, v171
	v_min_i32_e32 v45, s12, v42
	v_cmp_lt_i32_e32 vcc, -1, v42
	s_ashr_i32 s8, s8, 9
	s_mul_i32 s8, s8, 24
	v_cndmask_b32_e32 v42, 0, v45, vcc
	v_add_u32_e32 v80, s9, v42
	v_add_u32_e32 v42, s10, v172
	v_min_i32_e32 v45, s12, v42
	v_cmp_lt_i32_e32 vcc, -1, v42
	s_add_i32 s6, s7, s8
	s_ashr_i32 s7, s6, 31
	v_cndmask_b32_e32 v42, 0, v45, vcc
	v_add_u32_e32 v96, s9, v42
	v_add_u32_e32 v42, s10, v173
	v_min_i32_e32 v45, s12, v42
	v_cmp_lt_i32_e32 vcc, -1, v42
	v_ashrrev_i32_e32 v65, 31, v64
	v_ashrrev_i32_e32 v73, 31, v72
	v_cndmask_b32_e32 v42, 0, v45, vcc
	v_add_u32_e32 v112, s9, v42
	v_add_u32_e32 v42, s10, v174
	v_min_i32_e32 v45, s12, v42
	v_cmp_lt_i32_e32 vcc, -1, v42
	v_ashrrev_i32_e32 v81, 31, v80
	v_ashrrev_i32_e32 v97, 31, v96
	v_cndmask_b32_e32 v42, 0, v45, vcc
	v_add_u32_e32 v120, s9, v42
	v_ashrrev_i32_e32 v113, 31, v112
	v_ashrrev_i32_e32 v121, 31, v120
	s_lshl_b64 s[6:7], s[6:7], 19
	v_lshlrev_b64 v[64:65], 6, v[64:65]
	v_lshlrev_b64 v[72:73], 6, v[72:73]
	v_lshlrev_b64 v[80:81], 6, v[80:81]
	v_lshlrev_b64 v[96:97], 6, v[96:97]
	v_lshlrev_b64 v[112:113], 6, v[112:113]
	v_lshlrev_b64 v[120:121], 6, v[120:121]
	v_lshl_add_u64 v[64:65], v[64:65], 0, s[6:7]
	v_lshl_add_u64 v[72:73], v[72:73], 0, s[6:7]
	v_lshl_add_u64 v[80:81], v[80:81], 0, s[6:7]
	v_lshl_add_u64 v[96:97], v[96:97], 0, s[6:7]
	v_lshl_add_u64 v[112:113], v[112:113], 0, s[6:7]
	v_lshl_add_u64 v[120:121], v[120:121], 0, s[6:7]
	v_or_b32_e32 v64, v64, v144
	v_or_b32_e32 v72, v72, v144
	v_or_b32_e32 v80, v80, v144
	v_or_b32_e32 v96, v96, v144
	v_or_b32_e32 v112, v112, v144
	v_or_b32_e32 v120, v120, v144
	v_lshlrev_b64 v[64:65], 1, v[64:65]
	v_lshlrev_b64 v[72:73], 1, v[72:73]
	v_lshlrev_b64 v[80:81], 1, v[80:81]
	v_lshlrev_b64 v[96:97], 1, v[96:97]
	v_lshlrev_b64 v[112:113], 1, v[112:113]
	v_lshlrev_b64 v[120:121], 1, v[120:121]
	v_lshl_add_u64 v[66:67], s[58:59], 0, v[64:65]
	v_lshl_add_u64 v[68:69], s[60:61], 0, v[64:65]
	v_lshl_add_u64 v[74:75], s[58:59], 0, v[72:73]
	v_lshl_add_u64 v[76:77], s[60:61], 0, v[72:73]
	v_lshl_add_u64 v[82:83], s[58:59], 0, v[80:81]
	v_lshl_add_u64 v[84:85], s[60:61], 0, v[80:81]
	v_lshl_add_u64 v[98:99], s[58:59], 0, v[96:97]
	v_lshl_add_u64 v[104:105], s[60:61], 0, v[96:97]
	v_lshl_add_u64 v[114:115], s[58:59], 0, v[112:113]
	v_lshl_add_u64 v[116:117], s[60:61], 0, v[112:113]
	v_lshl_add_u64 v[122:123], s[58:59], 0, v[120:121]
	v_lshl_add_u64 v[124:125], s[60:61], 0, v[120:121]
	global_load_dwordx4 v[64:67], v[66:67], off
	s_nop 0
	global_load_dwordx4 v[68:71], v[68:69], off
	s_nop 0
	global_load_dwordx4 v[72:75], v[74:75], off
	s_nop 0
	global_load_dwordx4 v[76:79], v[76:77], off
	s_nop 0
	global_load_dwordx4 v[80:83], v[82:83], off
	s_nop 0
	global_load_dwordx4 v[84:87], v[84:85], off
	s_nop 0
	global_load_dwordx4 v[96:99], v[98:99], off
	s_nop 0
	global_load_dwordx4 v[104:107], v[104:105], off
	s_nop 0
	global_load_dwordx4 v[112:115], v[114:115], off
	s_nop 0
	global_load_dwordx4 v[116:119], v[116:117], off
	s_nop 0
	global_load_dwordx4 v[120:123], v[122:123], off
	s_nop 0
	global_load_dwordx4 v[124:127], v[124:125], off
	v_add_f32_e32 v31, v31, v37
	v_fmamk_f32 v31, v31, 0x3c800000, v176
	v_rsq_f32_e32 v42, v31
	v_mov_b32_e32 v37, v29
	v_mov_b32_e32 v29, v39
	v_mov_b32_e32 v39, v43
	v_mul_f32_e32 v58, 0x3e38aa3b, v42
	v_pk_mul_f32 v[42:43], v[58:59], v[132:133] op_sel_hi:[0,1]
	s_waitcnt vmcnt(19)
	v_pk_mul_f32 v[24:25], v[24:25], v[42:43]
	v_mov_b32_e32 v31, v41
	v_cvt_pk_bf16_f32 v136, v24, v25
	v_pk_mul_f32 v[24:25], v[58:59], v[130:131] op_sel_hi:[0,1]
	v_pk_mul_f32 v[24:25], v[26:27], v[24:25]
	v_mov_b32_e32 v41, v61
	v_cvt_pk_bf16_f32 v137, v24, v25
	v_pk_mul_f32 v[24:25], v[58:59], v[128:129] op_sel_hi:[0,1]
	v_pk_mul_f32 v[20:21], v[20:21], v[24:25]
	v_mov_b32_e32 v45, v59
	v_cvt_pk_bf16_f32 v138, v20, v21
	v_pk_mul_f32 v[20:21], v[58:59], v[62:63] op_sel_hi:[0,1]
	v_pk_mul_f32 v[20:21], v[22:23], v[20:21]
	s_and_b32 s7, s66, 7
	v_cvt_pk_bf16_f32 v139, v20, v21
	v_pk_mul_f32 v[20:21], v[58:59], v[56:57] op_sel_hi:[0,1]
	s_waitcnt vmcnt(17)
	v_pk_mul_f32 v[16:17], v[16:17], v[20:21]
	s_add_i32 s7, s7, 1
	v_cvt_pk_bf16_f32 v132, v16, v17
	v_pk_mul_f32 v[16:17], v[58:59], v[54:55] op_sel_hi:[0,1]
	v_pk_mul_f32 v[16:17], v[18:19], v[16:17]
	s_ashr_i32 s6, s68, 2
	v_cvt_pk_bf16_f32 v133, v16, v17
	v_pk_mul_f32 v[16:17], v[58:59], v[52:53] op_sel_hi:[0,1]
	v_pk_mul_f32 v[12:13], v[12:13], v[16:17]
	s_and_b32 s75, s6, -2
	v_cvt_pk_bf16_f32 v134, v12, v13
	v_pk_mul_f32 v[12:13], v[58:59], v[50:51] op_sel_hi:[0,1]
	v_pk_mul_f32 v[12:13], v[14:15], v[12:13]
	s_lshr_b32 s6, 32, s75
	v_cvt_pk_bf16_f32 v135, v12, v13
	v_pk_mul_f32 v[12:13], v[58:59], v[48:49] op_sel_hi:[0,1]
	s_waitcnt vmcnt(15)
	v_pk_mul_f32 v[8:9], v[8:9], v[12:13]
	v_mov_b32_e32 v48, v175
	v_cvt_pk_bf16_f32 v128, v8, v9
	v_pk_mul_f32 v[8:9], v[58:59], v[46:47] op_sel_hi:[0,1]
	v_pk_mul_f32 v[8:9], v[10:11], v[8:9]
	v_pk_mul_f32 v[46:47], v[58:59], v[28:29] op_sel_hi:[0,1]
	v_cvt_pk_bf16_f32 v129, v8, v9
	v_pk_mul_f32 v[8:9], v[58:59], v[40:41] op_sel_hi:[0,1]
	v_pk_mul_f32 v[4:5], v[4:5], v[8:9]
	s_waitcnt vmcnt(14)
	v_pk_mul_f32 v[32:33], v[46:47], v[32:33]
	v_cvt_pk_bf16_f32 v130, v4, v5
	v_pk_mul_f32 v[4:5], v[58:59], v[44:45] op_sel_hi:[0,1]
	v_pk_mul_f32 v[4:5], v[6:7], v[4:5]
	ds_read_b128 v[42:45], v199 offset:32
	v_cvt_pk_bf16_f32 v131, v4, v5
	v_pk_mul_f32 v[4:5], v[58:59], v[38:39] op_sel_hi:[0,1]
	ds_read_b128 v[38:41], v199
	s_waitcnt vmcnt(13)
	v_pk_mul_f32 v[0:1], v[4:5], v[0:1]
	v_cvt_pk_bf16_f32 v142, v32, v33
	v_cvt_pk_bf16_f32 v140, v0, v1
	v_pk_mul_f32 v[0:1], v[58:59], v[30:31] op_sel_hi:[0,1]
	v_pk_mul_f32 v[0:1], v[0:1], v[2:3]
	v_cvt_f32_ubyte0_e32 v32, s7
	v_cvt_pk_bf16_f32 v141, v0, v1
	s_waitcnt vmcnt(12)
	s_branch .Lattn1_join

; #define LAS __attribute__((address_space(3)))
; __device__ __forceinline__ float attn_tile_exp(f32x16& st, int j, float tlf, float bsl, float rlo, float rhi) {
;     float sum = 0.f;
; #pragma unroll
;     for (int i = 0; i < 16; ++i) { const float tmp = (float)(32 * j - 64 + (i & 3) + 8 * (i >> 2)) + tlf;
;         float arg = __builtin_fmaf(-bsl, __builtin_fabsf(tmp), st[i]);
;         arg = (tmp >= rlo && tmp <= rhi) ? arg : -1.0e30f;
;         const float pe = __builtin_amdgcn_exp2f(arg); st[i] = pe; sum += pe; }
;     return sum;
; template <bool FUSED> __device__ __forceinline__ void attn_phase(const Args& a, LAS unsigned char* lds, int tid, int lane, int wave) {
;     ...
;         const float bsl = __builtin_amdgcn_exp2f(-(float)(slot + 1)) * (float)w.dil * LOG2E;
;         int tl = 4 * h - l31; asm volatile("" : "+v"(tl));
;         const float tlf = (float)tl;
;         const int lo_i = -iq > -64 ? -iq : -64, hi_i = (L - 1 - iq) < 64 ? (L - 1 - iq) : 64;
;         const float rlo = (float)lo_i, rhi = (float)hi_i;
;         const int wq0 = i0 + 32 * wave;
;         const bool edge = (wq0 < 64) || (wq0 + 32 > L - 64);
;         float sum = 0.f;
;         f32x16 o[2]; o[0] = f32x16{}; o[1] = f32x16{};
; #pragma unroll
;         for (int j = 0; j < 5; ++j) {
;             f32x16 st;
; #pragma unroll
;             for (int i = 0; i < 16; ++i) st[i] = -mb;
;             LAS const unsigned char* kp = lds + (32 * wave + 32 * j + l31) * KP + 16 * h;
; #pragma unroll
;             for (int ks = 0; ks < 4; ++ks) { const bf16x8 kf = *(LAS const bf16x8*)(kp + 32 * ks); st = __builtin_amdgcn_mfma_f32_32x32x16_bf16(kf, qf[ks], st, 0, 0, 0); }
;             sum += attn_tile_exp(st, j, tlf, bsl, rlo, rhi);
.Lattn1_join:
	v_xor_b32_e32 v0, 0x80000000, v222
	v_mov_b32_e32 v1, v0
	v_mov_b32_e32 v2, v0
	v_mov_b32_e32 v3, v0
	v_mov_b32_e32 v4, v0
	v_mov_b32_e32 v5, v0
	v_mov_b32_e32 v6, v0
	v_mov_b32_e32 v7, v0
	v_mov_b32_e32 v8, v0
	v_mov_b32_e32 v9, v0
	v_mov_b32_e32 v10, v0
	v_mov_b32_e32 v11, v0
	v_mov_b32_e32 v12, v0
	v_mov_b32_e32 v13, v0
	v_mov_b32_e32 v14, v0
	v_mov_b32_e32 v15, v0
	v_exp_f32_e64 v46, -v32
	v_pk_mul_f32 v[32:33], v[58:59], v[36:37] op_sel_hi:[0,1]
	s_waitcnt lgkmcnt(0)
	v_mfma_f32_32x32x16_bf16 v[16:31], v[38:41], v[136:139], v[0:15]
	ds_read_b128 v[38:41], v199 offset:64
	v_mul_f32_e64 v32, v32, v34
	v_mul_f32_e64 v33, v33, v35
	s_and_b32 s77, s67, 31
	v_cvt_pk_bf16_f32 v143, v32, v33
	ds_read_b128 v[32:35], v199 offset:96
	s_add_i32 s6, s6, -1
	s_and_b32 s6, s6, s77
	v_mfma_f32_32x32x16_bf16 v[16:31], v[42:45], v[132:135], v[16:31]
	s_lshr_b32 s76, 0x2000, s75
	v_lshl_add_u32 v168, s6, 8, v145
	s_lshl_b32 s6, 1, s75
	v_sub_u32_e32 v37, 0, v168
	v_cvt_f32_u32_e32 v42, s6
	v_cvt_f32_i32_e32 v225, v48
	v_max_i32_e32 v37, 0xffffffc0, v37
	s_waitcnt lgkmcnt(1)
	v_mfma_f32_32x32x16_bf16 v[16:31], v[38:41], v[128:131], v[16:31]
	v_xad_u32 v38, v168, -1, s76
	v_min_i32_e32 v38, 64, v38
	v_cvt_f32_i32_e32 v169, v37
	v_cvt_f32_i32_e32 v223, v38
	v_mul_f32_e32 v36, v46, v42
	v_mul_f32_e32 v224, 0xbfb8aa3b, v36
	s_waitcnt lgkmcnt(0)
	v_mfma_f32_32x32x16_bf16 v[16:31], v[32:35], v[140:143], v[16:31]
	v_add_f32_e32 v32, 0xc2800000, v225
	v_cmp_nge_f32_e32 vcc, v32, v169
	v_cmp_nle_f32_e64 s[6:7], v32, v223
	s_or_b64 vcc, vcc, s[6:7]
	v_add_f32_e32 v33, 0xc27c0000, v225
	v_cmp_nle_f32_e64 s[6:7], v33, v223
	s_nop 5
	v_fma_f32 v16, v224, |v32|, v16
	v_cndmask_b32_e32 v16, v16, v221, vcc
	v_cmp_nge_f32_e32 vcc, v33, v169
	v_fma_f32 v17, v224, |v33|, v17
	s_or_b64 vcc, vcc, s[6:7]
	v_cndmask_b32_e32 v17, v17, v221, vcc
	v_exp_f32_e32 v33, v17
	v_add_f32_e32 v17, 0xc2780000, v225
	v_cmp_nge_f32_e32 vcc, v17, v169
	v_cmp_nle_f32_e64 s[6:7], v17, v223
	v_fma_f32 v18, v224, |v17|, v18
	s_or_b64 vcc, vcc, s[6:7]
	v_cndmask_b32_e32 v17, v18, v221, vcc
	v_exp_f32_e32 v34, v17
	v_add_f32_e32 v17, 0xc2740000, v225
	v_cmp_nge_f32_e32 vcc, v17, v169
	v_cmp_nle_f32_e64 s[6:7], v17, v223
	v_fma_f32 v18, v224, |v17|, v19
	s_or_b64 vcc, vcc, s[6:7]
	v_cndmask_b32_e32 v17, v18, v221, vcc
	v_exp_f32_e32 v35, v17
	v_add_f32_e32 v17, 0xc2600000, v225
	v_cmp_nge_f32_e32 vcc, v17, v169
	v_cmp_nle_f32_e64 s[6:7], v17, v223
	v_fma_f32 v18, v224, |v17|, v20
	s_or_b64 vcc, vcc, s[6:7]
	v_cndmask_b32_e32 v17, v18, v221, vcc
	v_exp_f32_e32 v36, v17
	v_add_f32_e32 v17, 0xc25c0000, v225
	v_cmp_nge_f32_e32 vcc, v17, v169
	v_cmp_nle_f32_e64 s[6:7], v17, v223
	v_fma_f32 v18, v224, |v17|, v21
	s_or_b64 vcc, vcc, s[6:7]
	v_cndmask_b32_e32 v17, v18, v221, vcc
	v_exp_f32_e32 v37, v17
	v_add_f32_e32 v17, 0xc2580000, v225
	v_cmp_nge_f32_e32 vcc, v17, v169
	v_cmp_nle_f32_e64 s[6:7], v17, v223
	v_fma_f32 v18, v224, |v17|, v22
	s_or_b64 vcc, vcc, s[6:7]
	v_cndmask_b32_e32 v17, v18, v221, vcc
	v_exp_f32_e32 v32, v16
	v_exp_f32_e32 v38, v17
	v_add_f32_e32 v17, 0xc2540000, v225
	v_cmp_nge_f32_e32 vcc, v17, v169
	v_cmp_nle_f32_e64 s[6:7], v17, v223
	v_fma_f32 v18, v224, |v17|, v23
	s_or_b64 vcc, vcc, s[6:7]
	v_cndmask_b32_e32 v17, v18, v221, vcc
	v_add_f32_e32 v16, 0, v32
	v_exp_f32_e32 v23, v17
	v_add_f32_e32 v17, 0xc2400000, v225
	v_add_f32_e32 v16, v33, v16
	v_cmp_nge_f32_e32 vcc, v17, v169
	v_cmp_nle_f32_e64 s[6:7], v17, v223
	v_add_f32_e32 v16, v34, v16
	v_fma_f32 v18, v224, |v17|, v24
	s_or_b64 vcc, vcc, s[6:7]
	v_add_f32_e32 v16, v35, v16
	v_cndmask_b32_e32 v17, v18, v221, vcc
	v_add_f32_e32 v16, v36, v16
	v_exp_f32_e32 v52, v17
	v_add_f32_e32 v16, v37, v16
	v_add_f32_e32 v16, v38, v16
	v_add_f32_e32 v16, v23, v16
	v_add_f32_e32 v60, v52, v16
	v_add_f32_e32 v16, 0xc23c0000, v225
	v_cmp_nge_f32_e32 vcc, v16, v169
	v_cmp_nle_f32_e64 s[6:7], v16, v223
	v_fma_f32 v17, v224, |v16|, v25
	s_or_b64 vcc, vcc, s[6:7]
	v_cndmask_b32_e32 v16, v17, v221, vcc
	v_exp_f32_e32 v61, v16
	v_add_f32_e32 v16, 0xc2380000, v225
	v_cmp_nge_f32_e32 vcc, v16, v169
	v_cmp_nle_f32_e64 s[6:7], v16, v223
	v_fma_f32 v17, v224, |v16|, v26
	s_or_b64 vcc, vcc, s[6:7]
	v_cndmask_b32_e32 v16, v17, v221, vcc
	v_exp_f32_e32 v62, v16
	v_add_f32_e32 v16, 0xc2340000, v225
	v_cmp_nge_f32_e32 vcc, v16, v169
	v_cmp_nle_f32_e64 s[6:7], v16, v223
	v_fma_f32 v17, v224, |v16|, v27
	s_or_b64 vcc, vcc, s[6:7]
	v_cndmask_b32_e32 v16, v17, v221, vcc
	v_exp_f32_e32 v63, v16
	v_add_f32_e32 v16, 0xc2200000, v225
	v_cmp_nge_f32_e32 vcc, v16, v169
	v_cmp_nle_f32_e64 s[6:7], v16, v223
	v_fma_f32 v17, v224, |v16|, v28
	s_or_b64 vcc, vcc, s[6:7]
	v_cndmask_b32_e32 v16, v17, v221, vcc
	v_exp_f32_e32 v226, v16
	v_add_f32_e32 v16, 0xc21c0000, v225
	v_cmp_nge_f32_e32 vcc, v16, v169
	v_cmp_nle_f32_e64 s[6:7], v16, v223
	v_fma_f32 v17, v224, |v16|, v29
	s_or_b64 vcc, vcc, s[6:7]
	v_cndmask_b32_e32 v16, v17, v221, vcc
	v_exp_f32_e32 v227, v16
	v_add_f32_e32 v16, 0xc2180000, v225
	v_cmp_nge_f32_e32 vcc, v16, v169
	v_cmp_nle_f32_e64 s[6:7], v16, v223
	v_fma_f32 v17, v224, |v16|, v30
	s_or_b64 vcc, vcc, s[6:7]
	v_cndmask_b32_e32 v20, v17, v221, vcc
	ds_read_b64_tr_b16 v[16:17], v200 offset:55296
	ds_read_b64_tr_b16 v[18:19], v200 offset:56832
	ds_read_b64_tr_b16 v[26:27], v200 offset:56896
	ds_read_b64_tr_b16 v[24:25], v200 offset:55360
	v_add_f32_e32 v28, 0xc2140000, v225
	v_exp_f32_e32 v228, v20
	v_cvt_pk_bf16_f32 v20, v32, v33
	v_cvt_pk_bf16_f32 v21, v34, v35
	v_cvt_pk_bf16_f32 v22, v36, v37
	v_cvt_pk_bf16_f32 v23, v38, v23
	v_cmp_nge_f32_e32 vcc, v28, v169
	v_cmp_nle_f32_e64 s[6:7], v28, v223
	s_waitcnt lgkmcnt(2)
; #define LAS __attribute__((address_space(3)))
; __device__ __forceinline__ unsigned pk2(float lo, float hi) { f32x2_t v = {lo, hi}; bf16x2_t b = __builtin_convertvector(v, bf16x2_t); return __builtin_bit_cast(unsigned, b); }
; __device__ __forceinline__ s16x4 trrd(LAS const unsigned char* p) { return __builtin_bit_cast(s16x4, __builtin_amdgcn_ds_read_tr16_b64_v4i16((LAS v4i16_t*)p)); }
; __device__ __forceinline__ float attn_tile_exp(f32x16& st, int j, float tlf, float bsl, float rlo, float rhi) {
;     float sum = 0.f;
; #pragma unroll
;     for (int i = 0; i < 16; ++i) { const float tmp = (float)(32 * j - 64 + (i & 3) + 8 * (i >> 2)) + tlf;
;         float arg = __builtin_fmaf(-bsl, __builtin_fabsf(tmp), st[i]);
;         arg = (tmp >= rlo && tmp <= rhi) ? arg : -1.0e30f;
;         const float pe = __builtin_amdgcn_exp2f(arg); st[i] = pe; sum += pe; }
;     return sum;
; template <bool FUSED> __device__ __forceinline__ void attn_phase(const Args& a, LAS unsigned char* lds, int tid, int lane, int wave) {
;     ...
;         for (int j = 0; j < 5; ++j) {
;             f32x16 st;
; #pragma unroll
;             for (int i = 0; i < 16; ++i) st[i] = -mb;
;             LAS const unsigned char* kp = lds + (32 * wave + 32 * j + l31) * KP + 16 * h;
; #pragma unroll
;             for (int ks = 0; ks < 4; ++ks) { const bf16x8 kf = *(LAS const bf16x8*)(kp + 32 * ks); st = __builtin_amdgcn_mfma_f32_32x32x16_bf16(kf, qf[ks], st, 0, 0, 0); }
;             sum += attn_tile_exp(st, j, tlf, bsl, rlo, rhi);
; #pragma unroll
;             for (int s2 = 0; s2 < 2; ++s2) { u32x4 pw; pw.x = pk2(st[8 * s2 + 0], st[8 * s2 + 1]); pw.y = pk2(st[8 * s2 + 2], st[8 * s2 + 3]); pw.z = pk2(st[8 * s2 + 4], st[8 * s2 + 5]); pw.w = pk2(st[8 * s2 + 6], st[8 * s2 + 7]);
;                 const bf16x8 pf = __builtin_bit_cast(bf16x8, pw);
;                 LAS const unsigned char* vp = lds + LDS_VOFF + (32 * wave + 32 * j + 16 * s2 + 4 * h + q) * VP + 32 * blk + 8 * p;
; #pragma unroll
;                 for (int dt = 0; dt < 2; ++dt) { const s16x4 lo = trrd(vp + dt * 64), hi = trrd(vp + 8 * VP + dt * 64);
;                     const bf16x8 vf = __builtin_shufflevector(lo, hi, 0, 1, 2, 3, 4, 5, 6, 7);
;                     o[dt] = __builtin_amdgcn_mfma_f32_32x32x16_bf16(vf, pf, o[dt], 0, 0, 0); } }
;             __builtin_amdgcn_sched_barrier(0);
;         }
	v_mfma_f32_32x32x16_bf16 v[32:47], v[16:19], v[20:23], 0
	v_fma_f32 v16, v224, |v28|, v31
	s_or_b64 vcc, vcc, s[6:7]
	v_cndmask_b32_e32 v53, v16, v221, vcc
	ds_read_b64_tr_b16 v[48:49], v200 offset:58368
	ds_read_b64_tr_b16 v[50:51], v200 offset:59904
	v_exp_f32_e32 v229, v53
	ds_read_b64_tr_b16 v[58:59], v200 offset:59968
	ds_read_b64_tr_b16 v[56:57], v200 offset:58432
	v_cvt_pk_bf16_f32 v52, v52, v61
	s_waitcnt lgkmcnt(4)
	v_mfma_f32_32x32x16_bf16 v[16:31], v[24:27], v[20:23], 0
	v_cvt_pk_bf16_f32 v53, v62, v63
	v_cvt_pk_bf16_f32 v54, v226, v227
	v_cvt_pk_bf16_f32 v55, v228, v229
	s_waitcnt lgkmcnt(2)
	s_nop 0
	v_mfma_f32_32x32x16_bf16 v[32:47], v[48:51], v[52:55], v[32:47]
	v_add_f32_e32 v48, v61, v60
	v_add_f32_e32 v48, v62, v48
	v_add_f32_e32 v48, v63, v48
	v_add_f32_e32 v48, v226, v48
	v_add_f32_e32 v48, v227, v48
	v_add_f32_e32 v48, v228, v48
	v_add_f32_e32 v48, v229, v48
	s_waitcnt lgkmcnt(0)
	v_mfma_f32_32x32x16_bf16 v[16:31], v[56:59], v[52:55], v[16:31]
	v_add_f32_e32 v238, 0, v48
	ds_read_b128 v[226:229], v201
	ds_read_b128 v[230:233], v201 offset:32
	v_add_f32_e32 v239, 0xc2000000, v225
	v_add_f32_e32 v240, 0xc1f80000, v225
	v_cmp_nge_f32_e32 vcc, v239, v169
	s_waitcnt lgkmcnt(1)
	v_mfma_f32_32x32x16_bf16 v[48:63], v[226:229], v[136:139], v[0:15]
	ds_read_b128 v[226:229], v201 offset:64
	ds_read_b128 v[234:237], v201 offset:96
	v_cmp_nle_f32_e64 s[6:7], v239, v223
	v_add_f32_e32 v241, 0xc1f00000, v225
	v_cmp_nge_f32_e64 s[8:9], v240, v169
	v_cmp_nle_f32_e64 s[10:11], v240, v223
	s_or_b64 vcc, vcc, s[6:7]
	v_add_f32_e32 v242, 0xc1e80000, v225
	s_waitcnt lgkmcnt(2)
	v_mfma_f32_32x32x16_bf16 v[48:63], v[230:233], v[132:135], v[48:63]
	v_cmp_nge_f32_e64 s[12:13], v241, v169
	v_cmp_nle_f32_e64 s[14:15], v241, v223
	v_add_f32_e32 v230, 0xc1c00000, v225
	v_cmp_nge_f32_e64 s[16:17], v242, v169
	v_cmp_nle_f32_e64 s[20:21], v242, v223
	v_add_f32_e32 v231, 0xc1b80000, v225
	v_cmp_nge_f32_e64 s[22:23], v230, v169
	s_waitcnt lgkmcnt(1)
	v_mfma_f32_32x32x16_bf16 v[48:63], v[226:229], v[128:131], v[48:63]
	v_cmp_nle_f32_e64 s[24:25], v230, v223
	v_cmp_nge_f32_e64 s[26:27], v231, v169
	v_cmp_nle_f32_e64 s[28:29], v231, v223
	s_waitcnt lgkmcnt(0)
	v_mfma_f32_32x32x16_bf16 v[48:63], v[234:237], v[140:143], v[48:63]
	s_nop 11
	v_fma_f32 v48, v224, |v239|, v48
	v_fma_f32 v49, v224, |v240|, v49
	v_cndmask_b32_e32 v48, v48, v221, vcc
	s_or_b64 vcc, s[8:9], s[10:11]
	v_fma_f32 v50, v224, |v241|, v50
	v_cndmask_b32_e32 v49, v49, v221, vcc
	s_or_b64 vcc, s[12:13], s[14:15]
	v_fma_f32 v51, v224, |v242|, v51
	v_cndmask_b32_e32 v50, v50, v221, vcc
	s_or_b64 vcc, s[16:17], s[20:21]
	v_fma_f32 v52, v224, |v230|, v52
	v_cndmask_b32_e32 v51, v51, v221, vcc
	s_or_b64 vcc, s[22:23], s[24:25]
	v_fma_f32 v53, v224, |v231|, v53
	v_cndmask_b32_e32 v52, v52, v221, vcc
	s_or_b64 vcc, s[26:27], s[28:29]
	v_exp_f32_e32 v227, v49
	v_cndmask_b32_e32 v49, v53, v221, vcc
	v_exp_f32_e32 v231, v49
	v_add_f32_e32 v49, 0xc1b00000, v225
	v_cmp_nge_f32_e32 vcc, v49, v169
	v_cmp_nle_f32_e64 s[6:7], v49, v223
	v_exp_f32_e32 v228, v50
	v_fma_f32 v50, v224, |v49|, v54
	s_or_b64 vcc, vcc, s[6:7]
	v_cndmask_b32_e32 v49, v50, v221, vcc
	v_exp_f32_e32 v226, v48
	v_exp_f32_e32 v232, v49
	v_add_f32_e32 v49, 0xc1a80000, v225
	v_cmp_nge_f32_e32 vcc, v49, v169
	v_cmp_nle_f32_e64 s[6:7], v49, v223
	v_fma_f32 v50, v224, |v49|, v55
	s_or_b64 vcc, vcc, s[6:7]
	v_exp_f32_e32 v229, v51
	v_cndmask_b32_e32 v49, v50, v221, vcc
	v_exp_f32_e32 v230, v52
	v_add_f32_e32 v48, 0, v226
	v_exp_f32_e32 v55, v49
	v_add_f32_e32 v49, 0xc1800000, v225
	v_add_f32_e32 v48, v227, v48
	v_cmp_nge_f32_e32 vcc, v49, v169
	v_cmp_nle_f32_e64 s[6:7], v49, v223
	v_add_f32_e32 v48, v228, v48
	v_fma_f32 v50, v224, |v49|, v56
	s_or_b64 vcc, vcc, s[6:7]
	v_add_f32_e32 v48, v229, v48
	v_cndmask_b32_e32 v49, v50, v221, vcc
	v_add_f32_e32 v48, v230, v48
	v_exp_f32_e32 v233, v49
	v_add_f32_e32 v48, v231, v48
	v_add_f32_e32 v48, v232, v48
	v_add_f32_e32 v48, v55, v48
	v_add_f32_e32 v234, v233, v48
	v_add_f32_e32 v48, 0xc1700000, v225
	v_cmp_nge_f32_e32 vcc, v48, v169
	v_cmp_nle_f32_e64 s[6:7], v48, v223
	v_fma_f32 v49, v224, |v48|, v57
	s_or_b64 vcc, vcc, s[6:7]
	v_cndmask_b32_e32 v48, v49, v221, vcc
	v_exp_f32_e32 v235, v48
	v_add_f32_e32 v48, 0xc1600000, v225
	v_cmp_nge_f32_e32 vcc, v48, v169
	v_cmp_nle_f32_e64 s[6:7], v48, v223
	v_fma_f32 v49, v224, |v48|, v58
	s_or_b64 vcc, vcc, s[6:7]
	v_cndmask_b32_e32 v48, v49, v221, vcc
	v_exp_f32_e32 v236, v48
	v_add_f32_e32 v48, 0xc1500000, v225
	v_cmp_nge_f32_e32 vcc, v48, v169
	v_cmp_nle_f32_e64 s[6:7], v48, v223
	v_fma_f32 v49, v224, |v48|, v59
	s_or_b64 vcc, vcc, s[6:7]
	v_cndmask_b32_e32 v48, v49, v221, vcc
	v_exp_f32_e32 v237, v48
	v_add_f32_e32 v48, 0xc1000000, v225
	v_cmp_nge_f32_e32 vcc, v48, v169
	v_cmp_nle_f32_e64 s[6:7], v48, v223
	v_fma_f32 v49, v224, |v48|, v60
	s_or_b64 vcc, vcc, s[6:7]
	v_cndmask_b32_e32 v48, v49, v221, vcc
	v_exp_f32_e32 v60, v48
	v_add_f32_e32 v48, 0xc0e00000, v225
	v_cmp_nge_f32_e32 vcc, v48, v169
	v_cmp_nle_f32_e64 s[6:7], v48, v223
	v_fma_f32 v49, v224, |v48|, v61
	s_or_b64 vcc, vcc, s[6:7]
	v_cndmask_b32_e32 v48, v49, v221, vcc
	v_exp_f32_e32 v61, v48
	v_add_f32_e32 v48, 0xc0c00000, v225
	v_cmp_nge_f32_e32 vcc, v48, v169
	v_cmp_nle_f32_e64 s[6:7], v48, v223
	v_fma_f32 v49, v224, |v48|, v62
	s_or_b64 vcc, vcc, s[6:7]
	v_cndmask_b32_e32 v52, v49, v221, vcc
	ds_read_b64_tr_b16 v[48:49], v202 offset:55296
	ds_read_b64_tr_b16 v[50:51], v202 offset:56832
	ds_read_b64_tr_b16 v[58:59], v202 offset:56896
	ds_read_b64_tr_b16 v[56:57], v202 offset:55360
	v_exp_f32_e32 v62, v52
	v_add_f32_e32 v239, 0xc0a00000, v225
	v_cvt_pk_bf16_f32 v52, v226, v227
	v_cvt_pk_bf16_f32 v53, v228, v229
	v_cvt_pk_bf16_f32 v54, v230, v231
	v_cvt_pk_bf16_f32 v55, v232, v55
	v_cmp_nge_f32_e32 vcc, v239, v169
	v_cmp_nle_f32_e64 s[6:7], v239, v223
	s_waitcnt lgkmcnt(2)
; #define LAS __attribute__((address_space(3)))
; __device__ __forceinline__ unsigned pk2(float lo, float hi) { f32x2_t v = {lo, hi}; bf16x2_t b = __builtin_convertvector(v, bf16x2_t); return __builtin_bit_cast(unsigned, b); }
; __device__ __forceinline__ s16x4 trrd(LAS const unsigned char* p) { return __builtin_bit_cast(s16x4, __builtin_amdgcn_ds_read_tr16_b64_v4i16((LAS v4i16_t*)p)); }
; __device__ __forceinline__ float attn_tile_exp(f32x16& st, int j, float tlf, float bsl, float rlo, float rhi) {
;     float sum = 0.f;
; #pragma unroll
;     for (int i = 0; i < 16; ++i) { const float tmp = (float)(32 * j - 64 + (i & 3) + 8 * (i >> 2)) + tlf;
;         float arg = __builtin_fmaf(-bsl, __builtin_fabsf(tmp), st[i]);
;         arg = (tmp >= rlo && tmp <= rhi) ? arg : -1.0e30f;
;         const float pe = __builtin_amdgcn_exp2f(arg); st[i] = pe; sum += pe; }
;     return sum;
; template <bool FUSED> __device__ __forceinline__ void attn_phase(const Args& a, LAS unsigned char* lds, int tid, int lane, int wave) {
;     ...
;         for (int j = 0; j < 5; ++j) {
;             f32x16 st;
; #pragma unroll
;             for (int i = 0; i < 16; ++i) st[i] = -mb;
;             LAS const unsigned char* kp = lds + (32 * wave + 32 * j + l31) * KP + 16 * h;
; #pragma unroll
;             for (int ks = 0; ks < 4; ++ks) { const bf16x8 kf = *(LAS const bf16x8*)(kp + 32 * ks); st = __builtin_amdgcn_mfma_f32_32x32x16_bf16(kf, qf[ks], st, 0, 0, 0); }
;             sum += attn_tile_exp(st, j, tlf, bsl, rlo, rhi);
; #pragma unroll
;             for (int s2 = 0; s2 < 2; ++s2) { u32x4 pw; pw.x = pk2(st[8 * s2 + 0], st[8 * s2 + 1]); pw.y = pk2(st[8 * s2 + 2], st[8 * s2 + 3]); pw.z = pk2(st[8 * s2 + 4], st[8 * s2 + 5]); pw.w = pk2(st[8 * s2 + 6], st[8 * s2 + 7]);
;                 const bf16x8 pf = __builtin_bit_cast(bf16x8, pw);
;                 LAS const unsigned char* vp = lds + LDS_VOFF + (32 * wave + 32 * j + 16 * s2 + 4 * h + q) * VP + 32 * blk + 8 * p;
; #pragma unroll
;                 for (int dt = 0; dt < 2; ++dt) { const s16x4 lo = trrd(vp + dt * 64), hi = trrd(vp + 8 * VP + dt * 64);
;                     const bf16x8 vf = __builtin_shufflevector(lo, hi, 0, 1, 2, 3, 4, 5, 6, 7);
;                     o[dt] = __builtin_amdgcn_mfma_f32_32x32x16_bf16(vf, pf, o[dt], 0, 0, 0); } }
;             __builtin_amdgcn_sched_barrier(0);
;         }
	v_mfma_f32_32x32x16_bf16 v[32:47], v[48:51], v[52:55], v[32:47]
	v_fma_f32 v48, v224, |v239|, v63
	s_or_b64 vcc, vcc, s[6:7]
	v_cndmask_b32_e32 v63, v48, v221, vcc
	ds_read_b64_tr_b16 v[48:49], v202 offset:58368
	ds_read_b64_tr_b16 v[50:51], v202 offset:59904
	v_exp_f32_e32 v63, v63
	s_waitcnt lgkmcnt(2)
	v_mfma_f32_32x32x16_bf16 v[16:31], v[56:59], v[52:55], v[16:31]
	ds_read_b64_tr_b16 v[58:59], v202 offset:59968
	ds_read_b64_tr_b16 v[56:57], v202 offset:58432
	v_cvt_pk_bf16_f32 v52, v233, v235
	v_cvt_pk_bf16_f32 v53, v236, v237
	v_cvt_pk_bf16_f32 v54, v60, v61
	v_cvt_pk_bf16_f32 v55, v62, v63
	s_waitcnt lgkmcnt(2)
	s_nop 0
	v_mfma_f32_32x32x16_bf16 v[32:47], v[48:51], v[52:55], v[32:47]
	v_add_f32_e32 v48, v235, v234
	v_add_f32_e32 v48, v236, v48
	v_add_f32_e32 v48, v237, v48
	v_add_f32_e32 v48, v60, v48
	v_add_f32_e32 v48, v61, v48
	v_add_f32_e32 v48, v62, v48
	v_add_f32_e32 v48, v63, v48
	s_waitcnt lgkmcnt(0)
	v_mfma_f32_32x32x16_bf16 v[16:31], v[56:59], v[52:55], v[16:31]
	v_add_f32_e32 v238, v238, v48
	ds_read_b128 v[226:229], v203
	ds_read_b128 v[230:233], v203 offset:32
	v_cmp_nge_f32_e32 vcc, v225, v169
	v_cmp_nle_f32_e64 s[6:7], v225, v223
	v_add_f32_e32 v239, 1.0, v225
	s_waitcnt lgkmcnt(1)
	v_mfma_f32_32x32x16_bf16 v[48:63], v[226:229], v[136:139], v[0:15]
	ds_read_b128 v[226:229], v203 offset:64
	ds_read_b128 v[234:237], v203 offset:96
	v_cmp_nge_f32_e64 s[8:9], v239, v169
	v_cmp_nle_f32_e64 s[10:11], v239, v223
	s_or_b64 vcc, vcc, s[6:7]
	s_waitcnt lgkmcnt(2)
	v_mfma_f32_32x32x16_bf16 v[48:63], v[230:233], v[132:135], v[48:63]
	v_add_f32_e32 v230, 2.0, v225
	v_add_f32_e32 v231, 0x40400000, v225
	v_cmp_nge_f32_e64 s[12:13], v230, v169
	v_cmp_nle_f32_e64 s[14:15], v230, v223
	v_add_f32_e32 v232, 0x41000000, v225
	v_cmp_nge_f32_e64 s[16:17], v231, v169
	v_cmp_nle_f32_e64 s[20:21], v231, v223
	s_waitcnt lgkmcnt(1)
	v_mfma_f32_32x32x16_bf16 v[48:63], v[226:229], v[128:131], v[48:63]
	v_add_f32_e32 v233, 0x41100000, v225
	v_cmp_nge_f32_e64 s[22:23], v232, v169
	v_cmp_nle_f32_e64 s[24:25], v232, v223
	v_cmp_nge_f32_e64 s[26:27], v233, v169
	v_cmp_nle_f32_e64 s[28:29], v233, v223
	s_waitcnt lgkmcnt(0)
	v_mfma_f32_32x32x16_bf16 v[48:63], v[234:237], v[140:143], v[48:63]
	s_nop 11
	v_fma_f32 v48, v224, |v225|, v48
	v_fma_f32 v49, v224, |v239|, v49
	v_cndmask_b32_e32 v48, v48, v221, vcc
	s_or_b64 vcc, s[8:9], s[10:11]
	v_fma_f32 v50, v224, |v230|, v50
	v_cndmask_b32_e32 v49, v49, v221, vcc
	s_or_b64 vcc, s[12:13], s[14:15]
	v_fma_f32 v51, v224, |v231|, v51
	v_cndmask_b32_e32 v50, v50, v221, vcc
	s_or_b64 vcc, s[16:17], s[20:21]
	v_fma_f32 v52, v224, |v232|, v52
	v_cndmask_b32_e32 v51, v51, v221, vcc
	s_or_b64 vcc, s[22:23], s[24:25]
	v_fma_f32 v53, v224, |v233|, v53
	v_cndmask_b32_e32 v52, v52, v221, vcc
	s_or_b64 vcc, s[26:27], s[28:29]
	v_exp_f32_e32 v227, v49
	v_cndmask_b32_e32 v49, v53, v221, vcc
	v_exp_f32_e32 v231, v49
	v_add_f32_e32 v49, 0x41200000, v225
	v_cmp_nge_f32_e32 vcc, v49, v169
	v_cmp_nle_f32_e64 s[6:7], v49, v223
	v_exp_f32_e32 v228, v50
	v_fma_f32 v50, v224, |v49|, v54
	s_or_b64 vcc, vcc, s[6:7]
	v_cndmask_b32_e32 v49, v50, v221, vcc
	v_exp_f32_e32 v226, v48
	v_exp_f32_e32 v232, v49
	v_add_f32_e32 v49, 0x41300000, v225
	v_cmp_nge_f32_e32 vcc, v49, v169
	v_cmp_nle_f32_e64 s[6:7], v49, v223
	v_fma_f32 v50, v224, |v49|, v55
	s_or_b64 vcc, vcc, s[6:7]
	v_exp_f32_e32 v229, v51
	v_cndmask_b32_e32 v49, v50, v221, vcc
	v_exp_f32_e32 v230, v52
	v_add_f32_e32 v48, 0, v226
	v_exp_f32_e32 v55, v49
	v_add_f32_e32 v49, 0x41800000, v225
	v_add_f32_e32 v48, v227, v48
	v_cmp_nge_f32_e32 vcc, v49, v169
	v_cmp_nle_f32_e64 s[6:7], v49, v223
	v_add_f32_e32 v48, v228, v48
	v_fma_f32 v50, v224, |v49|, v56
	s_or_b64 vcc, vcc, s[6:7]
	v_add_f32_e32 v48, v229, v48
	v_cndmask_b32_e32 v49, v50, v221, vcc
	v_add_f32_e32 v48, v230, v48
	v_exp_f32_e32 v233, v49
	v_add_f32_e32 v48, v231, v48
	v_add_f32_e32 v48, v232, v48
	v_add_f32_e32 v48, v55, v48
	v_add_f32_e32 v234, v233, v48
	v_add_f32_e32 v48, 0x41880000, v225
	v_cmp_nge_f32_e32 vcc, v48, v169
	v_cmp_nle_f32_e64 s[6:7], v48, v223
	v_fma_f32 v49, v224, |v48|, v57
	s_or_b64 vcc, vcc, s[6:7]
	v_cndmask_b32_e32 v48, v49, v221, vcc
	v_exp_f32_e32 v235, v48
	v_add_f32_e32 v48, 0x41900000, v225
	v_cmp_nge_f32_e32 vcc, v48, v169
	v_cmp_nle_f32_e64 s[6:7], v48, v223
	v_fma_f32 v49, v224, |v48|, v58
	s_or_b64 vcc, vcc, s[6:7]
	v_cndmask_b32_e32 v48, v49, v221, vcc
	v_exp_f32_e32 v236, v48
	v_add_f32_e32 v48, 0x41980000, v225
	v_cmp_nge_f32_e32 vcc, v48, v169
	v_cmp_nle_f32_e64 s[6:7], v48, v223
	v_fma_f32 v49, v224, |v48|, v59
	s_or_b64 vcc, vcc, s[6:7]
	v_cndmask_b32_e32 v48, v49, v221, vcc
	v_exp_f32_e32 v237, v48
	v_add_f32_e32 v48, 0x41c00000, v225
	v_cmp_nge_f32_e32 vcc, v48, v169
	v_cmp_nle_f32_e64 s[6:7], v48, v223
	v_fma_f32 v49, v224, |v48|, v60
	s_or_b64 vcc, vcc, s[6:7]
	v_cndmask_b32_e32 v48, v49, v221, vcc
	v_exp_f32_e32 v60, v48
	v_add_f32_e32 v48, 0x41c80000, v225
	v_cmp_nge_f32_e32 vcc, v48, v169
	v_cmp_nle_f32_e64 s[6:7], v48, v223
	v_fma_f32 v49, v224, |v48|, v61
	s_or_b64 vcc, vcc, s[6:7]
	v_cndmask_b32_e32 v48, v49, v221, vcc
	v_exp_f32_e32 v61, v48
	v_add_f32_e32 v48, 0x41d00000, v225
	v_cmp_nge_f32_e32 vcc, v48, v169
	v_cmp_nle_f32_e64 s[6:7], v48, v223
	v_fma_f32 v49, v224, |v48|, v62
	s_or_b64 vcc, vcc, s[6:7]
	v_cndmask_b32_e32 v52, v49, v221, vcc
	ds_read_b64_tr_b16 v[48:49], v204 offset:55296
	ds_read_b64_tr_b16 v[50:51], v204 offset:56832
	ds_read_b64_tr_b16 v[58:59], v204 offset:56896
	ds_read_b64_tr_b16 v[56:57], v204 offset:55360
	v_exp_f32_e32 v62, v52
	v_add_f32_e32 v239, 0x41d80000, v225
	v_cvt_pk_bf16_f32 v52, v226, v227
	v_cvt_pk_bf16_f32 v53, v228, v229
	v_cvt_pk_bf16_f32 v54, v230, v231
	v_cvt_pk_bf16_f32 v55, v232, v55
	v_cmp_nge_f32_e32 vcc, v239, v169
	v_cmp_nle_f32_e64 s[6:7], v239, v223
	s_waitcnt lgkmcnt(2)
; #define LAS __attribute__((address_space(3)))
; __device__ __forceinline__ unsigned pk2(float lo, float hi) { f32x2_t v = {lo, hi}; bf16x2_t b = __builtin_convertvector(v, bf16x2_t); return __builtin_bit_cast(unsigned, b); }
; __device__ __forceinline__ s16x4 trrd(LAS const unsigned char* p) { return __builtin_bit_cast(s16x4, __builtin_amdgcn_ds_read_tr16_b64_v4i16((LAS v4i16_t*)p)); }
; __device__ __forceinline__ float attn_tile_exp(f32x16& st, int j, float tlf, float bsl, float rlo, float rhi) {
;     float sum = 0.f;
; #pragma unroll
;     for (int i = 0; i < 16; ++i) { const float tmp = (float)(32 * j - 64 + (i & 3) + 8 * (i >> 2)) + tlf;
;         float arg = __builtin_fmaf(-bsl, __builtin_fabsf(tmp), st[i]);
;         arg = (tmp >= rlo && tmp <= rhi) ? arg : -1.0e30f;
;         const float pe = __builtin_amdgcn_exp2f(arg); st[i] = pe; sum += pe; }
;     return sum;
; template <bool FUSED> __device__ __forceinline__ void attn_phase(const Args& a, LAS unsigned char* lds, int tid, int lane, int wave) {
;     ...
;         for (int j = 0; j < 5; ++j) {
;             f32x16 st;
; #pragma unroll
;             for (int i = 0; i < 16; ++i) st[i] = -mb;
;             LAS const unsigned char* kp = lds + (32 * wave + 32 * j + l31) * KP + 16 * h;
; #pragma unroll
;             for (int ks = 0; ks < 4; ++ks) { const bf16x8 kf = *(LAS const bf16x8*)(kp + 32 * ks); st = __builtin_amdgcn_mfma_f32_32x32x16_bf16(kf, qf[ks], st, 0, 0, 0); }
;             sum += attn_tile_exp(st, j, tlf, bsl, rlo, rhi);
; #pragma unroll
;             for (int s2 = 0; s2 < 2; ++s2) { u32x4 pw; pw.x = pk2(st[8 * s2 + 0], st[8 * s2 + 1]); pw.y = pk2(st[8 * s2 + 2], st[8 * s2 + 3]); pw.z = pk2(st[8 * s2 + 4], st[8 * s2 + 5]); pw.w = pk2(st[8 * s2 + 6], st[8 * s2 + 7]);
;                 const bf16x8 pf = __builtin_bit_cast(bf16x8, pw);
;                 LAS const unsigned char* vp = lds + LDS_VOFF + (32 * wave + 32 * j + 16 * s2 + 4 * h + q) * VP + 32 * blk + 8 * p;
; #pragma unroll
;                 for (int dt = 0; dt < 2; ++dt) { const s16x4 lo = trrd(vp + dt * 64), hi = trrd(vp + 8 * VP + dt * 64);
;                     const bf16x8 vf = __builtin_shufflevector(lo, hi, 0, 1, 2, 3, 4, 5, 6, 7);
;                     o[dt] = __builtin_amdgcn_mfma_f32_32x32x16_bf16(vf, pf, o[dt], 0, 0, 0); } }
;             __builtin_amdgcn_sched_barrier(0);
;         }
	v_mfma_f32_32x32x16_bf16 v[32:47], v[48:51], v[52:55], v[32:47]
	v_fma_f32 v48, v224, |v239|, v63
	s_or_b64 vcc, vcc, s[6:7]
	v_cndmask_b32_e32 v63, v48, v221, vcc
	ds_read_b64_tr_b16 v[48:49], v204 offset:58368
	ds_read_b64_tr_b16 v[50:51], v204 offset:59904
	v_exp_f32_e32 v63, v63
	s_waitcnt lgkmcnt(2)
	v_mfma_f32_32x32x16_bf16 v[16:31], v[56:59], v[52:55], v[16:31]
	ds_read_b64_tr_b16 v[58:59], v204 offset:59968
	ds_read_b64_tr_b16 v[56:57], v204 offset:58432
	v_cvt_pk_bf16_f32 v52, v233, v235
	v_cvt_pk_bf16_f32 v53, v236, v237
	v_cvt_pk_bf16_f32 v54, v60, v61
	v_cvt_pk_bf16_f32 v55, v62, v63
	s_waitcnt lgkmcnt(2)
	s_nop 0
	v_mfma_f32_32x32x16_bf16 v[32:47], v[48:51], v[52:55], v[32:47]
	v_add_f32_e32 v48, v235, v234
	v_add_f32_e32 v48, v236, v48
	v_add_f32_e32 v48, v237, v48
	v_add_f32_e32 v48, v60, v48
	v_add_f32_e32 v48, v61, v48
	v_add_f32_e32 v48, v62, v48
	v_add_f32_e32 v48, v63, v48
	s_waitcnt lgkmcnt(0)
	v_mfma_f32_32x32x16_bf16 v[16:31], v[56:59], v[52:55], v[16:31]
	v_add_f32_e32 v238, v238, v48
	ds_read_b128 v[226:229], v205
	ds_read_b128 v[230:233], v205 offset:32
	v_add_f32_e32 v239, 0x42000000, v225
	v_add_f32_e32 v240, 0x42040000, v225
	v_cmp_nge_f32_e32 vcc, v239, v169
	s_waitcnt lgkmcnt(1)
	v_mfma_f32_32x32x16_bf16 v[48:63], v[226:229], v[136:139], v[0:15]
	ds_read_b128 v[226:229], v205 offset:64
	ds_read_b128 v[234:237], v205 offset:96
	v_cmp_nle_f32_e64 s[6:7], v239, v223
	v_add_f32_e32 v241, 0x42080000, v225
	v_cmp_nge_f32_e64 s[8:9], v240, v169
	v_cmp_nle_f32_e64 s[10:11], v240, v223
	s_or_b64 vcc, vcc, s[6:7]
	v_add_f32_e32 v242, 0x420c0000, v225
	s_waitcnt lgkmcnt(2)
	v_mfma_f32_32x32x16_bf16 v[48:63], v[230:233], v[132:135], v[48:63]
	v_cmp_nge_f32_e64 s[12:13], v241, v169
	v_cmp_nle_f32_e64 s[14:15], v241, v223
	v_add_f32_e32 v230, 0x42200000, v225
	v_cmp_nge_f32_e64 s[16:17], v242, v169
	v_cmp_nle_f32_e64 s[20:21], v242, v223
	v_add_f32_e32 v231, 0x42240000, v225
	v_cmp_nge_f32_e64 s[22:23], v230, v169
	s_waitcnt lgkmcnt(1)
	v_mfma_f32_32x32x16_bf16 v[48:63], v[226:229], v[128:131], v[48:63]
	v_cmp_nle_f32_e64 s[24:25], v230, v223
	v_cmp_nge_f32_e64 s[26:27], v231, v169
	v_cmp_nle_f32_e64 s[28:29], v231, v223
	s_waitcnt lgkmcnt(0)
	v_mfma_f32_32x32x16_bf16 v[48:63], v[234:237], v[140:143], v[48:63]
	s_nop 11
	v_fma_f32 v48, v224, |v239|, v48
	v_fma_f32 v49, v224, |v240|, v49
	v_cndmask_b32_e32 v48, v48, v221, vcc
	s_or_b64 vcc, s[8:9], s[10:11]
	v_fma_f32 v50, v224, |v241|, v50
	v_cndmask_b32_e32 v49, v49, v221, vcc
	s_or_b64 vcc, s[12:13], s[14:15]
	v_fma_f32 v51, v224, |v242|, v51
	v_cndmask_b32_e32 v50, v50, v221, vcc
	s_or_b64 vcc, s[16:17], s[20:21]
	v_fma_f32 v52, v224, |v230|, v52
	v_cndmask_b32_e32 v51, v51, v221, vcc
	s_or_b64 vcc, s[22:23], s[24:25]
	v_fma_f32 v53, v224, |v231|, v53
	v_cndmask_b32_e32 v52, v52, v221, vcc
	s_or_b64 vcc, s[26:27], s[28:29]
	v_exp_f32_e32 v227, v49
	v_cndmask_b32_e32 v49, v53, v221, vcc
	v_exp_f32_e32 v231, v49
	v_add_f32_e32 v49, 0x42280000, v225
	v_cmp_nge_f32_e32 vcc, v49, v169
	v_cmp_nle_f32_e64 s[6:7], v49, v223
	v_exp_f32_e32 v228, v50
	v_fma_f32 v50, v224, |v49|, v54
	s_or_b64 vcc, vcc, s[6:7]
	v_cndmask_b32_e32 v49, v50, v221, vcc
	v_exp_f32_e32 v226, v48
	v_exp_f32_e32 v232, v49
	v_add_f32_e32 v49, 0x422c0000, v225
	v_cmp_nge_f32_e32 vcc, v49, v169
	v_cmp_nle_f32_e64 s[6:7], v49, v223
	v_fma_f32 v50, v224, |v49|, v55
	s_or_b64 vcc, vcc, s[6:7]
	v_exp_f32_e32 v229, v51
	v_cndmask_b32_e32 v49, v50, v221, vcc
	v_exp_f32_e32 v230, v52
	v_add_f32_e32 v48, 0, v226
	v_exp_f32_e32 v55, v49
	v_add_f32_e32 v49, 0x42400000, v225
	v_add_f32_e32 v48, v227, v48
	v_cmp_nge_f32_e32 vcc, v49, v169
	v_cmp_nle_f32_e64 s[6:7], v49, v223
	v_add_f32_e32 v48, v228, v48
	v_fma_f32 v50, v224, |v49|, v56
	s_or_b64 vcc, vcc, s[6:7]
	v_add_f32_e32 v48, v229, v48
	v_cndmask_b32_e32 v49, v50, v221, vcc
	v_add_f32_e32 v48, v230, v48
	v_exp_f32_e32 v233, v49
	v_add_f32_e32 v48, v231, v48
	v_add_f32_e32 v48, v232, v48
	v_add_f32_e32 v48, v55, v48
	v_add_f32_e32 v234, v233, v48
	v_add_f32_e32 v48, 0x42440000, v225
	v_cmp_nge_f32_e32 vcc, v48, v169
	v_cmp_nle_f32_e64 s[6:7], v48, v223
	v_fma_f32 v49, v224, |v48|, v57
	s_or_b64 vcc, vcc, s[6:7]
	v_cndmask_b32_e32 v48, v49, v221, vcc
	v_exp_f32_e32 v235, v48
	v_add_f32_e32 v48, 0x42480000, v225
	v_cmp_nge_f32_e32 vcc, v48, v169
	v_cmp_nle_f32_e64 s[6:7], v48, v223
	v_fma_f32 v49, v224, |v48|, v58
	s_or_b64 vcc, vcc, s[6:7]
	v_cndmask_b32_e32 v48, v49, v221, vcc
	v_exp_f32_e32 v236, v48
	v_add_f32_e32 v48, 0x424c0000, v225
	v_cmp_nge_f32_e32 vcc, v48, v169
	v_cmp_nle_f32_e64 s[6:7], v48, v223
	v_fma_f32 v49, v224, |v48|, v59
	s_or_b64 vcc, vcc, s[6:7]
	v_cndmask_b32_e32 v48, v49, v221, vcc
	v_exp_f32_e32 v237, v48
	v_add_f32_e32 v48, 0x42600000, v225
	v_cmp_nge_f32_e32 vcc, v48, v169
	v_cmp_nle_f32_e64 s[6:7], v48, v223
	v_fma_f32 v49, v224, |v48|, v60
	s_or_b64 vcc, vcc, s[6:7]
	v_cndmask_b32_e32 v48, v49, v221, vcc
	v_exp_f32_e32 v60, v48
	v_add_f32_e32 v48, 0x42640000, v225
	v_cmp_nge_f32_e32 vcc, v48, v169
	v_cmp_nle_f32_e64 s[6:7], v48, v223
	v_fma_f32 v49, v224, |v48|, v61
	s_or_b64 vcc, vcc, s[6:7]
	v_cndmask_b32_e32 v48, v49, v221, vcc
	v_exp_f32_e32 v61, v48
	v_add_f32_e32 v48, 0x42680000, v225
	v_cmp_nge_f32_e32 vcc, v48, v169
	v_cmp_nle_f32_e64 s[6:7], v48, v223
	v_fma_f32 v49, v224, |v48|, v62
	s_or_b64 vcc, vcc, s[6:7]
	v_cndmask_b32_e32 v52, v49, v221, vcc
	ds_read_b64_tr_b16 v[48:49], v206 offset:55296
	ds_read_b64_tr_b16 v[50:51], v206 offset:56832
	ds_read_b64_tr_b16 v[58:59], v206 offset:56896
	ds_read_b64_tr_b16 v[56:57], v206 offset:55360
	v_exp_f32_e32 v62, v52
	v_add_f32_e32 v239, 0x426c0000, v225
	v_cvt_pk_bf16_f32 v52, v226, v227
	v_cvt_pk_bf16_f32 v53, v228, v229
	v_cvt_pk_bf16_f32 v54, v230, v231
	v_cvt_pk_bf16_f32 v55, v232, v55
	v_cmp_nge_f32_e32 vcc, v239, v169
	v_cmp_nle_f32_e64 s[6:7], v239, v223
	s_waitcnt lgkmcnt(2)
; #define LAS __attribute__((address_space(3)))
; __device__ __forceinline__ unsigned pk2(float lo, float hi) { f32x2_t v = {lo, hi}; bf16x2_t b = __builtin_convertvector(v, bf16x2_t); return __builtin_bit_cast(unsigned, b); }
; __device__ __forceinline__ s16x4 trrd(LAS const unsigned char* p) { return __builtin_bit_cast(s16x4, __builtin_amdgcn_ds_read_tr16_b64_v4i16((LAS v4i16_t*)p)); }
; #define ATTN_QLOAD(W) do { const bf16_t* qr_ = Qb + ((size_t)((W).b * 24 + (W).hd) * SEQ + (size_t)((W).r * (W).L + (W).i0 + 32 * wave + l31)) * 64; \
;         _Pragma("unroll") for (int ks_ = 0; ks_ < 4; ++ks_) qv[ks_] = *(const u32x4*)(qr_ + 16 * ks_ + 8 * h); } while (0)
; template <bool FUSED> __device__ __forceinline__ void attn_phase(const Args& a, LAS unsigned char* lds, int tid, int lane, int wave) {
;     ...
;         for (int j = 0; j < 5; ++j) {
;             f32x16 st;
; #pragma unroll
;             for (int i = 0; i < 16; ++i) st[i] = -mb;
;             LAS const unsigned char* kp = lds + (32 * wave + 32 * j + l31) * KP + 16 * h;
; #pragma unroll
;             for (int ks = 0; ks < 4; ++ks) { const bf16x8 kf = *(LAS const bf16x8*)(kp + 32 * ks); st = __builtin_amdgcn_mfma_f32_32x32x16_bf16(kf, qf[ks], st, 0, 0, 0); }
;             sum += attn_tile_exp(st, j, tlf, bsl, rlo, rhi);
; #pragma unroll
;             for (int s2 = 0; s2 < 2; ++s2) { u32x4 pw; pw.x = pk2(st[8 * s2 + 0], st[8 * s2 + 1]); pw.y = pk2(st[8 * s2 + 2], st[8 * s2 + 3]); pw.z = pk2(st[8 * s2 + 4], st[8 * s2 + 5]); pw.w = pk2(st[8 * s2 + 6], st[8 * s2 + 7]);
;                 const bf16x8 pf = __builtin_bit_cast(bf16x8, pw);
;                 LAS const unsigned char* vp = lds + LDS_VOFF + (32 * wave + 32 * j + 16 * s2 + 4 * h + q) * VP + 32 * blk + 8 * p;
; #pragma unroll
;                 for (int dt = 0; dt < 2; ++dt) { const s16x4 lo = trrd(vp + dt * 64), hi = trrd(vp + 8 * VP + dt * 64);
;                     const bf16x8 vf = __builtin_shufflevector(lo, hi, 0, 1, 2, 3, 4, 5, 6, 7);
;                     o[dt] = __builtin_amdgcn_mfma_f32_32x32x16_bf16(vf, pf, o[dt], 0, 0, 0); } }
;             __builtin_amdgcn_sched_barrier(0);
;         }
;         sum += __shfl_xor(sum, 32);
;         if (un < NU) { const AUnit wq = attn_decode(un, HD0, NH); ATTN_QLOAD(wq); }
;         const float inv = __builtin_amdgcn_rcpf(sum);
	v_mfma_f32_32x32x16_bf16 v[32:47], v[48:51], v[52:55], v[32:47]
	v_fma_f32 v48, v224, |v239|, v63
	s_or_b64 vcc, vcc, s[6:7]
	v_cndmask_b32_e32 v63, v48, v221, vcc
	ds_read_b64_tr_b16 v[48:49], v206 offset:58368
	ds_read_b64_tr_b16 v[50:51], v206 offset:59904
	v_exp_f32_e32 v63, v63
	s_waitcnt lgkmcnt(2)
	v_mfma_f32_32x32x16_bf16 v[16:31], v[56:59], v[52:55], v[16:31]
	ds_read_b64_tr_b16 v[58:59], v206 offset:59968
	ds_read_b64_tr_b16 v[56:57], v206 offset:58432
	v_cvt_pk_bf16_f32 v52, v233, v235
	v_cvt_pk_bf16_f32 v53, v236, v237
	v_cvt_pk_bf16_f32 v54, v60, v61
	v_cvt_pk_bf16_f32 v55, v62, v63
	s_waitcnt lgkmcnt(2)
	s_nop 0
	v_mfma_f32_32x32x16_bf16 v[32:47], v[48:51], v[52:55], v[32:47]
	v_add_f32_e32 v48, v235, v234
	v_add_f32_e32 v48, v236, v48
	v_add_f32_e32 v48, v237, v48
	v_add_f32_e32 v48, v60, v48
	v_add_f32_e32 v48, v61, v48
	v_add_f32_e32 v48, v62, v48
	v_add_f32_e32 v48, v63, v48
	s_waitcnt lgkmcnt(0)
	v_mfma_f32_32x32x16_bf16 v[16:31], v[56:59], v[52:55], v[16:31]
	v_add_f32_e32 v60, v238, v48
	ds_read_b128 v[48:51], v207
	ds_read_b128 v[52:55], v207 offset:32
	v_add_f32_e32 v61, 0x42800000, v225
	v_add_f32_e32 v62, 0x42820000, v225
	v_cmp_nge_f32_e32 vcc, v61, v169
	s_waitcnt lgkmcnt(1)
	v_mfma_f32_32x32x16_bf16 v[0:15], v[48:51], v[136:139], v[0:15]
	ds_read_b128 v[48:51], v207 offset:64
	ds_read_b128 v[56:59], v207 offset:96
	v_cmp_nle_f32_e64 s[6:7], v61, v223
	v_add_f32_e32 v63, 0x42840000, v225
	v_cmp_nge_f32_e64 s[8:9], v62, v169
	v_cmp_nle_f32_e64 s[10:11], v62, v223
	s_or_b64 vcc, vcc, s[6:7]
	v_add_f32_e32 v136, 0x42860000, v225
	s_waitcnt lgkmcnt(2)
	v_mfma_f32_32x32x16_bf16 v[0:15], v[52:55], v[132:135], v[0:15]
	v_cmp_nge_f32_e64 s[12:13], v63, v169
	v_cmp_nle_f32_e64 s[14:15], v63, v223
	v_add_f32_e32 v52, 0x42900000, v225
	v_cmp_nge_f32_e64 s[16:17], v136, v169
	v_cmp_nle_f32_e64 s[20:21], v136, v223
	v_add_f32_e32 v53, 0x42920000, v225
	v_cmp_nge_f32_e64 s[22:23], v52, v169
	s_waitcnt lgkmcnt(1)
	v_mfma_f32_32x32x16_bf16 v[0:15], v[48:51], v[128:131], v[0:15]
	v_cmp_nle_f32_e64 s[24:25], v52, v223
	v_cmp_nge_f32_e64 s[26:27], v53, v169
	v_cmp_nle_f32_e64 s[28:29], v53, v223
	s_waitcnt lgkmcnt(0)
	v_mfma_f32_32x32x16_bf16 v[0:15], v[56:59], v[140:143], v[0:15]
	s_nop 11
	v_fma_f32 v0, v224, |v61|, v0
	v_fma_f32 v1, v224, |v62|, v1
	v_cndmask_b32_e32 v0, v0, v221, vcc
	s_or_b64 vcc, s[8:9], s[10:11]
	v_fma_f32 v2, v224, |v63|, v2
	v_cndmask_b32_e32 v1, v1, v221, vcc
	s_or_b64 vcc, s[12:13], s[14:15]
	v_fma_f32 v3, v224, |v136|, v3
	v_cndmask_b32_e32 v2, v2, v221, vcc
	s_or_b64 vcc, s[16:17], s[20:21]
	v_fma_f32 v4, v224, |v52|, v4
	v_cndmask_b32_e32 v3, v3, v221, vcc
	s_or_b64 vcc, s[22:23], s[24:25]
	v_fma_f32 v5, v224, |v53|, v5
	v_cndmask_b32_e32 v4, v4, v221, vcc
	s_or_b64 vcc, s[26:27], s[28:29]
	v_exp_f32_e32 v49, v1
	v_cndmask_b32_e32 v1, v5, v221, vcc
	v_exp_f32_e32 v53, v1
	v_add_f32_e32 v1, 0x42940000, v225
	v_cmp_nge_f32_e32 vcc, v1, v169
	v_cmp_nle_f32_e64 s[6:7], v1, v223
	v_exp_f32_e32 v50, v2
	v_fma_f32 v2, v224, |v1|, v6
	s_or_b64 vcc, vcc, s[6:7]
	v_cndmask_b32_e32 v1, v2, v221, vcc
	v_exp_f32_e32 v48, v0
	v_exp_f32_e32 v54, v1
	v_add_f32_e32 v1, 0x42960000, v225
	v_cmp_nge_f32_e32 vcc, v1, v169
	v_cmp_nle_f32_e64 s[6:7], v1, v223
	v_fma_f32 v2, v224, |v1|, v7
	s_or_b64 vcc, vcc, s[6:7]
	v_exp_f32_e32 v51, v3
	v_cndmask_b32_e32 v1, v2, v221, vcc
	v_exp_f32_e32 v52, v4
	v_add_f32_e32 v0, 0, v48
	v_exp_f32_e32 v7, v1
	v_add_f32_e32 v1, 0x42a00000, v225
	v_add_f32_e32 v0, v49, v0
	v_cmp_nge_f32_e32 vcc, v1, v169
	v_cmp_nle_f32_e64 s[6:7], v1, v223
	v_add_f32_e32 v0, v50, v0
	v_fma_f32 v2, v224, |v1|, v8
	s_or_b64 vcc, vcc, s[6:7]
	v_add_f32_e32 v0, v51, v0
	v_cndmask_b32_e32 v1, v2, v221, vcc
	v_add_f32_e32 v0, v52, v0
	v_exp_f32_e32 v55, v1
	v_add_f32_e32 v0, v53, v0
	v_add_f32_e32 v0, v54, v0
	v_add_f32_e32 v0, v7, v0
	v_add_f32_e32 v56, v55, v0
	v_add_f32_e32 v0, 0x42a20000, v225
	v_cmp_nge_f32_e32 vcc, v0, v169
	v_cmp_nle_f32_e64 s[6:7], v0, v223
	v_fma_f32 v1, v224, |v0|, v9
	s_or_b64 vcc, vcc, s[6:7]
	v_cndmask_b32_e32 v0, v1, v221, vcc
	v_exp_f32_e32 v57, v0
	v_add_f32_e32 v0, 0x42a40000, v225
	v_cmp_nge_f32_e32 vcc, v0, v169
	v_cmp_nle_f32_e64 s[6:7], v0, v223
	v_fma_f32 v1, v224, |v0|, v10
	s_or_b64 vcc, vcc, s[6:7]
	v_cndmask_b32_e32 v0, v1, v221, vcc
	v_exp_f32_e32 v58, v0
	v_add_f32_e32 v0, 0x42a60000, v225
	v_cmp_nge_f32_e32 vcc, v0, v169
	v_cmp_nle_f32_e64 s[6:7], v0, v223
	v_fma_f32 v1, v224, |v0|, v11
	s_or_b64 vcc, vcc, s[6:7]
	v_cndmask_b32_e32 v0, v1, v221, vcc
	v_exp_f32_e32 v59, v0
	v_add_f32_e32 v0, 0x42b00000, v225
	v_cmp_nge_f32_e32 vcc, v0, v169
	v_cmp_nle_f32_e64 s[6:7], v0, v223
	v_fma_f32 v1, v224, |v0|, v12
	s_or_b64 vcc, vcc, s[6:7]
	v_cndmask_b32_e32 v0, v1, v221, vcc
	v_exp_f32_e32 v12, v0
	v_add_f32_e32 v0, 0x42b20000, v225
	v_cmp_nge_f32_e32 vcc, v0, v169
	v_cmp_nle_f32_e64 s[6:7], v0, v223
	v_fma_f32 v1, v224, |v0|, v13
	s_or_b64 vcc, vcc, s[6:7]
	v_cndmask_b32_e32 v0, v1, v221, vcc
	v_exp_f32_e32 v13, v0
	v_add_f32_e32 v0, 0x42b40000, v225
	v_cmp_nge_f32_e32 vcc, v0, v169
	v_cmp_nle_f32_e64 s[6:7], v0, v223
	v_fma_f32 v1, v224, |v0|, v14
	s_or_b64 vcc, vcc, s[6:7]
	v_cndmask_b32_e32 v4, v1, v221, vcc
	ds_read_b64_tr_b16 v[0:1], v208 offset:55296
	ds_read_b64_tr_b16 v[2:3], v208 offset:56832
	ds_read_b64_tr_b16 v[10:11], v208 offset:56896
	ds_read_b64_tr_b16 v[8:9], v208 offset:55360
	v_exp_f32_e32 v14, v4
	v_add_f32_e32 v61, 0x42b60000, v225
	v_cvt_pk_bf16_f32 v4, v48, v49
	v_cvt_pk_bf16_f32 v5, v50, v51
	v_cvt_pk_bf16_f32 v6, v52, v53
	v_cvt_pk_bf16_f32 v7, v54, v7
	v_cmp_nge_f32_e32 vcc, v61, v169
	v_cmp_nle_f32_e64 s[6:7], v61, v223
	s_waitcnt lgkmcnt(2)
	v_mfma_f32_32x32x16_bf16 v[32:47], v[0:3], v[4:7], v[32:47]
	v_fma_f32 v0, v224, |v61|, v15
	s_or_b64 vcc, vcc, s[6:7]
	v_cndmask_b32_e32 v15, v0, v221, vcc
	ds_read_b64_tr_b16 v[0:1], v208 offset:58368
	ds_read_b64_tr_b16 v[2:3], v208 offset:59904
	v_exp_f32_e32 v15, v15
	s_waitcnt lgkmcnt(2)
	v_mfma_f32_32x32x16_bf16 v[16:31], v[8:11], v[4:7], v[16:31]
	ds_read_b64_tr_b16 v[10:11], v208 offset:59968
	ds_read_b64_tr_b16 v[8:9], v208 offset:58432
	v_cvt_pk_bf16_f32 v4, v55, v57
	v_cvt_pk_bf16_f32 v5, v58, v59
	v_cvt_pk_bf16_f32 v6, v12, v13
	v_cvt_pk_bf16_f32 v7, v14, v15
	s_waitcnt lgkmcnt(2)
	s_nop 0
	v_mfma_f32_32x32x16_bf16 v[32:47], v[0:3], v[4:7], v[32:47]
	v_add_f32_e32 v0, v57, v56
	v_add_f32_e32 v0, v58, v0
	v_add_f32_e32 v0, v59, v0
	v_add_f32_e32 v0, v12, v0
	v_add_f32_e32 v0, v13, v0
	v_add_f32_e32 v0, v14, v0
	v_add_f32_e32 v0, v15, v0
	s_waitcnt lgkmcnt(0)
	v_mfma_f32_32x32x16_bf16 v[16:31], v[8:11], v[4:7], v[16:31]
	v_add_f32_e32 v0, v60, v0
	ds_bpermute_b32 v1, v153, v0
	s_andn2_b64 vcc, exec, s[72:73]
	s_cbranch_vccnz .LBB0_284
; #define ATTN_QLOAD(W) do { const bf16_t* qr_ = Qb + ((size_t)((W).b * 24 + (W).hd) * SEQ + (size_t)((W).r * (W).L + (W).i0 + 32 * wave + l31)) * 64; \
;         _Pragma("unroll") for (int ks_ = 0; ks_ < 4; ++ks_) qv[ks_] = *(const u32x4*)(qr_ + 16 * ks_ + 8 * h); } while (0)
; template <bool FUSED> __device__ __forceinline__ void attn_phase(const Args& a, LAS unsigned char* lds, int tid, int lane, int wave) {
;     ...
;         if (un < NU) { const AUnit wq = attn_decode(un, HD0, NH); ATTN_QLOAD(wq); }
	s_ashr_i32 s7, s69, 5
	s_lshr_b32 s8, s7, 28
	s_add_i32 s8, s7, s8
	s_and_b32 s8, s8, -16
	s_sub_i32 s7, s7, s8
	s_add_i32 s7, s7, 8
	s_ashr_i32 s8, s69, 31
	s_ashr_i32 s9, s7, 2
	s_lshr_b32 s8, s8, 23
	s_and_b32 s9, s9, -2
	s_add_i32 s8, s69, s8
	s_lshr_b32 s10, 32, s9
	s_and_b32 s6, s69, 31
	s_ashr_i32 s8, s8, 9
	s_lshr_b32 s11, 0x2000, s9
	s_sub_i32 s9, 5, s9
	s_add_i32 s10, s10, -1
	s_lshr_b32 s9, s6, s9
	s_and_b32 s6, s10, s6
	s_mul_i32 s8, s8, 24
	s_lshl_b32 s10, s6, 8
	s_add_i32 s6, s7, s8
	s_mul_i32 s9, s9, s11
	s_ashr_i32 s7, s6, 31
	s_add_i32 s10, s10, s9
	v_add_u32_e32 v2, s10, v145
	s_lshl_b64 s[6:7], s[6:7], 20
	v_ashrrev_i32_e32 v3, 31, v2
	s_add_u32 s6, s40, s6
	s_addc_u32 s7, s41, s7
	v_lshlrev_b64 v[2:3], 7, v[2:3]
	v_lshl_add_u64 v[2:3], s[6:7], 0, v[2:3]
	v_lshl_add_u64 v[2:3], v[148:149], 1, v[2:3]
	global_load_dwordx4 v[88:91], v[2:3], off
	global_load_dwordx4 v[92:95], v[2:3], off offset:32
	global_load_dwordx4 v[100:103], v[2:3], off offset:64
	global_load_dwordx4 v[108:111], v[2:3], off offset:96

; #define LAS __attribute__((address_space(3)))
; __device__ __forceinline__ unsigned pk2(float lo, float hi) { f32x2_t v = {lo, hi}; bf16x2_t b = __builtin_convertvector(v, bf16x2_t); return __builtin_bit_cast(unsigned, b); }
; template <int CTRL> __device__ __forceinline__ float dpp_movf(float v) { return __builtin_bit_cast(float, dpp_mov<CTRL>(__builtin_bit_cast(unsigned, v))); }
; template <bool FUSED> __device__ __forceinline__ void attn_phase(const Args& a, LAS unsigned char* lds, int tid, int lane, int wave) {
;     ...
;         {
;             const int ch = tid & 7;
;             const f32x4 g0 = *(const f32x4*)(a.kw + hd * 64 + ch * 8), g1 = *(const f32x4*)(a.kw + hd * 64 + ch * 8 + 4);
; #pragma unroll
;             for (int i = 0; i < 6; ++i) { const int row = (tid + 512 * i) >> 3;
;                 const float e0 = bflo(kv[i].x), e1 = bfhi(kv[i].x), e2 = bflo(kv[i].y), e3 = bfhi(kv[i].y), e4 = bflo(kv[i].z), e5 = bfhi(kv[i].z), e6 = bflo(kv[i].w), e7 = bfhi(kv[i].w);
;                 float ss = (e0 * e0 + e1 * e1) + (e2 * e2 + e3 * e3) + (e4 * e4 + e5 * e5) + (e6 * e6 + e7 * e7);
;                 ss += dpp_movf<0xB1>(ss); ss += dpp_movf<0x4E>(ss); ss += dpp_movf<0x141>(ss);
;                 const float rk = __builtin_amdgcn_rsqf(ss * (1.f / 64.f) + 1e-6f);
;                 u32x4 wv; wv.x = pk2(e0 * rk * g0.x, e1 * rk * g0.y); wv.y = pk2(e2 * rk * g0.z, e3 * rk * g0.w); wv.z = pk2(e4 * rk * g1.x, e5 * rk * g1.y); wv.w = pk2(e6 * rk * g1.z, e7 * rk * g1.w);
;                 *(LAS u32x4*)(lds + row * KP + ch * 16) = wv;
;                 *(LAS u32x4*)(lds + LDS_VOFF + row * VP + ch * 16) = vv[i];
;                 if (i & 1) __builtin_amdgcn_sched_barrier(0); }
;         }
.LBB0_402:
	s_ashr_i32 s6, s46, 5
	s_lshr_b32 s7, s6, 29
	s_add_i32 s7, s6, s7
	s_and_b32 s7, s7, -8
	s_sub_i32 s6, s6, s7
	s_lshl_b32 s8, s6, 6
	s_ashr_i32 s9, s8, 31
	s_lshl_b64 s[8:9], s[8:9], 2
	v_lshl_add_u64 v[0:1], v[164:165], 0, s[8:9]
	global_load_dwordx4 v[4:7], v[0:1], off
	s_nop 0
	global_load_dwordx4 v[0:3], v[0:1], off offset:16
	s_waitcnt vmcnt(17)
	v_and_b32_e32 v9, 0xffff0000, v67
	v_and_b32_e32 v11, 0xffff0000, v66
	v_and_b32_e32 v13, 0xffff0000, v65
	v_and_b32_e32 v15, 0xffff0000, v64
	s_waitcnt vmcnt(15)
	v_and_b32_e32 v21, 0xffff0000, v73
	v_and_b32_e32 v23, 0xffff0000, v72
	v_lshlrev_b32_e32 v8, 16, v67
	v_lshlrev_b32_e32 v10, 16, v66
	v_lshlrev_b32_e32 v12, 16, v65
	v_lshlrev_b32_e32 v14, 16, v64
	v_and_b32_e32 v17, 0xffff0000, v75
	v_and_b32_e32 v19, 0xffff0000, v74
	v_lshlrev_b32_e32 v20, 16, v73
	v_lshlrev_b32_e32 v22, 16, v72
	v_mov_b32_e32 v26, v9
	v_mov_b32_e32 v27, v11
	v_mov_b32_e32 v30, v15
	v_mov_b32_e32 v31, v13
	v_mov_b32_e32 v38, v23
	v_mov_b32_e32 v39, v21
	v_lshlrev_b32_e32 v16, 16, v75
	v_lshlrev_b32_e32 v18, 16, v74
	v_mov_b32_e32 v24, v8
	v_mov_b32_e32 v25, v10
	v_mov_b32_e32 v28, v14
	v_mov_b32_e32 v29, v12
	v_mov_b32_e32 v34, v17
	v_mov_b32_e32 v35, v19
	v_mov_b32_e32 v36, v22
	v_mov_b32_e32 v37, v20
	v_pk_mul_f32 v[26:27], v[26:27], v[26:27]
	v_pk_mul_f32 v[30:31], v[30:31], v[30:31]
	v_pk_mul_f32 v[38:39], v[38:39], v[38:39]
	v_mov_b32_e32 v32, v16
	v_mov_b32_e32 v33, v18
	v_pk_mul_f32 v[34:35], v[34:35], v[34:35]
	v_pk_fma_f32 v[24:25], v[24:25], v[24:25], v[26:27]
	v_pk_fma_f32 v[26:27], v[28:29], v[28:29], v[30:31]
	v_pk_fma_f32 v[30:31], v[36:37], v[36:37], v[38:39]
	v_pk_fma_f32 v[28:29], v[32:33], v[32:33], v[34:35]
	v_add_f32_e32 v26, v26, v27
	v_add_f32_e32 v27, v30, v31
	v_add_f32_e32 v25, v25, v26
	v_add_f32_e32 v26, v29, v27
	v_add_f32_e32 v24, v24, v25
	v_add_f32_e32 v25, v28, v26
	s_nop 0
	v_add_f32_dpp v24, v24, v24 quad_perm:[1,0,3,2] row_mask:0xf bank_mask:0xf bound_ctrl:1
	v_add_f32_dpp v25, v25, v25 quad_perm:[1,0,3,2] row_mask:0xf bank_mask:0xf bound_ctrl:1
	s_nop 0
	v_add_f32_dpp v24, v24, v24 quad_perm:[2,3,0,1] row_mask:0xf bank_mask:0xf bound_ctrl:1
	v_add_f32_dpp v25, v25, v25 quad_perm:[2,3,0,1] row_mask:0xf bank_mask:0xf bound_ctrl:1
	s_nop 0
	v_add_f32_dpp v24, v24, v24 row_half_mirror row_mask:0xf bank_mask:0xf bound_ctrl:1
	v_add_f32_dpp v25, v25, v25 row_half_mirror row_mask:0xf bank_mask:0xf bound_ctrl:1
	v_fmamk_f32 v24, v24, 0x3c800000, v186
	v_fmamk_f32 v25, v25, 0x3c800000, v186
	v_rsq_f32_e32 v24, v24
	v_rsq_f32_e32 v26, v25
	v_pk_mul_f32 v[14:15], v[24:25], v[14:15] op_sel_hi:[0,1]
	v_pk_mul_f32 v[12:13], v[24:25], v[12:13] op_sel_hi:[0,1]
	v_pk_mul_f32 v[10:11], v[24:25], v[10:11] op_sel_hi:[0,1]
	v_pk_mul_f32 v[8:9], v[24:25], v[8:9] op_sel_hi:[0,1]
	v_pk_mul_f32 v[22:23], v[26:27], v[22:23] op_sel_hi:[0,1]
	v_pk_mul_f32 v[20:21], v[26:27], v[20:21] op_sel_hi:[0,1]
	v_pk_mul_f32 v[18:19], v[26:27], v[18:19] op_sel_hi:[0,1]
	v_pk_mul_f32 v[16:17], v[26:27], v[16:17] op_sel_hi:[0,1]
	s_waitcnt vmcnt(1)
	v_pk_mul_f32 v[14:15], v[4:5], v[14:15]
	v_pk_mul_f32 v[12:13], v[6:7], v[12:13]
	s_waitcnt vmcnt(0)
	v_pk_mul_f32 v[10:11], v[0:1], v[10:11]
	v_pk_mul_f32 v[24:25], v[2:3], v[8:9]
	v_pk_mul_f32 v[22:23], v[4:5], v[22:23]
	v_pk_mul_f32 v[20:21], v[6:7], v[20:21]
	v_pk_mul_f32 v[18:19], v[0:1], v[18:19]
	v_pk_mul_f32 v[16:17], v[2:3], v[16:17]
	v_cvt_pk_bf16_f32 v8, v14, v15
	v_cvt_pk_bf16_f32 v9, v12, v13
	v_cvt_pk_bf16_f32 v10, v10, v11
	v_cvt_pk_bf16_f32 v11, v24, v25
	v_cvt_pk_bf16_f32 v12, v22, v23
	v_cvt_pk_bf16_f32 v13, v20, v21
	v_cvt_pk_bf16_f32 v14, v18, v19
	v_cvt_pk_bf16_f32 v15, v16, v17
	ds_write_b128 v194, v[8:11]
	ds_write_b128 v195, v[68:71] offset:55296
	ds_write_b128 v196, v[12:15]
	ds_write_b128 v197, v[76:79] offset:55296
	v_and_b32_e32 v13, 0xffff0000, v83
	v_and_b32_e32 v11, 0xffff0000, v82
	v_lshlrev_b32_e32 v12, 16, v83
	v_lshlrev_b32_e32 v10, 16, v82
	v_mov_b32_e32 v14, v13
	v_mov_b32_e32 v15, v11
	v_mov_b32_e32 v8, v12
	v_mov_b32_e32 v9, v10
	v_pk_mul_f32 v[14:15], v[14:15], v[14:15]
	v_and_b32_e32 v17, 0xffff0000, v80
	v_pk_fma_f32 v[8:9], v[8:9], v[8:9], v[14:15]
	v_and_b32_e32 v15, 0xffff0000, v81
	v_lshlrev_b32_e32 v14, 16, v81
	v_lshlrev_b32_e32 v16, 16, v80
	v_mov_b32_e32 v20, v17
	v_mov_b32_e32 v21, v15
	v_mov_b32_e32 v18, v16
	v_mov_b32_e32 v19, v14
	v_pk_mul_f32 v[20:21], v[20:21], v[20:21]
	v_and_b32_e32 v23, 0xffff0000, v88
	v_pk_fma_f32 v[18:19], v[18:19], v[18:19], v[20:21]
	v_lshlrev_b32_e32 v22, 16, v88
	v_add_f32_e32 v18, v18, v19
	v_add_f32_e32 v9, v9, v18
	v_add_f32_e32 v8, v8, v9
	v_mov_b32_e32 v26, v23
	v_mov_b32_e32 v24, v22
	v_add_f32_dpp v8, v8, v8 quad_perm:[1,0,3,2] row_mask:0xf bank_mask:0xf bound_ctrl:1
	s_nop 1
	v_add_f32_dpp v8, v8, v8 quad_perm:[2,3,0,1] row_mask:0xf bank_mask:0xf bound_ctrl:1
	s_nop 1
	v_add_f32_dpp v8, v8, v8 row_half_mirror row_mask:0xf bank_mask:0xf bound_ctrl:1
	v_fmamk_f32 v8, v8, 0x3c800000, v186
	v_rsq_f32_e32 v18, v8
	s_nop 0
	v_pk_mul_f32 v[8:9], v[18:19], v[16:17] op_sel_hi:[0,1]
	v_pk_mul_f32 v[14:15], v[18:19], v[14:15] op_sel_hi:[0,1]
	v_pk_mul_f32 v[8:9], v[4:5], v[8:9]
	v_pk_mul_f32 v[14:15], v[6:7], v[14:15]
	v_cvt_pk_bf16_f32 v8, v8, v9
	v_cvt_pk_bf16_f32 v9, v14, v15
	v_and_b32_e32 v15, 0xffff0000, v91
	v_and_b32_e32 v17, 0xffff0000, v90
	v_lshlrev_b32_e32 v14, 16, v91
	v_lshlrev_b32_e32 v16, 16, v90
	v_mov_b32_e32 v20, v15
	v_mov_b32_e32 v21, v17
	v_pk_mul_f32 v[10:11], v[18:19], v[10:11] op_sel_hi:[0,1]
	v_pk_mul_f32 v[12:13], v[18:19], v[12:13] op_sel_hi:[0,1]
	v_mov_b32_e32 v18, v14
	v_mov_b32_e32 v19, v16
	v_pk_mul_f32 v[20:21], v[20:21], v[20:21]
; #define LAS __attribute__((address_space(3)))
; template <int CTRL> __device__ __forceinline__ float dpp_movf(float v) { return __builtin_bit_cast(float, dpp_mov<CTRL>(__builtin_bit_cast(unsigned, v))); }
; template <bool FUSED> __device__ __forceinline__ void attn_phase(const Args& a, LAS unsigned char* lds, int tid, int lane, int wave) {
;     ...
;             for (int i = 0; i < 6; ++i) { const int row = (tid + 512 * i) >> 3;
;                 const float e0 = bflo(kv[i].x), e1 = bfhi(kv[i].x), e2 = bflo(kv[i].y), e3 = bfhi(kv[i].y), e4 = bflo(kv[i].z), e5 = bfhi(kv[i].z), e6 = bflo(kv[i].w), e7 = bfhi(kv[i].w);
;                 float ss = (e0 * e0 + e1 * e1) + (e2 * e2 + e3 * e3) + (e4 * e4 + e5 * e5) + (e6 * e6 + e7 * e7);
;                 ss += dpp_movf<0xB1>(ss); ss += dpp_movf<0x4E>(ss); ss += dpp_movf<0x141>(ss);
;                 const float rk = __builtin_amdgcn_rsqf(ss * (1.f / 64.f) + 1e-6f);
;                 u32x4 wv; wv.x = pk2(e0 * rk * g0.x, e1 * rk * g0.y); wv.y = pk2(e2 * rk * g0.z, e3 * rk * g0.w); wv.z = pk2(e4 * rk * g1.x, e5 * rk * g1.y); wv.w = pk2(e6 * rk * g1.z, e7 * rk * g1.w);
;                 *(LAS u32x4*)(lds + row * KP + ch * 16) = wv;
;                 *(LAS u32x4*)(lds + LDS_VOFF + row * VP + ch * 16) = vv[i];
;                 if (i & 1) __builtin_amdgcn_sched_barrier(0); }
;         }
;         bf16x8 qf[4];
;         {
;             float ss = 0.f;
; #pragma unroll
;             for (int ks = 0; ks < 4; ++ks)
; #pragma unroll
;                 for (int e = 0; e < 4; ++e) { const float lo = bflo(qv[ks][e]), hi = bfhi(qv[ks][e]); ss += lo * lo + hi * hi; }
;             ss += __shfl_xor(ss, 32);
;             const float rq = 0.125f * LOG2E * __builtin_amdgcn_rsqf(ss * (1.f / 64.f) + 1e-6f);
; #pragma unroll
;             for (int ks = 0; ks < 4; ++ks) { const f32x4 g0 = *(const f32x4*)(a.qw + hd * 64 + 16 * ks + 8 * h), g1 = *(const f32x4*)(a.qw + hd * 64 + 16 * ks + 8 * h + 4); u32x4 wv;
;                 wv.x = pk2(bflo(qv[ks].x) * rq * g0.x, bfhi(qv[ks].x) * rq * g0.y); wv.y = pk2(bflo(qv[ks].y) * rq * g0.z, bfhi(qv[ks].y) * rq * g0.w);
;                 wv.z = pk2(bflo(qv[ks].z) * rq * g1.x, bfhi(qv[ks].z) * rq * g1.y); wv.w = pk2(bflo(qv[ks].w) * rq * g1.z, bfhi(qv[ks].w) * rq * g1.w);
;                 qf[ks] = __builtin_bit_cast(bf16x8, wv); }
;         }
;         const float mb = ((const float*)(a.ws + WS_RS))[hd];
	v_pk_mul_f32 v[10:11], v[0:1], v[10:11]
	v_pk_fma_f32 v[18:19], v[18:19], v[18:19], v[20:21]
	v_and_b32_e32 v21, 0xffff0000, v89
	v_lshlrev_b32_e32 v20, 16, v89
	v_mov_b32_e32 v27, v21
	v_mov_b32_e32 v25, v20
	v_pk_mul_f32 v[26:27], v[26:27], v[26:27]
	v_cvt_pk_bf16_f32 v10, v10, v11
	v_pk_fma_f32 v[24:25], v[24:25], v[24:25], v[26:27]
	v_pk_mul_f32 v[12:13], v[2:3], v[12:13]
	v_add_f32_e32 v11, v24, v25
	v_add_f32_e32 v11, v19, v11
	v_add_f32_e32 v11, v18, v11
	s_nop 1
	v_add_f32_dpp v11, v11, v11 quad_perm:[1,0,3,2] row_mask:0xf bank_mask:0xf bound_ctrl:1
	s_nop 1
	v_add_f32_dpp v11, v11, v11 quad_perm:[2,3,0,1] row_mask:0xf bank_mask:0xf bound_ctrl:1
	s_nop 1
	v_add_f32_dpp v11, v11, v11 row_half_mirror row_mask:0xf bank_mask:0xf bound_ctrl:1
	v_fmamk_f32 v11, v11, 0x3c800000, v186
	v_rsq_f32_e32 v18, v11
	v_cvt_pk_bf16_f32 v11, v12, v13
	ds_write_b128 v198, v[8:11]
	ds_write_b128 v199, v[84:87] offset:55296
	v_pk_mul_f32 v[8:9], v[18:19], v[22:23] op_sel_hi:[0,1]
	v_pk_mul_f32 v[10:11], v[18:19], v[20:21] op_sel_hi:[0,1]
	v_pk_mul_f32 v[8:9], v[4:5], v[8:9]
	v_pk_mul_f32 v[10:11], v[6:7], v[10:11]
	v_cvt_pk_bf16_f32 v8, v8, v9
	v_cvt_pk_bf16_f32 v9, v10, v11
	v_pk_mul_f32 v[10:11], v[18:19], v[16:17] op_sel_hi:[0,1]
	v_pk_mul_f32 v[12:13], v[18:19], v[14:15] op_sel_hi:[0,1]
	v_pk_mul_f32 v[10:11], v[0:1], v[10:11]
	v_pk_mul_f32 v[12:13], v[2:3], v[12:13]
	v_cvt_pk_bf16_f32 v10, v10, v11
	v_cvt_pk_bf16_f32 v11, v12, v13
	ds_write_b128 v200, v[8:11]
	ds_write_b128 v201, v[92:95] offset:55296
	v_and_b32_e32 v13, 0xffff0000, v115
	v_and_b32_e32 v11, 0xffff0000, v114
	v_lshlrev_b32_e32 v12, 16, v115
	v_lshlrev_b32_e32 v10, 16, v114
	v_mov_b32_e32 v14, v13
	v_mov_b32_e32 v15, v11
	v_mov_b32_e32 v8, v12
	v_mov_b32_e32 v9, v10
	v_pk_mul_f32 v[14:15], v[14:15], v[14:15]
	v_and_b32_e32 v17, 0xffff0000, v112
	v_pk_fma_f32 v[8:9], v[8:9], v[8:9], v[14:15]
	v_and_b32_e32 v15, 0xffff0000, v113
	v_lshlrev_b32_e32 v14, 16, v113
	v_lshlrev_b32_e32 v16, 16, v112
	v_mov_b32_e32 v20, v17
	v_mov_b32_e32 v21, v15
	v_mov_b32_e32 v18, v16
	v_mov_b32_e32 v19, v14
	v_pk_mul_f32 v[20:21], v[20:21], v[20:21]
	v_and_b32_e32 v23, 0xffff0000, v120
	v_pk_fma_f32 v[18:19], v[18:19], v[18:19], v[20:21]
	v_lshlrev_b32_e32 v22, 16, v120
	v_add_f32_e32 v18, v18, v19
	v_add_f32_e32 v9, v9, v18
	v_add_f32_e32 v8, v8, v9
	v_mov_b32_e32 v26, v23
	v_mov_b32_e32 v24, v22
	v_add_f32_dpp v8, v8, v8 quad_perm:[1,0,3,2] row_mask:0xf bank_mask:0xf bound_ctrl:1
	s_nop 1
	v_add_f32_dpp v8, v8, v8 quad_perm:[2,3,0,1] row_mask:0xf bank_mask:0xf bound_ctrl:1
	s_nop 1
	v_add_f32_dpp v8, v8, v8 row_half_mirror row_mask:0xf bank_mask:0xf bound_ctrl:1
	v_fmamk_f32 v8, v8, 0x3c800000, v186
	v_rsq_f32_e32 v18, v8
	s_nop 0
	v_pk_mul_f32 v[8:9], v[18:19], v[16:17] op_sel_hi:[0,1]
	v_pk_mul_f32 v[14:15], v[18:19], v[14:15] op_sel_hi:[0,1]
	v_pk_mul_f32 v[8:9], v[4:5], v[8:9]
	v_pk_mul_f32 v[14:15], v[6:7], v[14:15]
	v_cvt_pk_bf16_f32 v8, v8, v9
	v_cvt_pk_bf16_f32 v9, v14, v15
	v_and_b32_e32 v15, 0xffff0000, v123
	v_and_b32_e32 v17, 0xffff0000, v122
	v_lshlrev_b32_e32 v14, 16, v123
	v_lshlrev_b32_e32 v16, 16, v122
	v_mov_b32_e32 v20, v15
	v_mov_b32_e32 v21, v17
	v_pk_mul_f32 v[10:11], v[18:19], v[10:11] op_sel_hi:[0,1]
	v_pk_mul_f32 v[12:13], v[18:19], v[12:13] op_sel_hi:[0,1]
	v_mov_b32_e32 v18, v14
	v_mov_b32_e32 v19, v16
	v_pk_mul_f32 v[20:21], v[20:21], v[20:21]
	v_pk_mul_f32 v[10:11], v[0:1], v[10:11]
	v_pk_fma_f32 v[18:19], v[18:19], v[18:19], v[20:21]
	v_and_b32_e32 v21, 0xffff0000, v121
	v_lshlrev_b32_e32 v20, 16, v121
	v_mov_b32_e32 v27, v21
	v_mov_b32_e32 v25, v20
	v_pk_mul_f32 v[26:27], v[26:27], v[26:27]
	v_cvt_pk_bf16_f32 v10, v10, v11
	v_pk_fma_f32 v[24:25], v[24:25], v[24:25], v[26:27]
	v_pk_mul_f32 v[12:13], v[2:3], v[12:13]
	v_add_f32_e32 v11, v24, v25
	v_add_f32_e32 v11, v19, v11
	v_add_f32_e32 v11, v18, v11
	s_nop 1
	v_add_f32_dpp v11, v11, v11 quad_perm:[1,0,3,2] row_mask:0xf bank_mask:0xf bound_ctrl:1
	s_nop 1
	v_add_f32_dpp v11, v11, v11 quad_perm:[2,3,0,1] row_mask:0xf bank_mask:0xf bound_ctrl:1
	s_nop 1
	v_add_f32_dpp v11, v11, v11 row_half_mirror row_mask:0xf bank_mask:0xf bound_ctrl:1
	v_fmamk_f32 v11, v11, 0x3c800000, v186
	v_rsq_f32_e32 v18, v11
	v_cvt_pk_bf16_f32 v11, v12, v13
	ds_write_b128 v202, v[8:11]
	ds_write_b128 v203, v[116:119] offset:55296
	v_pk_mul_f32 v[8:9], v[18:19], v[22:23] op_sel_hi:[0,1]
	v_pk_mul_f32 v[4:5], v[4:5], v[8:9]
	v_pk_mul_f32 v[8:9], v[18:19], v[20:21] op_sel_hi:[0,1]
	v_pk_mul_f32 v[6:7], v[6:7], v[8:9]
	v_cvt_pk_bf16_f32 v4, v4, v5
	v_cvt_pk_bf16_f32 v5, v6, v7
	v_pk_mul_f32 v[6:7], v[18:19], v[16:17] op_sel_hi:[0,1]
	v_pk_mul_f32 v[0:1], v[0:1], v[6:7]
	s_nop 0
	v_cvt_pk_bf16_f32 v6, v0, v1
	v_pk_mul_f32 v[0:1], v[18:19], v[14:15] op_sel_hi:[0,1]
	v_pk_mul_f32 v[0:1], v[2:3], v[0:1]
	s_nop 0
	v_cvt_pk_bf16_f32 v7, v0, v1
	ds_write_b128 v204, v[4:7]
	ds_write_b128 v205, v[124:127] offset:55296
	v_lshl_add_u64 v[0:1], v[166:167], 0, s[8:9]
	global_load_dwordx4 v[24:27], v[0:1], off offset:16
	global_load_dwordx4 v[28:31], v[0:1], off
	global_load_dwordx4 v[12:15], v[0:1], off offset:80
	global_load_dwordx4 v[20:23], v[0:1], off offset:64
	global_load_dwordx4 v[4:7], v[0:1], off offset:144
	global_load_dwordx4 v[8:11], v[0:1], off offset:128
	global_load_dwordx4 v[16:19], v[0:1], off offset:208
	s_nop 0
	global_load_dwordx4 v[0:3], v[0:1], off offset:192
	s_ashr_i32 s7, s6, 31
	s_lshl_b64 s[8:9], s[6:7], 2
	s_add_u32 s8, s87, s8
	s_addc_u32 s9, s88, s9
	global_load_dword v229, v147, s[8:9]
	v_and_b32_e32 v35, 0xffff0000, v111
	v_and_b32_e32 v39, 0xffff0000, v109
	v_lshlrev_b32_e32 v132, 16, v97
	v_and_b32_e32 v133, 0xffff0000, v97
; __device__ __forceinline__ unsigned pk2(float lo, float hi) { f32x2_t v = {lo, hi}; bf16x2_t b = __builtin_convertvector(v, bf16x2_t); return __builtin_bit_cast(unsigned, b); }
; template <bool FUSED> __device__ __forceinline__ void attn_phase(const Args& a, LAS unsigned char* lds, int tid, int lane, int wave) {
;     ...
;             float ss = 0.f;
; #pragma unroll
;             for (int ks = 0; ks < 4; ++ks)
; #pragma unroll
;                 for (int e = 0; e < 4; ++e) { const float lo = bflo(qv[ks][e]), hi = bfhi(qv[ks][e]); ss += lo * lo + hi * hi; }
;             ss += __shfl_xor(ss, 32);
;             const float rq = 0.125f * LOG2E * __builtin_amdgcn_rsqf(ss * (1.f / 64.f) + 1e-6f);
; #pragma unroll
;             for (int ks = 0; ks < 4; ++ks) { const f32x4 g0 = *(const f32x4*)(a.qw + hd * 64 + 16 * ks + 8 * h), g1 = *(const f32x4*)(a.qw + hd * 64 + 16 * ks + 8 * h + 4); u32x4 wv;
;                 wv.x = pk2(bflo(qv[ks].x) * rq * g0.x, bfhi(qv[ks].x) * rq * g0.y); wv.y = pk2(bflo(qv[ks].y) * rq * g0.z, bfhi(qv[ks].y) * rq * g0.w);
;                 wv.z = pk2(bflo(qv[ks].z) * rq * g1.x, bfhi(qv[ks].z) * rq * g1.y); wv.w = pk2(bflo(qv[ks].w) * rq * g1.z, bfhi(qv[ks].w) * rq * g1.w);
;                 qf[ks] = __builtin_bit_cast(bf16x8, wv); }
;         }
;         const float mb = ((const float*)(a.ws + WS_RS))[hd];
;         __syncthreads();
;         const int un = u + gridDim.x;
;         if (un < NU) { const AUnit wn = attn_decode(un, HD0, NH); attn_issue(wn, Qb, Kb, Vb, tid, wave, lane, kv, vv); }
	v_lshlrev_b32_e32 v134, 16, v96
	v_and_b32_e32 v135, 0xffff0000, v96
	v_lshlrev_b32_e32 v50, 16, v110
	v_and_b32_e32 v37, 0xffff0000, v110
	v_mov_b32_e32 v36, v35
	v_and_b32_e32 v41, 0xffff0000, v108
	v_mov_b32_e32 v40, v39
	v_lshlrev_b32_e32 v130, 16, v98
	v_and_b32_e32 v131, 0xffff0000, v98
	v_pk_mul_f32 v[236:237], v[132:133], v[132:133]
	v_pk_mul_f32 v[238:239], v[134:135], v[134:135]
	v_lshlrev_b32_e32 v48, 16, v111
	v_mov_b32_e32 v49, v50
	v_pk_mul_f32 v[32:33], v[36:37], v[36:37]
	v_lshlrev_b32_e32 v34, 16, v108
	v_pk_mul_f32 v[42:43], v[40:41], v[40:41]
	v_lshlrev_b32_e32 v128, 16, v99
	v_and_b32_e32 v129, 0xffff0000, v99
	v_pk_mul_f32 v[234:235], v[130:131], v[130:131]
	v_add_f32_e32 v38, v236, v237
	v_add_f32_e32 v40, v238, v239
	v_pk_fma_f32 v[136:137], v[48:49], v[48:49], v[32:33]
	v_lshlrev_b32_e32 v32, 16, v109
	v_mov_b32_e32 v33, v34
	v_lshlrev_b32_e32 v58, 16, v100
	v_and_b32_e32 v59, 0xffff0000, v100
	v_pk_mul_f32 v[232:233], v[128:129], v[128:129]
	v_add_f32_e32 v38, v40, v38
	v_add_f32_e32 v40, v234, v235
	v_pk_fma_f32 v[138:139], v[32:33], v[32:33], v[42:43]
	v_lshlrev_b32_e32 v56, 16, v101
	v_and_b32_e32 v57, 0xffff0000, v101
	v_pk_mul_f32 v[230:231], v[58:59], v[58:59]
	v_add_f32_e32 v33, v232, v233
	v_add_f32_e32 v38, v40, v38
	v_and_b32_e32 v61, 0xffff0000, v107
	v_lshlrev_b32_e32 v54, 16, v102
	v_and_b32_e32 v55, 0xffff0000, v102
	v_pk_mul_f32 v[174:175], v[56:57], v[56:57]
	v_add_f32_e32 v33, v33, v38
	v_add_f32_e32 v38, v230, v231
	v_lshlrev_b32_e32 v36, 16, v106
	v_and_b32_e32 v63, 0xffff0000, v106
	v_mov_b32_e32 v62, v61
	v_lshlrev_b32_e32 v52, 16, v103
	v_and_b32_e32 v53, 0xffff0000, v103
	v_pk_mul_f32 v[172:173], v[54:55], v[54:55]
	v_add_f32_e32 v33, v38, v33
	v_add_f32_e32 v38, v174, v175
	v_lshlrev_b32_e32 v42, 16, v107
	v_mov_b32_e32 v43, v36
	v_pk_mul_f32 v[44:45], v[62:63], v[62:63]
	v_lshlrev_b32_e32 v46, 16, v104
	v_and_b32_e32 v47, 0xffff0000, v104
	v_pk_mul_f32 v[170:171], v[52:53], v[52:53]
	v_add_f32_e32 v33, v38, v33
	v_add_f32_e32 v38, v172, v173
	v_pk_fma_f32 v[140:141], v[42:43], v[42:43], v[44:45]
	v_lshlrev_b32_e32 v44, 16, v105
	v_and_b32_e32 v45, 0xffff0000, v105
	v_pk_mul_f32 v[168:169], v[46:47], v[46:47]
	v_add_f32_e32 v33, v38, v33
	v_add_f32_e32 v38, v170, v171
	v_pk_mul_f32 v[142:143], v[44:45], v[44:45]
	v_add_f32_e32 v33, v38, v33
	v_add_f32_e32 v38, v168, v169
	v_add_f32_e32 v33, v38, v33
	v_add_f32_e32 v38, v142, v143
	v_add_f32_e32 v33, v38, v33
	v_add_f32_e32 v33, v141, v33
	v_add_f32_e32 v33, v140, v33
	v_add_f32_e32 v33, v139, v33
	v_add_f32_e32 v33, v138, v33
	v_add_f32_e32 v33, v137, v33
	v_add_f32_e32 v33, v136, v33
	ds_bpermute_b32 v38, v151, v33
	s_add_i32 s64, s46, s54
	s_cmpk_lt_i32 s64, 0x800
	s_cselect_b64 s[44:45], -1, 0
	s_cmpk_gt_i32 s64, 0x7ff
	s_cselect_b64 s[42:43], -1, 0
	s_and_b64 vcc, exec, s[42:43]
	s_waitcnt lgkmcnt(0)
	s_barrier
	s_cbranch_vccnz .LBB0_404
; __device__ __forceinline__ unsigned pk2(float lo, float hi) { f32x2_t v = {lo, hi}; bf16x2_t b = __builtin_convertvector(v, bf16x2_t); return __builtin_bit_cast(unsigned, b); }
; template <bool FUSED> __device__ __forceinline__ void attn_phase(const Args& a, LAS unsigned char* lds, int tid, int lane, int wave) {
;     ...
;             for (int ks = 0; ks < 4; ++ks)
; #pragma unroll
;                 for (int e = 0; e < 4; ++e) { const float lo = bflo(qv[ks][e]), hi = bfhi(qv[ks][e]); ss += lo * lo + hi * hi; }
;             ss += __shfl_xor(ss, 32);
;             const float rq = 0.125f * LOG2E * __builtin_amdgcn_rsqf(ss * (1.f / 64.f) + 1e-6f);
; #pragma unroll
;             for (int ks = 0; ks < 4; ++ks) { const f32x4 g0 = *(const f32x4*)(a.qw + hd * 64 + 16 * ks + 8 * h), g1 = *(const f32x4*)(a.qw + hd * 64 + 16 * ks + 8 * h + 4); u32x4 wv;
;                 wv.x = pk2(bflo(qv[ks].x) * rq * g0.x, bfhi(qv[ks].x) * rq * g0.y); wv.y = pk2(bflo(qv[ks].y) * rq * g0.z, bfhi(qv[ks].y) * rq * g0.w);
;                 wv.z = pk2(bflo(qv[ks].z) * rq * g1.x, bfhi(qv[ks].z) * rq * g1.y); wv.w = pk2(bflo(qv[ks].w) * rq * g1.z, bfhi(qv[ks].w) * rq * g1.w);
;                 qf[ks] = __builtin_bit_cast(bf16x8, wv); }
;         }
;         const float mb = ((const float*)(a.ws + WS_RS))[hd];
;         __syncthreads();
;         const int un = u + gridDim.x;
;         if (un < NU) { const AUnit wn = attn_decode(un, HD0, NH); attn_issue(wn, Qb, Kb, Vb, tid, wave, lane, kv, vv); }
;         const float bsl = __builtin_amdgcn_exp2f(-(float)(slot + 1)) * (float)w.dil * LOG2E;
	s_ashr_i32 s8, s64, 5
	s_lshr_b32 s9, s8, 29
	s_add_i32 s9, s8, s9
	s_and_b32 s9, s9, -8
	s_sub_i32 s8, s8, s9
	s_ashr_i32 s10, s8, 2
	s_and_b32 s10, s10, -2
	s_lshr_b32 s11, 32, s10
	s_and_b32 s7, s64, 31
	s_lshr_b32 s12, 0x2000, s10
	s_sub_i32 s10, 5, s10
	s_add_i32 s11, s11, -1
	s_lshr_b32 s10, s7, s10
	s_and_b32 s7, s11, s7
	s_lshl_b32 s7, s7, 8
	v_add_u32_e32 v40, s7, v153
	s_add_i32 s11, s12, -1
	v_min_i32_e32 v43, s11, v40
	v_cmp_lt_i32_e32 vcc, -1, v40
	s_mul_i32 s10, s10, s12
	s_ashr_i32 s9, s64, 31
	v_cndmask_b32_e32 v40, 0, v43, vcc
	v_add_u32_e32 v64, s10, v40
	v_add_u32_e32 v40, s7, v155
	v_min_i32_e32 v43, s11, v40
	v_cmp_lt_i32_e32 vcc, -1, v40
	s_lshr_b32 s9, s9, 24
	s_add_i32 s9, s64, s9
	v_cndmask_b32_e32 v40, 0, v43, vcc
	v_add_u32_e32 v72, s10, v40
	v_add_u32_e32 v40, s7, v159
	v_min_i32_e32 v43, s11, v40
	v_cmp_lt_i32_e32 vcc, -1, v40
	s_ashr_i32 s9, s9, 8
	s_mul_i32 s9, s9, 24
	v_cndmask_b32_e32 v40, 0, v43, vcc
	v_add_u32_e32 v80, s10, v40
	v_add_u32_e32 v40, s7, v161
	v_min_i32_e32 v43, s11, v40
	v_cmp_lt_i32_e32 vcc, -1, v40
	s_add_i32 s8, s9, s8
	s_ashr_i32 s9, s8, 31
	v_cndmask_b32_e32 v40, 0, v43, vcc
	v_add_u32_e32 v88, s10, v40
	v_add_u32_e32 v40, s7, v163
	v_min_i32_e32 v43, s11, v40
	v_cmp_lt_i32_e32 vcc, -1, v40
	v_ashrrev_i32_e32 v65, 31, v64
	v_ashrrev_i32_e32 v73, 31, v72
	v_cndmask_b32_e32 v40, 0, v43, vcc
	v_add_u32_e32 v112, s10, v40
	v_add_u32_e32 v40, s7, v176
	v_min_i32_e32 v43, s11, v40
	v_cmp_lt_i32_e32 vcc, -1, v40
	v_ashrrev_i32_e32 v81, 31, v80
	v_ashrrev_i32_e32 v89, 31, v88
	v_cndmask_b32_e32 v40, 0, v43, vcc
	v_add_u32_e32 v120, s10, v40
	v_ashrrev_i32_e32 v113, 31, v112
	v_ashrrev_i32_e32 v121, 31, v120
	s_lshl_b64 s[8:9], s[8:9], 19
	v_lshlrev_b64 v[64:65], 6, v[64:65]
	v_lshlrev_b64 v[72:73], 6, v[72:73]
	v_lshlrev_b64 v[80:81], 6, v[80:81]
	v_lshlrev_b64 v[88:89], 6, v[88:89]
	v_lshlrev_b64 v[112:113], 6, v[112:113]
	v_lshlrev_b64 v[120:121], 6, v[120:121]
	v_lshl_add_u64 v[64:65], v[64:65], 0, s[8:9]
	v_lshl_add_u64 v[72:73], v[72:73], 0, s[8:9]
	v_lshl_add_u64 v[80:81], v[80:81], 0, s[8:9]
	v_lshl_add_u64 v[88:89], v[88:89], 0, s[8:9]
	v_lshl_add_u64 v[112:113], v[112:113], 0, s[8:9]
	v_lshl_add_u64 v[120:121], v[120:121], 0, s[8:9]
	v_or_b32_e32 v64, v64, v144
	v_or_b32_e32 v72, v72, v144
	v_or_b32_e32 v80, v80, v144
	v_or_b32_e32 v88, v88, v144
	v_or_b32_e32 v112, v112, v144
	v_or_b32_e32 v120, v120, v144
	v_lshlrev_b64 v[64:65], 1, v[64:65]
	v_lshlrev_b64 v[72:73], 1, v[72:73]
	v_lshlrev_b64 v[80:81], 1, v[80:81]
	v_lshlrev_b64 v[88:89], 1, v[88:89]
	v_lshlrev_b64 v[112:113], 1, v[112:113]
	v_lshlrev_b64 v[120:121], 1, v[120:121]
	v_lshl_add_u64 v[66:67], s[58:59], 0, v[64:65]
	v_lshl_add_u64 v[68:69], s[60:61], 0, v[64:65]
	v_lshl_add_u64 v[74:75], s[58:59], 0, v[72:73]
	v_lshl_add_u64 v[76:77], s[60:61], 0, v[72:73]
	v_lshl_add_u64 v[82:83], s[58:59], 0, v[80:81]
	v_lshl_add_u64 v[84:85], s[60:61], 0, v[80:81]
	v_lshl_add_u64 v[90:91], s[58:59], 0, v[88:89]
	v_lshl_add_u64 v[92:93], s[60:61], 0, v[88:89]
	v_lshl_add_u64 v[114:115], s[58:59], 0, v[112:113]
	v_lshl_add_u64 v[116:117], s[60:61], 0, v[112:113]
	v_lshl_add_u64 v[122:123], s[58:59], 0, v[120:121]
	v_lshl_add_u64 v[124:125], s[60:61], 0, v[120:121]
	global_load_dwordx4 v[64:67], v[66:67], off
	s_nop 0
	global_load_dwordx4 v[68:71], v[68:69], off
	s_nop 0
	global_load_dwordx4 v[72:75], v[74:75], off
	s_nop 0
	global_load_dwordx4 v[76:79], v[76:77], off
	s_nop 0
	global_load_dwordx4 v[80:83], v[82:83], off
	s_nop 0
	global_load_dwordx4 v[84:87], v[84:85], off
	s_nop 0
	global_load_dwordx4 v[88:91], v[90:91], off
	s_nop 0
	global_load_dwordx4 v[92:95], v[92:93], off
	s_nop 0
	global_load_dwordx4 v[112:115], v[114:115], off
	s_nop 0
	global_load_dwordx4 v[116:119], v[116:117], off
	s_nop 0
	global_load_dwordx4 v[120:123], v[122:123], off
	s_nop 0
	global_load_dwordx4 v[124:127], v[124:125], off
	v_add_f32_e32 v33, v33, v38
	v_fmamk_f32 v33, v33, 0x3c800000, v186
	v_rsq_f32_e32 v38, v33
	v_mov_b32_e32 v33, v39
	v_mov_b32_e32 v51, v37
	v_mov_b32_e32 v37, v63
	v_mul_f32_e32 v60, 0x3e38aa3b, v38
	v_pk_mul_f32 v[38:39], v[60:61], v[134:135] op_sel_hi:[0,1]
	s_waitcnt vmcnt(19)
	v_pk_mul_f32 v[28:29], v[28:29], v[38:39]
	v_mov_b32_e32 v43, v61
	v_cvt_pk_bf16_f32 v136, v28, v29
	v_pk_mul_f32 v[28:29], v[60:61], v[132:133] op_sel_hi:[0,1]
	v_pk_mul_f32 v[28:29], v[30:31], v[28:29]
	v_mov_b32_e32 v49, v35
	v_cvt_pk_bf16_f32 v137, v28, v29
	v_pk_mul_f32 v[28:29], v[60:61], v[130:131] op_sel_hi:[0,1]
	v_pk_mul_f32 v[24:25], v[24:25], v[28:29]
	v_mov_b32_e32 v28, v177
	v_cvt_pk_bf16_f32 v138, v24, v25
	v_pk_mul_f32 v[24:25], v[60:61], v[128:129] op_sel_hi:[0,1]
	v_pk_mul_f32 v[24:25], v[26:27], v[24:25]
	v_mov_b32_e32 v35, v41
	v_cvt_pk_bf16_f32 v139, v24, v25
	v_pk_mul_f32 v[24:25], v[60:61], v[58:59] op_sel_hi:[0,1]
	s_waitcnt vmcnt(17)
	v_pk_mul_f32 v[20:21], v[20:21], v[24:25]
	ds_read_b128 v[24:27], v206 offset:32
	v_cvt_pk_bf16_f32 v132, v20, v21
	v_pk_mul_f32 v[20:21], v[60:61], v[56:57] op_sel_hi:[0,1]
	v_pk_mul_f32 v[20:21], v[22:23], v[20:21]
	s_and_b32 s65, s6, 7
	v_cvt_pk_bf16_f32 v133, v20, v21
	v_pk_mul_f32 v[20:21], v[60:61], v[54:55] op_sel_hi:[0,1]
	v_pk_mul_f32 v[12:13], v[12:13], v[20:21]
	ds_read_b128 v[20:23], v206
	v_cvt_pk_bf16_f32 v134, v12, v13
	v_pk_mul_f32 v[12:13], v[60:61], v[52:53] op_sel_hi:[0,1]
	v_pk_mul_f32 v[12:13], v[14:15], v[12:13]
	s_ashr_i32 s7, s6, 2
	v_cvt_pk_bf16_f32 v135, v12, v13
	v_pk_mul_f32 v[12:13], v[60:61], v[46:47] op_sel_hi:[0,1]
	s_waitcnt vmcnt(15)
	v_pk_mul_f32 v[8:9], v[8:9], v[12:13]
	s_add_i32 s6, s65, 1
	v_cvt_pk_bf16_f32 v128, v8, v9
	v_pk_mul_f32 v[8:9], v[60:61], v[44:45] op_sel_hi:[0,1]
	v_pk_mul_f32 v[8:9], v[10:11], v[8:9]
	s_and_b32 s7, s7, -2
	v_cvt_pk_bf16_f32 v129, v8, v9
	v_pk_mul_f32 v[8:9], v[60:61], v[36:37] op_sel_hi:[0,1]
	v_pk_mul_f32 v[4:5], v[4:5], v[8:9]
	s_lshr_b32 s8, 32, s7
	v_cvt_pk_bf16_f32 v130, v4, v5
	v_pk_mul_f32 v[4:5], v[60:61], v[42:43] op_sel_hi:[0,1]
	v_pk_mul_f32 v[4:5], v[6:7], v[4:5]
	s_add_i32 s8, s8, -1
	v_cvt_pk_bf16_f32 v131, v4, v5
	v_pk_mul_f32 v[4:5], v[60:61], v[34:35] op_sel_hi:[0,1]
	s_waitcnt vmcnt(13)
	v_pk_mul_f32 v[0:1], v[4:5], v[0:1]
	s_and_b32 s8, s46, s8
	v_cvt_pk_bf16_f32 v140, v0, v1
	v_pk_mul_f32 v[0:1], v[60:61], v[32:33] op_sel_hi:[0,1]
	s_waitcnt vmcnt(12)
	s_branch .Lattn2_join

; #define LAS __attribute__((address_space(3)))
; __device__ __forceinline__ float attn_tile_exp(f32x16& st, int j, float tlf, float bsl, float rlo, float rhi) {
;     float sum = 0.f;
; #pragma unroll
;     for (int i = 0; i < 16; ++i) { const float tmp = (float)(32 * j - 64 + (i & 3) + 8 * (i >> 2)) + tlf;
;         float arg = __builtin_fmaf(-bsl, __builtin_fabsf(tmp), st[i]);
;         arg = (tmp >= rlo && tmp <= rhi) ? arg : -1.0e30f;
;         const float pe = __builtin_amdgcn_exp2f(arg); st[i] = pe; sum += pe; }
;     return sum;
; template <bool FUSED> __device__ __forceinline__ void attn_phase(const Args& a, LAS unsigned char* lds, int tid, int lane, int wave) {
;     ...
;         const float bsl = __builtin_amdgcn_exp2f(-(float)(slot + 1)) * (float)w.dil * LOG2E;
;         int tl = 4 * h - l31; asm volatile("" : "+v"(tl));
;         const float tlf = (float)tl;
;         const int lo_i = -iq > -64 ? -iq : -64, hi_i = (L - 1 - iq) < 64 ? (L - 1 - iq) : 64;
;         const float rlo = (float)lo_i, rhi = (float)hi_i;
;         const int wq0 = i0 + 32 * wave;
;         const bool edge = (wq0 < 64) || (wq0 + 32 > L - 64);
;         float sum = 0.f;
;         f32x16 o[2]; o[0] = f32x16{}; o[1] = f32x16{};
; #pragma unroll
;         for (int j = 0; j < 5; ++j) {
;             f32x16 st;
; #pragma unroll
;             for (int i = 0; i < 16; ++i) st[i] = -mb;
;             LAS const unsigned char* kp = lds + (32 * wave + 32 * j + l31) * KP + 16 * h;
; #pragma unroll
;             for (int ks = 0; ks < 4; ++ks) { const bf16x8 kf = *(LAS const bf16x8*)(kp + 32 * ks); st = __builtin_amdgcn_mfma_f32_32x32x16_bf16(kf, qf[ks], st, 0, 0, 0); }
;             sum += attn_tile_exp(st, j, tlf, bsl, rlo, rhi);
.Lattn2_join:
	v_xor_b32_e32 v32, 0x80000000, v229
	v_pk_mul_f32 v[0:1], v[0:1], v[2:3]
	v_mov_b32_e32 v33, v32
	v_mov_b32_e32 v34, v32
	v_mov_b32_e32 v35, v32
	v_mov_b32_e32 v36, v32
	v_mov_b32_e32 v37, v32
	v_mov_b32_e32 v38, v32
	v_mov_b32_e32 v39, v32
	v_mov_b32_e32 v40, v32
	v_mov_b32_e32 v41, v32
	v_mov_b32_e32 v42, v32
	v_mov_b32_e32 v43, v32
	v_mov_b32_e32 v44, v32
	v_mov_b32_e32 v45, v32
	v_mov_b32_e32 v46, v32
	v_mov_b32_e32 v47, v32
	v_cvt_pk_bf16_f32 v141, v0, v1
	s_and_b32 s8, s8, 31
	s_waitcnt lgkmcnt(0)
	v_mfma_f32_32x32x16_bf16 v[0:15], v[20:23], v[136:139], v[32:47]
	v_mul_f32_e64 v20, v60, v50
	v_mul_f32_e64 v21, v60, v51
	v_mul_f32_e64 v16, v20, v16
	v_mul_f32_e64 v17, v21, v17
	ds_read_b128 v[20:23], v206 offset:64
	v_cvt_pk_bf16_f32 v142, v16, v17
	v_cvt_f32_ubyte0_e32 v16, s6
	v_exp_f32_e64 v29, -v16
	v_pk_mul_f32 v[16:17], v[60:61], v[48:49] op_sel_hi:[0,1]
	v_mfma_f32_32x32x16_bf16 v[0:15], v[24:27], v[132:135], v[0:15]
	v_mul_f32_e64 v16, v16, v18
	v_mul_f32_e64 v17, v17, v19
	s_lshl_b32 s66, s8, 8
	v_cvt_pk_bf16_f32 v143, v16, v17
	ds_read_b128 v[16:19], v206 offset:96
	s_add_i32 s66, s66, s48
	s_lshl_b32 s9, 1, s7
	s_lshr_b32 s7, 0x2000, s7
	s_waitcnt lgkmcnt(1)
	v_mfma_f32_32x32x16_bf16 v[0:15], v[20:23], v[128:131], v[0:15]
	v_or_b32_e32 v62, s66, v145
	v_sub_u32_e32 v20, 0, v62
	v_xad_u32 v21, v62, -1, s7
	v_cvt_f32_u32_e32 v24, s9
	v_cvt_f32_i32_e32 v171, v28
	v_max_i32_e32 v20, 0xffffffc0, v20
	v_min_i32_e32 v21, 64, v21
	s_waitcnt lgkmcnt(0)
	v_mfma_f32_32x32x16_bf16 v[0:15], v[16:19], v[140:143], v[0:15]
	v_cvt_f32_i32_e32 v168, v20
	v_cvt_f32_i32_e32 v169, v21
	v_mul_f32_e32 v24, v29, v24
	v_add_f32_e32 v16, 0xc2800000, v171
	v_mul_f32_e32 v170, 0xbfb8aa3b, v24
	v_cmp_nge_f32_e32 vcc, v16, v168
	v_cmp_nle_f32_e64 s[6:7], v16, v169
	s_nop 4
	v_fma_f32 v0, v170, |v16|, v0
	s_or_b64 vcc, vcc, s[6:7]
	v_add_f32_e32 v17, 0xc27c0000, v171
	v_cndmask_b32_e32 v0, v0, v228, vcc
	v_cmp_nge_f32_e32 vcc, v17, v168
	v_cmp_nle_f32_e64 s[6:7], v17, v169
	v_fma_f32 v1, v170, |v17|, v1
	s_or_b64 vcc, vcc, s[6:7]
	v_cndmask_b32_e32 v1, v1, v228, vcc
	v_exp_f32_e32 v17, v1
	v_add_f32_e32 v1, 0xc2780000, v171
	v_cmp_nge_f32_e32 vcc, v1, v168
	v_cmp_nle_f32_e64 s[6:7], v1, v169
	v_fma_f32 v2, v170, |v1|, v2
	s_or_b64 vcc, vcc, s[6:7]
	v_cndmask_b32_e32 v1, v2, v228, vcc
	v_exp_f32_e32 v18, v1
	v_add_f32_e32 v1, 0xc2740000, v171
	v_cmp_nge_f32_e32 vcc, v1, v168
	v_cmp_nle_f32_e64 s[6:7], v1, v169
	v_fma_f32 v2, v170, |v1|, v3
	s_or_b64 vcc, vcc, s[6:7]
	v_cndmask_b32_e32 v1, v2, v228, vcc
	v_exp_f32_e32 v19, v1
	v_add_f32_e32 v1, 0xc2600000, v171
	v_cmp_nge_f32_e32 vcc, v1, v168
	v_cmp_nle_f32_e64 s[6:7], v1, v169
	v_fma_f32 v2, v170, |v1|, v4
	s_or_b64 vcc, vcc, s[6:7]
	v_cndmask_b32_e32 v1, v2, v228, vcc
	v_exp_f32_e32 v20, v1
	v_add_f32_e32 v1, 0xc25c0000, v171
	v_cmp_nge_f32_e32 vcc, v1, v168
	v_cmp_nle_f32_e64 s[6:7], v1, v169
	v_fma_f32 v2, v170, |v1|, v5
	s_or_b64 vcc, vcc, s[6:7]
	v_cndmask_b32_e32 v1, v2, v228, vcc
	v_exp_f32_e32 v21, v1
	v_add_f32_e32 v1, 0xc2580000, v171
	v_cmp_nge_f32_e32 vcc, v1, v168
	v_cmp_nle_f32_e64 s[6:7], v1, v169
	v_fma_f32 v2, v170, |v1|, v6
	s_or_b64 vcc, vcc, s[6:7]
	v_cndmask_b32_e32 v1, v2, v228, vcc
	v_exp_f32_e32 v16, v0
	v_exp_f32_e32 v22, v1
	v_add_f32_e32 v1, 0xc2540000, v171
	v_cmp_nge_f32_e32 vcc, v1, v168
	v_cmp_nle_f32_e64 s[6:7], v1, v169
	v_fma_f32 v2, v170, |v1|, v7
	s_or_b64 vcc, vcc, s[6:7]
	v_cndmask_b32_e32 v1, v2, v228, vcc
	v_add_f32_e32 v0, 0, v16
	v_exp_f32_e32 v7, v1
	v_add_f32_e32 v1, 0xc2400000, v171
	v_add_f32_e32 v0, v17, v0
	v_cmp_nge_f32_e32 vcc, v1, v168
	v_cmp_nle_f32_e64 s[6:7], v1, v169
	v_add_f32_e32 v0, v18, v0
	v_fma_f32 v2, v170, |v1|, v8
	s_or_b64 vcc, vcc, s[6:7]
	v_add_f32_e32 v0, v19, v0
	v_cndmask_b32_e32 v1, v2, v228, vcc
	v_add_f32_e32 v0, v20, v0
	v_exp_f32_e32 v52, v1
	v_add_f32_e32 v0, v21, v0
	v_add_f32_e32 v0, v22, v0
	v_add_f32_e32 v0, v7, v0
	v_add_f32_e32 v60, v52, v0
	v_add_f32_e32 v0, 0xc23c0000, v171
	v_cmp_nge_f32_e32 vcc, v0, v168
	v_cmp_nle_f32_e64 s[6:7], v0, v169
	v_fma_f32 v1, v170, |v0|, v9
	s_or_b64 vcc, vcc, s[6:7]
	v_cndmask_b32_e32 v0, v1, v228, vcc
	v_exp_f32_e32 v61, v0
	v_add_f32_e32 v0, 0xc2380000, v171
	v_cmp_nge_f32_e32 vcc, v0, v168
	v_cmp_nle_f32_e64 s[6:7], v0, v169
	v_fma_f32 v1, v170, |v0|, v10
	s_or_b64 vcc, vcc, s[6:7]
	v_cndmask_b32_e32 v0, v1, v228, vcc
	v_exp_f32_e32 v62, v0
	v_add_f32_e32 v0, 0xc2340000, v171
	v_cmp_nge_f32_e32 vcc, v0, v168
	v_cmp_nle_f32_e64 s[6:7], v0, v169
	v_fma_f32 v1, v170, |v0|, v11
	s_or_b64 vcc, vcc, s[6:7]
	v_cndmask_b32_e32 v0, v1, v228, vcc
	v_exp_f32_e32 v63, v0
	v_add_f32_e32 v0, 0xc2200000, v171
	v_cmp_nge_f32_e32 vcc, v0, v168
	v_cmp_nle_f32_e64 s[6:7], v0, v169
	v_fma_f32 v1, v170, |v0|, v12
	s_or_b64 vcc, vcc, s[6:7]
	v_cndmask_b32_e32 v0, v1, v228, vcc
	v_exp_f32_e32 v172, v0
	v_add_f32_e32 v0, 0xc21c0000, v171
	v_cmp_nge_f32_e32 vcc, v0, v168
	v_cmp_nle_f32_e64 s[6:7], v0, v169
	v_fma_f32 v1, v170, |v0|, v13
	s_or_b64 vcc, vcc, s[6:7]
	v_cndmask_b32_e32 v0, v1, v228, vcc
	v_exp_f32_e32 v173, v0
	v_add_f32_e32 v0, 0xc2180000, v171
	v_cmp_nge_f32_e32 vcc, v0, v168
	v_cmp_nle_f32_e64 s[6:7], v0, v169
	v_fma_f32 v1, v170, |v0|, v14
	s_or_b64 vcc, vcc, s[6:7]
	v_cndmask_b32_e32 v4, v1, v228, vcc
	ds_read_b64_tr_b16 v[0:1], v207 offset:55296
	ds_read_b64_tr_b16 v[2:3], v207 offset:56832
	ds_read_b64_tr_b16 v[10:11], v207 offset:56896
	ds_read_b64_tr_b16 v[8:9], v207 offset:55360
	v_add_f32_e32 v12, 0xc2140000, v171
	v_exp_f32_e32 v174, v4
	v_cvt_pk_bf16_f32 v4, v16, v17
	v_cvt_pk_bf16_f32 v5, v18, v19
	v_cvt_pk_bf16_f32 v6, v20, v21
	v_cvt_pk_bf16_f32 v7, v22, v7
	v_cmp_nge_f32_e32 vcc, v12, v168
	v_cmp_nle_f32_e64 s[6:7], v12, v169
	s_waitcnt lgkmcnt(2)
; #define LAS __attribute__((address_space(3)))
; __device__ __forceinline__ unsigned pk2(float lo, float hi) { f32x2_t v = {lo, hi}; bf16x2_t b = __builtin_convertvector(v, bf16x2_t); return __builtin_bit_cast(unsigned, b); }
; __device__ __forceinline__ s16x4 trrd(LAS const unsigned char* p) { return __builtin_bit_cast(s16x4, __builtin_amdgcn_ds_read_tr16_b64_v4i16((LAS v4i16_t*)p)); }
; __device__ __forceinline__ float attn_tile_exp(f32x16& st, int j, float tlf, float bsl, float rlo, float rhi) {
;     float sum = 0.f;
; #pragma unroll
;     for (int i = 0; i < 16; ++i) { const float tmp = (float)(32 * j - 64 + (i & 3) + 8 * (i >> 2)) + tlf;
;         float arg = __builtin_fmaf(-bsl, __builtin_fabsf(tmp), st[i]);
;         arg = (tmp >= rlo && tmp <= rhi) ? arg : -1.0e30f;
;         const float pe = __builtin_amdgcn_exp2f(arg); st[i] = pe; sum += pe; }
;     return sum;
; template <bool FUSED> __device__ __forceinline__ void attn_phase(const Args& a, LAS unsigned char* lds, int tid, int lane, int wave) {
;     ...
;         for (int j = 0; j < 5; ++j) {
;             f32x16 st;
; #pragma unroll
;             for (int i = 0; i < 16; ++i) st[i] = -mb;
;             LAS const unsigned char* kp = lds + (32 * wave + 32 * j + l31) * KP + 16 * h;
; #pragma unroll
;             for (int ks = 0; ks < 4; ++ks) { const bf16x8 kf = *(LAS const bf16x8*)(kp + 32 * ks); st = __builtin_amdgcn_mfma_f32_32x32x16_bf16(kf, qf[ks], st, 0, 0, 0); }
;             sum += attn_tile_exp(st, j, tlf, bsl, rlo, rhi);
; #pragma unroll
;             for (int s2 = 0; s2 < 2; ++s2) { u32x4 pw; pw.x = pk2(st[8 * s2 + 0], st[8 * s2 + 1]); pw.y = pk2(st[8 * s2 + 2], st[8 * s2 + 3]); pw.z = pk2(st[8 * s2 + 4], st[8 * s2 + 5]); pw.w = pk2(st[8 * s2 + 6], st[8 * s2 + 7]);
;                 const bf16x8 pf = __builtin_bit_cast(bf16x8, pw);
;                 LAS const unsigned char* vp = lds + LDS_VOFF + (32 * wave + 32 * j + 16 * s2 + 4 * h + q) * VP + 32 * blk + 8 * p;
; #pragma unroll
;                 for (int dt = 0; dt < 2; ++dt) { const s16x4 lo = trrd(vp + dt * 64), hi = trrd(vp + 8 * VP + dt * 64);
;                     const bf16x8 vf = __builtin_shufflevector(lo, hi, 0, 1, 2, 3, 4, 5, 6, 7);
;                     o[dt] = __builtin_amdgcn_mfma_f32_32x32x16_bf16(vf, pf, o[dt], 0, 0, 0); } }
;             __builtin_amdgcn_sched_barrier(0);
;         }
	v_mfma_f32_32x32x16_bf16 v[16:31], v[0:3], v[4:7], 0
	v_fma_f32 v0, v170, |v12|, v15
	s_or_b64 vcc, vcc, s[6:7]
	v_cndmask_b32_e32 v53, v0, v228, vcc
	ds_read_b64_tr_b16 v[48:49], v207 offset:58368
	ds_read_b64_tr_b16 v[50:51], v207 offset:59904
	v_exp_f32_e32 v175, v53
	ds_read_b64_tr_b16 v[58:59], v207 offset:59968
	ds_read_b64_tr_b16 v[56:57], v207 offset:58432
	v_cvt_pk_bf16_f32 v52, v52, v61
	s_waitcnt lgkmcnt(4)
	v_mfma_f32_32x32x16_bf16 v[0:15], v[8:11], v[4:7], 0
	v_cvt_pk_bf16_f32 v53, v62, v63
	v_cvt_pk_bf16_f32 v54, v172, v173
	v_cvt_pk_bf16_f32 v55, v174, v175
	s_waitcnt lgkmcnt(2)
	s_nop 0
	v_mfma_f32_32x32x16_bf16 v[16:31], v[48:51], v[52:55], v[16:31]
	v_add_f32_e32 v48, v61, v60
	v_add_f32_e32 v48, v62, v48
	v_add_f32_e32 v48, v63, v48
	v_add_f32_e32 v48, v172, v48
	v_add_f32_e32 v48, v173, v48
	v_add_f32_e32 v48, v174, v48
	v_add_f32_e32 v48, v175, v48
	s_waitcnt lgkmcnt(0)
	v_mfma_f32_32x32x16_bf16 v[0:15], v[56:59], v[52:55], v[0:15]
	v_add_f32_e32 v238, 0, v48
	ds_read_b128 v[172:175], v208
	ds_read_b128 v[230:233], v208 offset:32
	v_add_f32_e32 v239, 0xc2000000, v171
	v_add_f32_e32 v240, 0xc1f80000, v171
	v_cmp_nge_f32_e32 vcc, v239, v168
	s_waitcnt lgkmcnt(1)
	v_mfma_f32_32x32x16_bf16 v[48:63], v[172:175], v[136:139], v[32:47]
	ds_read_b128 v[172:175], v208 offset:64
	ds_read_b128 v[234:237], v208 offset:96
	v_cmp_nle_f32_e64 s[6:7], v239, v169
	v_add_f32_e32 v241, 0xc1f00000, v171
	v_cmp_nge_f32_e64 s[8:9], v240, v168
	v_cmp_nle_f32_e64 s[10:11], v240, v169
	s_or_b64 vcc, vcc, s[6:7]
	v_add_f32_e32 v242, 0xc1e80000, v171
	s_waitcnt lgkmcnt(2)
	v_mfma_f32_32x32x16_bf16 v[48:63], v[230:233], v[132:135], v[48:63]
	v_cmp_nge_f32_e64 s[12:13], v241, v168
	v_cmp_nle_f32_e64 s[14:15], v241, v169
	v_add_f32_e32 v230, 0xc1c00000, v171
	v_cmp_nge_f32_e64 s[16:17], v242, v168
	v_cmp_nle_f32_e64 s[20:21], v242, v169
	v_add_f32_e32 v231, 0xc1b80000, v171
	v_cmp_nge_f32_e64 s[22:23], v230, v168
	s_waitcnt lgkmcnt(1)
	v_mfma_f32_32x32x16_bf16 v[48:63], v[172:175], v[128:131], v[48:63]
	v_cmp_nle_f32_e64 s[24:25], v230, v169
	v_cmp_nge_f32_e64 s[26:27], v231, v168
	v_cmp_nle_f32_e64 s[28:29], v231, v169
	s_waitcnt lgkmcnt(0)
	v_mfma_f32_32x32x16_bf16 v[48:63], v[234:237], v[140:143], v[48:63]
	s_nop 11
	v_fma_f32 v48, v170, |v239|, v48
	v_fma_f32 v49, v170, |v240|, v49
	v_cndmask_b32_e32 v48, v48, v228, vcc
	s_or_b64 vcc, s[8:9], s[10:11]
	v_fma_f32 v50, v170, |v241|, v50
	v_cndmask_b32_e32 v49, v49, v228, vcc
	s_or_b64 vcc, s[12:13], s[14:15]
	v_fma_f32 v51, v170, |v242|, v51
	v_cndmask_b32_e32 v50, v50, v228, vcc
	s_or_b64 vcc, s[16:17], s[20:21]
	v_fma_f32 v52, v170, |v230|, v52
	v_cndmask_b32_e32 v51, v51, v228, vcc
	s_or_b64 vcc, s[22:23], s[24:25]
	v_fma_f32 v53, v170, |v231|, v53
	v_cndmask_b32_e32 v52, v52, v228, vcc
	s_or_b64 vcc, s[26:27], s[28:29]
	v_exp_f32_e32 v173, v49
	v_cndmask_b32_e32 v49, v53, v228, vcc
	v_exp_f32_e32 v231, v49
	v_add_f32_e32 v49, 0xc1b00000, v171
	v_cmp_nge_f32_e32 vcc, v49, v168
	v_cmp_nle_f32_e64 s[6:7], v49, v169
	v_exp_f32_e32 v174, v50
	v_fma_f32 v50, v170, |v49|, v54
	s_or_b64 vcc, vcc, s[6:7]
	v_cndmask_b32_e32 v49, v50, v228, vcc
	v_exp_f32_e32 v172, v48
	v_exp_f32_e32 v232, v49
	v_add_f32_e32 v49, 0xc1a80000, v171
	v_cmp_nge_f32_e32 vcc, v49, v168
	v_cmp_nle_f32_e64 s[6:7], v49, v169
	v_fma_f32 v50, v170, |v49|, v55
	s_or_b64 vcc, vcc, s[6:7]
	v_exp_f32_e32 v175, v51
	v_cndmask_b32_e32 v49, v50, v228, vcc
	v_exp_f32_e32 v230, v52
	v_add_f32_e32 v48, 0, v172
	v_exp_f32_e32 v55, v49
	v_add_f32_e32 v49, 0xc1800000, v171
	v_add_f32_e32 v48, v173, v48
	v_cmp_nge_f32_e32 vcc, v49, v168
	v_cmp_nle_f32_e64 s[6:7], v49, v169
	v_add_f32_e32 v48, v174, v48
	v_fma_f32 v50, v170, |v49|, v56
	s_or_b64 vcc, vcc, s[6:7]
	v_add_f32_e32 v48, v175, v48
	v_cndmask_b32_e32 v49, v50, v228, vcc
	v_add_f32_e32 v48, v230, v48
	v_exp_f32_e32 v233, v49
	v_add_f32_e32 v48, v231, v48
	v_add_f32_e32 v48, v232, v48
	v_add_f32_e32 v48, v55, v48
	v_add_f32_e32 v234, v233, v48
	v_add_f32_e32 v48, 0xc1700000, v171
	v_cmp_nge_f32_e32 vcc, v48, v168
	v_cmp_nle_f32_e64 s[6:7], v48, v169
	v_fma_f32 v49, v170, |v48|, v57
	s_or_b64 vcc, vcc, s[6:7]
	v_cndmask_b32_e32 v48, v49, v228, vcc
	v_exp_f32_e32 v235, v48
	v_add_f32_e32 v48, 0xc1600000, v171
	v_cmp_nge_f32_e32 vcc, v48, v168
	v_cmp_nle_f32_e64 s[6:7], v48, v169
	v_fma_f32 v49, v170, |v48|, v58
	s_or_b64 vcc, vcc, s[6:7]
	v_cndmask_b32_e32 v48, v49, v228, vcc
	v_exp_f32_e32 v236, v48
	v_add_f32_e32 v48, 0xc1500000, v171
	v_cmp_nge_f32_e32 vcc, v48, v168
	v_cmp_nle_f32_e64 s[6:7], v48, v169
	v_fma_f32 v49, v170, |v48|, v59
	s_or_b64 vcc, vcc, s[6:7]
	v_cndmask_b32_e32 v48, v49, v228, vcc
	v_exp_f32_e32 v237, v48
	v_add_f32_e32 v48, 0xc1000000, v171
	v_cmp_nge_f32_e32 vcc, v48, v168
	v_cmp_nle_f32_e64 s[6:7], v48, v169
	v_fma_f32 v49, v170, |v48|, v60
	s_or_b64 vcc, vcc, s[6:7]
	v_cndmask_b32_e32 v48, v49, v228, vcc
	v_exp_f32_e32 v60, v48
	v_add_f32_e32 v48, 0xc0e00000, v171
	v_cmp_nge_f32_e32 vcc, v48, v168
	v_cmp_nle_f32_e64 s[6:7], v48, v169
	v_fma_f32 v49, v170, |v48|, v61
	s_or_b64 vcc, vcc, s[6:7]
	v_cndmask_b32_e32 v48, v49, v228, vcc
	v_exp_f32_e32 v61, v48
	v_add_f32_e32 v48, 0xc0c00000, v171
	v_cmp_nge_f32_e32 vcc, v48, v168
	v_cmp_nle_f32_e64 s[6:7], v48, v169
	v_fma_f32 v49, v170, |v48|, v62
	s_or_b64 vcc, vcc, s[6:7]
	v_cndmask_b32_e32 v52, v49, v228, vcc
	ds_read_b64_tr_b16 v[48:49], v209 offset:55296
	ds_read_b64_tr_b16 v[50:51], v209 offset:56832
	ds_read_b64_tr_b16 v[58:59], v209 offset:56896
	ds_read_b64_tr_b16 v[56:57], v209 offset:55360
	v_exp_f32_e32 v62, v52
	v_add_f32_e32 v239, 0xc0a00000, v171
	v_cvt_pk_bf16_f32 v52, v172, v173
	v_cvt_pk_bf16_f32 v53, v174, v175
	v_cvt_pk_bf16_f32 v54, v230, v231
	v_cvt_pk_bf16_f32 v55, v232, v55
	v_cmp_nge_f32_e32 vcc, v239, v168
	v_cmp_nle_f32_e64 s[6:7], v239, v169
	s_waitcnt lgkmcnt(2)
; #define LAS __attribute__((address_space(3)))
; __device__ __forceinline__ unsigned pk2(float lo, float hi) { f32x2_t v = {lo, hi}; bf16x2_t b = __builtin_convertvector(v, bf16x2_t); return __builtin_bit_cast(unsigned, b); }
; __device__ __forceinline__ s16x4 trrd(LAS const unsigned char* p) { return __builtin_bit_cast(s16x4, __builtin_amdgcn_ds_read_tr16_b64_v4i16((LAS v4i16_t*)p)); }
; __device__ __forceinline__ float attn_tile_exp(f32x16& st, int j, float tlf, float bsl, float rlo, float rhi) {
;     float sum = 0.f;
; #pragma unroll
;     for (int i = 0; i < 16; ++i) { const float tmp = (float)(32 * j - 64 + (i & 3) + 8 * (i >> 2)) + tlf;
;         float arg = __builtin_fmaf(-bsl, __builtin_fabsf(tmp), st[i]);
;         arg = (tmp >= rlo && tmp <= rhi) ? arg : -1.0e30f;
;         const float pe = __builtin_amdgcn_exp2f(arg); st[i] = pe; sum += pe; }
;     return sum;
; template <bool FUSED> __device__ __forceinline__ void attn_phase(const Args& a, LAS unsigned char* lds, int tid, int lane, int wave) {
;     ...
;         for (int j = 0; j < 5; ++j) {
;             f32x16 st;
; #pragma unroll
;             for (int i = 0; i < 16; ++i) st[i] = -mb;
;             LAS const unsigned char* kp = lds + (32 * wave + 32 * j + l31) * KP + 16 * h;
; #pragma unroll
;             for (int ks = 0; ks < 4; ++ks) { const bf16x8 kf = *(LAS const bf16x8*)(kp + 32 * ks); st = __builtin_amdgcn_mfma_f32_32x32x16_bf16(kf, qf[ks], st, 0, 0, 0); }
;             sum += attn_tile_exp(st, j, tlf, bsl, rlo, rhi);
; #pragma unroll
;             for (int s2 = 0; s2 < 2; ++s2) { u32x4 pw; pw.x = pk2(st[8 * s2 + 0], st[8 * s2 + 1]); pw.y = pk2(st[8 * s2 + 2], st[8 * s2 + 3]); pw.z = pk2(st[8 * s2 + 4], st[8 * s2 + 5]); pw.w = pk2(st[8 * s2 + 6], st[8 * s2 + 7]);
;                 const bf16x8 pf = __builtin_bit_cast(bf16x8, pw);
;                 LAS const unsigned char* vp = lds + LDS_VOFF + (32 * wave + 32 * j + 16 * s2 + 4 * h + q) * VP + 32 * blk + 8 * p;
; #pragma unroll
;                 for (int dt = 0; dt < 2; ++dt) { const s16x4 lo = trrd(vp + dt * 64), hi = trrd(vp + 8 * VP + dt * 64);
;                     const bf16x8 vf = __builtin_shufflevector(lo, hi, 0, 1, 2, 3, 4, 5, 6, 7);
;                     o[dt] = __builtin_amdgcn_mfma_f32_32x32x16_bf16(vf, pf, o[dt], 0, 0, 0); } }
;             __builtin_amdgcn_sched_barrier(0);
;         }
	v_mfma_f32_32x32x16_bf16 v[16:31], v[48:51], v[52:55], v[16:31]
	v_fma_f32 v48, v170, |v239|, v63
	s_or_b64 vcc, vcc, s[6:7]
	v_cndmask_b32_e32 v63, v48, v228, vcc
	ds_read_b64_tr_b16 v[48:49], v209 offset:58368
	ds_read_b64_tr_b16 v[50:51], v209 offset:59904
	v_exp_f32_e32 v63, v63
	s_waitcnt lgkmcnt(2)
	v_mfma_f32_32x32x16_bf16 v[0:15], v[56:59], v[52:55], v[0:15]
	ds_read_b64_tr_b16 v[58:59], v209 offset:59968
	ds_read_b64_tr_b16 v[56:57], v209 offset:58432
	v_cvt_pk_bf16_f32 v52, v233, v235
	v_cvt_pk_bf16_f32 v53, v236, v237
	v_cvt_pk_bf16_f32 v54, v60, v61
	v_cvt_pk_bf16_f32 v55, v62, v63
	s_waitcnt lgkmcnt(2)
	s_nop 0
	v_mfma_f32_32x32x16_bf16 v[16:31], v[48:51], v[52:55], v[16:31]
	v_add_f32_e32 v48, v235, v234
	v_add_f32_e32 v48, v236, v48
	v_add_f32_e32 v48, v237, v48
	v_add_f32_e32 v48, v60, v48
	v_add_f32_e32 v48, v61, v48
	v_add_f32_e32 v48, v62, v48
	v_add_f32_e32 v48, v63, v48
	s_waitcnt lgkmcnt(0)
	v_mfma_f32_32x32x16_bf16 v[0:15], v[56:59], v[52:55], v[0:15]
	v_add_f32_e32 v238, v238, v48
	ds_read_b128 v[172:175], v210
	ds_read_b128 v[230:233], v210 offset:32
	v_cmp_nge_f32_e32 vcc, v171, v168
	v_cmp_nle_f32_e64 s[6:7], v171, v169
	v_add_f32_e32 v239, 1.0, v171
	s_waitcnt lgkmcnt(1)
	v_mfma_f32_32x32x16_bf16 v[48:63], v[172:175], v[136:139], v[32:47]
	ds_read_b128 v[172:175], v210 offset:64
	ds_read_b128 v[234:237], v210 offset:96
	v_cmp_nge_f32_e64 s[8:9], v239, v168
	v_cmp_nle_f32_e64 s[10:11], v239, v169
	s_or_b64 vcc, vcc, s[6:7]
	s_waitcnt lgkmcnt(2)
	v_mfma_f32_32x32x16_bf16 v[48:63], v[230:233], v[132:135], v[48:63]
	v_add_f32_e32 v230, 2.0, v171
	v_add_f32_e32 v231, 0x40400000, v171
	v_cmp_nge_f32_e64 s[12:13], v230, v168
	v_cmp_nle_f32_e64 s[14:15], v230, v169
	v_add_f32_e32 v232, 0x41000000, v171
	v_cmp_nge_f32_e64 s[16:17], v231, v168
	v_cmp_nle_f32_e64 s[20:21], v231, v169
	s_waitcnt lgkmcnt(1)
	v_mfma_f32_32x32x16_bf16 v[48:63], v[172:175], v[128:131], v[48:63]
	v_add_f32_e32 v233, 0x41100000, v171
	v_cmp_nge_f32_e64 s[22:23], v232, v168
	v_cmp_nle_f32_e64 s[24:25], v232, v169
	v_cmp_nge_f32_e64 s[26:27], v233, v168
	v_cmp_nle_f32_e64 s[28:29], v233, v169
	s_waitcnt lgkmcnt(0)
	v_mfma_f32_32x32x16_bf16 v[48:63], v[234:237], v[140:143], v[48:63]
	s_nop 11
	v_fma_f32 v48, v170, |v171|, v48
	v_fma_f32 v49, v170, |v239|, v49
	v_cndmask_b32_e32 v48, v48, v228, vcc
	s_or_b64 vcc, s[8:9], s[10:11]
	v_fma_f32 v50, v170, |v230|, v50
	v_cndmask_b32_e32 v49, v49, v228, vcc
	s_or_b64 vcc, s[12:13], s[14:15]
	v_fma_f32 v51, v170, |v231|, v51
	v_cndmask_b32_e32 v50, v50, v228, vcc
	s_or_b64 vcc, s[16:17], s[20:21]
	v_fma_f32 v52, v170, |v232|, v52
	v_cndmask_b32_e32 v51, v51, v228, vcc
	s_or_b64 vcc, s[22:23], s[24:25]
	v_fma_f32 v53, v170, |v233|, v53
	v_cndmask_b32_e32 v52, v52, v228, vcc
	s_or_b64 vcc, s[26:27], s[28:29]
	v_exp_f32_e32 v173, v49
	v_cndmask_b32_e32 v49, v53, v228, vcc
	v_exp_f32_e32 v231, v49
	v_add_f32_e32 v49, 0x41200000, v171
	v_cmp_nge_f32_e32 vcc, v49, v168
	v_cmp_nle_f32_e64 s[6:7], v49, v169
	v_exp_f32_e32 v174, v50
	v_fma_f32 v50, v170, |v49|, v54
	s_or_b64 vcc, vcc, s[6:7]
	v_cndmask_b32_e32 v49, v50, v228, vcc
	v_exp_f32_e32 v172, v48
	v_exp_f32_e32 v232, v49
	v_add_f32_e32 v49, 0x41300000, v171
	v_cmp_nge_f32_e32 vcc, v49, v168
	v_cmp_nle_f32_e64 s[6:7], v49, v169
	v_fma_f32 v50, v170, |v49|, v55
	s_or_b64 vcc, vcc, s[6:7]
	v_exp_f32_e32 v175, v51
	v_cndmask_b32_e32 v49, v50, v228, vcc
	v_exp_f32_e32 v230, v52
	v_add_f32_e32 v48, 0, v172
	v_exp_f32_e32 v55, v49
	v_add_f32_e32 v49, 0x41800000, v171
	v_add_f32_e32 v48, v173, v48
	v_cmp_nge_f32_e32 vcc, v49, v168
	v_cmp_nle_f32_e64 s[6:7], v49, v169
	v_add_f32_e32 v48, v174, v48
	v_fma_f32 v50, v170, |v49|, v56
	s_or_b64 vcc, vcc, s[6:7]
	v_add_f32_e32 v48, v175, v48
	v_cndmask_b32_e32 v49, v50, v228, vcc
	v_add_f32_e32 v48, v230, v48
	v_exp_f32_e32 v233, v49
	v_add_f32_e32 v48, v231, v48
	v_add_f32_e32 v48, v232, v48
	v_add_f32_e32 v48, v55, v48
	v_add_f32_e32 v234, v233, v48
	v_add_f32_e32 v48, 0x41880000, v171
	v_cmp_nge_f32_e32 vcc, v48, v168
	v_cmp_nle_f32_e64 s[6:7], v48, v169
	v_fma_f32 v49, v170, |v48|, v57
	s_or_b64 vcc, vcc, s[6:7]
	v_cndmask_b32_e32 v48, v49, v228, vcc
	v_exp_f32_e32 v235, v48
	v_add_f32_e32 v48, 0x41900000, v171
	v_cmp_nge_f32_e32 vcc, v48, v168
	v_cmp_nle_f32_e64 s[6:7], v48, v169
	v_fma_f32 v49, v170, |v48|, v58
	s_or_b64 vcc, vcc, s[6:7]
	v_cndmask_b32_e32 v48, v49, v228, vcc
	v_exp_f32_e32 v236, v48
	v_add_f32_e32 v48, 0x41980000, v171
	v_cmp_nge_f32_e32 vcc, v48, v168
	v_cmp_nle_f32_e64 s[6:7], v48, v169
	v_fma_f32 v49, v170, |v48|, v59
	s_or_b64 vcc, vcc, s[6:7]
	v_cndmask_b32_e32 v48, v49, v228, vcc
	v_exp_f32_e32 v237, v48
	v_add_f32_e32 v48, 0x41c00000, v171
	v_cmp_nge_f32_e32 vcc, v48, v168
	v_cmp_nle_f32_e64 s[6:7], v48, v169
	v_fma_f32 v49, v170, |v48|, v60
	s_or_b64 vcc, vcc, s[6:7]
	v_cndmask_b32_e32 v48, v49, v228, vcc
	v_exp_f32_e32 v60, v48
	v_add_f32_e32 v48, 0x41c80000, v171
	v_cmp_nge_f32_e32 vcc, v48, v168
	v_cmp_nle_f32_e64 s[6:7], v48, v169
	v_fma_f32 v49, v170, |v48|, v61
	s_or_b64 vcc, vcc, s[6:7]
	v_cndmask_b32_e32 v48, v49, v228, vcc
	v_exp_f32_e32 v61, v48
	v_add_f32_e32 v48, 0x41d00000, v171
	v_cmp_nge_f32_e32 vcc, v48, v168
	v_cmp_nle_f32_e64 s[6:7], v48, v169
	v_fma_f32 v49, v170, |v48|, v62
	s_or_b64 vcc, vcc, s[6:7]
	v_cndmask_b32_e32 v52, v49, v228, vcc
	ds_read_b64_tr_b16 v[48:49], v211 offset:55296
	ds_read_b64_tr_b16 v[50:51], v211 offset:56832
	ds_read_b64_tr_b16 v[58:59], v211 offset:56896
	ds_read_b64_tr_b16 v[56:57], v211 offset:55360
	v_exp_f32_e32 v62, v52
	v_add_f32_e32 v239, 0x41d80000, v171
	v_cvt_pk_bf16_f32 v52, v172, v173
	v_cvt_pk_bf16_f32 v53, v174, v175
	v_cvt_pk_bf16_f32 v54, v230, v231
	v_cvt_pk_bf16_f32 v55, v232, v55
	v_cmp_nge_f32_e32 vcc, v239, v168
	v_cmp_nle_f32_e64 s[6:7], v239, v169
	s_waitcnt lgkmcnt(2)
; #define LAS __attribute__((address_space(3)))
; __device__ __forceinline__ unsigned pk2(float lo, float hi) { f32x2_t v = {lo, hi}; bf16x2_t b = __builtin_convertvector(v, bf16x2_t); return __builtin_bit_cast(unsigned, b); }
; __device__ __forceinline__ s16x4 trrd(LAS const unsigned char* p) { return __builtin_bit_cast(s16x4, __builtin_amdgcn_ds_read_tr16_b64_v4i16((LAS v4i16_t*)p)); }
; __device__ __forceinline__ float attn_tile_exp(f32x16& st, int j, float tlf, float bsl, float rlo, float rhi) {
;     float sum = 0.f;
; #pragma unroll
;     for (int i = 0; i < 16; ++i) { const float tmp = (float)(32 * j - 64 + (i & 3) + 8 * (i >> 2)) + tlf;
;         float arg = __builtin_fmaf(-bsl, __builtin_fabsf(tmp), st[i]);
;         arg = (tmp >= rlo && tmp <= rhi) ? arg : -1.0e30f;
;         const float pe = __builtin_amdgcn_exp2f(arg); st[i] = pe; sum += pe; }
;     return sum;
; template <bool FUSED> __device__ __forceinline__ void attn_phase(const Args& a, LAS unsigned char* lds, int tid, int lane, int wave) {
;     ...
;         for (int j = 0; j < 5; ++j) {
;             f32x16 st;
; #pragma unroll
;             for (int i = 0; i < 16; ++i) st[i] = -mb;
;             LAS const unsigned char* kp = lds + (32 * wave + 32 * j + l31) * KP + 16 * h;
; #pragma unroll
;             for (int ks = 0; ks < 4; ++ks) { const bf16x8 kf = *(LAS const bf16x8*)(kp + 32 * ks); st = __builtin_amdgcn_mfma_f32_32x32x16_bf16(kf, qf[ks], st, 0, 0, 0); }
;             sum += attn_tile_exp(st, j, tlf, bsl, rlo, rhi);
; #pragma unroll
;             for (int s2 = 0; s2 < 2; ++s2) { u32x4 pw; pw.x = pk2(st[8 * s2 + 0], st[8 * s2 + 1]); pw.y = pk2(st[8 * s2 + 2], st[8 * s2 + 3]); pw.z = pk2(st[8 * s2 + 4], st[8 * s2 + 5]); pw.w = pk2(st[8 * s2 + 6], st[8 * s2 + 7]);
;                 const bf16x8 pf = __builtin_bit_cast(bf16x8, pw);
;                 LAS const unsigned char* vp = lds + LDS_VOFF + (32 * wave + 32 * j + 16 * s2 + 4 * h + q) * VP + 32 * blk + 8 * p;
; #pragma unroll
;                 for (int dt = 0; dt < 2; ++dt) { const s16x4 lo = trrd(vp + dt * 64), hi = trrd(vp + 8 * VP + dt * 64);
;                     const bf16x8 vf = __builtin_shufflevector(lo, hi, 0, 1, 2, 3, 4, 5, 6, 7);
;                     o[dt] = __builtin_amdgcn_mfma_f32_32x32x16_bf16(vf, pf, o[dt], 0, 0, 0); } }
;             __builtin_amdgcn_sched_barrier(0);
;         }
	v_mfma_f32_32x32x16_bf16 v[16:31], v[48:51], v[52:55], v[16:31]
	v_fma_f32 v48, v170, |v239|, v63
	s_or_b64 vcc, vcc, s[6:7]
	v_cndmask_b32_e32 v63, v48, v228, vcc
	ds_read_b64_tr_b16 v[48:49], v211 offset:58368
	ds_read_b64_tr_b16 v[50:51], v211 offset:59904
	v_exp_f32_e32 v63, v63
	s_waitcnt lgkmcnt(2)
	v_mfma_f32_32x32x16_bf16 v[0:15], v[56:59], v[52:55], v[0:15]
	ds_read_b64_tr_b16 v[58:59], v211 offset:59968
	ds_read_b64_tr_b16 v[56:57], v211 offset:58432
	v_cvt_pk_bf16_f32 v52, v233, v235
	v_cvt_pk_bf16_f32 v53, v236, v237
	v_cvt_pk_bf16_f32 v54, v60, v61
	v_cvt_pk_bf16_f32 v55, v62, v63
	s_waitcnt lgkmcnt(2)
	s_nop 0
	v_mfma_f32_32x32x16_bf16 v[16:31], v[48:51], v[52:55], v[16:31]
	v_add_f32_e32 v48, v235, v234
	v_add_f32_e32 v48, v236, v48
	v_add_f32_e32 v48, v237, v48
	v_add_f32_e32 v48, v60, v48
	v_add_f32_e32 v48, v61, v48
	v_add_f32_e32 v48, v62, v48
	v_add_f32_e32 v48, v63, v48
	s_waitcnt lgkmcnt(0)
	v_mfma_f32_32x32x16_bf16 v[0:15], v[56:59], v[52:55], v[0:15]
	v_add_f32_e32 v238, v238, v48
	ds_read_b128 v[172:175], v212
	ds_read_b128 v[230:233], v212 offset:32
	v_add_f32_e32 v239, 0x42000000, v171
	v_add_f32_e32 v240, 0x42040000, v171
	v_cmp_nge_f32_e32 vcc, v239, v168
	s_waitcnt lgkmcnt(1)
	v_mfma_f32_32x32x16_bf16 v[48:63], v[172:175], v[136:139], v[32:47]
	ds_read_b128 v[172:175], v212 offset:64
	ds_read_b128 v[234:237], v212 offset:96
	v_cmp_nle_f32_e64 s[6:7], v239, v169
	v_add_f32_e32 v241, 0x42080000, v171
	v_cmp_nge_f32_e64 s[8:9], v240, v168
	v_cmp_nle_f32_e64 s[10:11], v240, v169
	s_or_b64 vcc, vcc, s[6:7]
	v_add_f32_e32 v242, 0x420c0000, v171
	s_waitcnt lgkmcnt(2)
	v_mfma_f32_32x32x16_bf16 v[48:63], v[230:233], v[132:135], v[48:63]
	v_cmp_nge_f32_e64 s[12:13], v241, v168
	v_cmp_nle_f32_e64 s[14:15], v241, v169
	v_add_f32_e32 v230, 0x42200000, v171
	v_cmp_nge_f32_e64 s[16:17], v242, v168
	v_cmp_nle_f32_e64 s[20:21], v242, v169
	v_add_f32_e32 v231, 0x42240000, v171
	v_cmp_nge_f32_e64 s[22:23], v230, v168
	s_waitcnt lgkmcnt(1)
	v_mfma_f32_32x32x16_bf16 v[48:63], v[172:175], v[128:131], v[48:63]
	v_cmp_nle_f32_e64 s[24:25], v230, v169
	v_cmp_nge_f32_e64 s[26:27], v231, v168
	v_cmp_nle_f32_e64 s[28:29], v231, v169
	s_waitcnt lgkmcnt(0)
	v_mfma_f32_32x32x16_bf16 v[48:63], v[234:237], v[140:143], v[48:63]
	s_nop 11
	v_fma_f32 v48, v170, |v239|, v48
	v_fma_f32 v49, v170, |v240|, v49
	v_cndmask_b32_e32 v48, v48, v228, vcc
	s_or_b64 vcc, s[8:9], s[10:11]
	v_fma_f32 v50, v170, |v241|, v50
	v_cndmask_b32_e32 v49, v49, v228, vcc
	s_or_b64 vcc, s[12:13], s[14:15]
	v_fma_f32 v51, v170, |v242|, v51
	v_cndmask_b32_e32 v50, v50, v228, vcc
	s_or_b64 vcc, s[16:17], s[20:21]
	v_fma_f32 v52, v170, |v230|, v52
	v_cndmask_b32_e32 v51, v51, v228, vcc
	s_or_b64 vcc, s[22:23], s[24:25]
	v_fma_f32 v53, v170, |v231|, v53
	v_cndmask_b32_e32 v52, v52, v228, vcc
	s_or_b64 vcc, s[26:27], s[28:29]
	v_exp_f32_e32 v173, v49
	v_cndmask_b32_e32 v49, v53, v228, vcc
	v_exp_f32_e32 v231, v49
	v_add_f32_e32 v49, 0x42280000, v171
	v_cmp_nge_f32_e32 vcc, v49, v168
	v_cmp_nle_f32_e64 s[6:7], v49, v169
	v_exp_f32_e32 v174, v50
	v_fma_f32 v50, v170, |v49|, v54
	s_or_b64 vcc, vcc, s[6:7]
	v_cndmask_b32_e32 v49, v50, v228, vcc
	v_exp_f32_e32 v172, v48
	v_exp_f32_e32 v232, v49
	v_add_f32_e32 v49, 0x422c0000, v171
	v_cmp_nge_f32_e32 vcc, v49, v168
	v_cmp_nle_f32_e64 s[6:7], v49, v169
	v_fma_f32 v50, v170, |v49|, v55
	s_or_b64 vcc, vcc, s[6:7]
	v_exp_f32_e32 v175, v51
	v_cndmask_b32_e32 v49, v50, v228, vcc
	v_exp_f32_e32 v230, v52
	v_add_f32_e32 v48, 0, v172
	v_exp_f32_e32 v55, v49
	v_add_f32_e32 v49, 0x42400000, v171
	v_add_f32_e32 v48, v173, v48
	v_cmp_nge_f32_e32 vcc, v49, v168
	v_cmp_nle_f32_e64 s[6:7], v49, v169
	v_add_f32_e32 v48, v174, v48
	v_fma_f32 v50, v170, |v49|, v56
	s_or_b64 vcc, vcc, s[6:7]
	v_add_f32_e32 v48, v175, v48
	v_cndmask_b32_e32 v49, v50, v228, vcc
	v_add_f32_e32 v48, v230, v48
	v_exp_f32_e32 v233, v49
	v_add_f32_e32 v48, v231, v48
	v_add_f32_e32 v48, v232, v48
	v_add_f32_e32 v48, v55, v48
	v_add_f32_e32 v234, v233, v48
	v_add_f32_e32 v48, 0x42440000, v171
	v_cmp_nge_f32_e32 vcc, v48, v168
	v_cmp_nle_f32_e64 s[6:7], v48, v169
	v_fma_f32 v49, v170, |v48|, v57
	s_or_b64 vcc, vcc, s[6:7]
	v_cndmask_b32_e32 v48, v49, v228, vcc
	v_exp_f32_e32 v235, v48
	v_add_f32_e32 v48, 0x42480000, v171
	v_cmp_nge_f32_e32 vcc, v48, v168
	v_cmp_nle_f32_e64 s[6:7], v48, v169
	v_fma_f32 v49, v170, |v48|, v58
	s_or_b64 vcc, vcc, s[6:7]
	v_cndmask_b32_e32 v48, v49, v228, vcc
	v_exp_f32_e32 v236, v48
	v_add_f32_e32 v48, 0x424c0000, v171
	v_cmp_nge_f32_e32 vcc, v48, v168
	v_cmp_nle_f32_e64 s[6:7], v48, v169
	v_fma_f32 v49, v170, |v48|, v59
	s_or_b64 vcc, vcc, s[6:7]
	v_cndmask_b32_e32 v48, v49, v228, vcc
	v_exp_f32_e32 v237, v48
	v_add_f32_e32 v48, 0x42600000, v171
	v_cmp_nge_f32_e32 vcc, v48, v168
	v_cmp_nle_f32_e64 s[6:7], v48, v169
	v_fma_f32 v49, v170, |v48|, v60
	s_or_b64 vcc, vcc, s[6:7]
	v_cndmask_b32_e32 v48, v49, v228, vcc
	v_exp_f32_e32 v60, v48
	v_add_f32_e32 v48, 0x42640000, v171
	v_cmp_nge_f32_e32 vcc, v48, v168
	v_cmp_nle_f32_e64 s[6:7], v48, v169
	v_fma_f32 v49, v170, |v48|, v61
	s_or_b64 vcc, vcc, s[6:7]
	v_cndmask_b32_e32 v48, v49, v228, vcc
	v_exp_f32_e32 v61, v48
	v_add_f32_e32 v48, 0x42680000, v171
	v_cmp_nge_f32_e32 vcc, v48, v168
	v_cmp_nle_f32_e64 s[6:7], v48, v169
	v_fma_f32 v49, v170, |v48|, v62
	s_or_b64 vcc, vcc, s[6:7]
	v_cndmask_b32_e32 v52, v49, v228, vcc
	ds_read_b64_tr_b16 v[48:49], v213 offset:55296
	ds_read_b64_tr_b16 v[50:51], v213 offset:56832
	ds_read_b64_tr_b16 v[58:59], v213 offset:56896
	ds_read_b64_tr_b16 v[56:57], v213 offset:55360
	v_exp_f32_e32 v62, v52
	v_add_f32_e32 v239, 0x426c0000, v171
	v_cvt_pk_bf16_f32 v52, v172, v173
	v_cvt_pk_bf16_f32 v53, v174, v175
	v_cvt_pk_bf16_f32 v54, v230, v231
	v_cvt_pk_bf16_f32 v55, v232, v55
	v_cmp_nge_f32_e32 vcc, v239, v168
	v_cmp_nle_f32_e64 s[6:7], v239, v169
	s_waitcnt lgkmcnt(2)
; #define LAS __attribute__((address_space(3)))
; __device__ __forceinline__ unsigned pk2(float lo, float hi) { f32x2_t v = {lo, hi}; bf16x2_t b = __builtin_convertvector(v, bf16x2_t); return __builtin_bit_cast(unsigned, b); }
; __device__ __forceinline__ s16x4 trrd(LAS const unsigned char* p) { return __builtin_bit_cast(s16x4, __builtin_amdgcn_ds_read_tr16_b64_v4i16((LAS v4i16_t*)p)); }
; #define ATTN_QLOAD(W) do { const bf16_t* qr_ = Qb + ((size_t)((W).b * 24 + (W).hd) * SEQ + (size_t)((W).r * (W).L + (W).i0 + 32 * wave + l31)) * 64; \
;         _Pragma("unroll") for (int ks_ = 0; ks_ < 4; ++ks_) qv[ks_] = *(const u32x4*)(qr_ + 16 * ks_ + 8 * h); } while (0)
; template <bool FUSED> __device__ __forceinline__ void attn_phase(const Args& a, LAS unsigned char* lds, int tid, int lane, int wave) {
;     ...
;         for (int j = 0; j < 5; ++j) {
;             f32x16 st;
; #pragma unroll
;             for (int i = 0; i < 16; ++i) st[i] = -mb;
;             LAS const unsigned char* kp = lds + (32 * wave + 32 * j + l31) * KP + 16 * h;
; #pragma unroll
;             for (int ks = 0; ks < 4; ++ks) { const bf16x8 kf = *(LAS const bf16x8*)(kp + 32 * ks); st = __builtin_amdgcn_mfma_f32_32x32x16_bf16(kf, qf[ks], st, 0, 0, 0); }
;             sum += attn_tile_exp(st, j, tlf, bsl, rlo, rhi);
; #pragma unroll
;             for (int s2 = 0; s2 < 2; ++s2) { u32x4 pw; pw.x = pk2(st[8 * s2 + 0], st[8 * s2 + 1]); pw.y = pk2(st[8 * s2 + 2], st[8 * s2 + 3]); pw.z = pk2(st[8 * s2 + 4], st[8 * s2 + 5]); pw.w = pk2(st[8 * s2 + 6], st[8 * s2 + 7]);
;                 const bf16x8 pf = __builtin_bit_cast(bf16x8, pw);
;                 LAS const unsigned char* vp = lds + LDS_VOFF + (32 * wave + 32 * j + 16 * s2 + 4 * h + q) * VP + 32 * blk + 8 * p;
; #pragma unroll
;                 for (int dt = 0; dt < 2; ++dt) { const s16x4 lo = trrd(vp + dt * 64), hi = trrd(vp + 8 * VP + dt * 64);
;                     const bf16x8 vf = __builtin_shufflevector(lo, hi, 0, 1, 2, 3, 4, 5, 6, 7);
;                     o[dt] = __builtin_amdgcn_mfma_f32_32x32x16_bf16(vf, pf, o[dt], 0, 0, 0); } }
;             __builtin_amdgcn_sched_barrier(0);
;         }
;         sum += __shfl_xor(sum, 32);
;         if (un < NU) { const AUnit wq = attn_decode(un, HD0, NH); ATTN_QLOAD(wq); }
;         const float inv = __builtin_amdgcn_rcpf(sum);
	v_mfma_f32_32x32x16_bf16 v[16:31], v[48:51], v[52:55], v[16:31]
	v_fma_f32 v48, v170, |v239|, v63
	s_or_b64 vcc, vcc, s[6:7]
	v_cndmask_b32_e32 v63, v48, v228, vcc
	ds_read_b64_tr_b16 v[48:49], v213 offset:58368
	ds_read_b64_tr_b16 v[50:51], v213 offset:59904
	v_exp_f32_e32 v63, v63
	s_waitcnt lgkmcnt(2)
	v_mfma_f32_32x32x16_bf16 v[0:15], v[56:59], v[52:55], v[0:15]
	ds_read_b64_tr_b16 v[58:59], v213 offset:59968
	ds_read_b64_tr_b16 v[56:57], v213 offset:58432
	v_cvt_pk_bf16_f32 v52, v233, v235
	v_cvt_pk_bf16_f32 v53, v236, v237
	v_cvt_pk_bf16_f32 v54, v60, v61
	v_cvt_pk_bf16_f32 v55, v62, v63
	s_waitcnt lgkmcnt(2)
	s_nop 0
	v_mfma_f32_32x32x16_bf16 v[16:31], v[48:51], v[52:55], v[16:31]
	v_add_f32_e32 v48, v235, v234
	v_add_f32_e32 v48, v236, v48
	v_add_f32_e32 v48, v237, v48
	v_add_f32_e32 v48, v60, v48
	v_add_f32_e32 v48, v61, v48
	v_add_f32_e32 v48, v62, v48
	v_add_f32_e32 v48, v63, v48
	s_waitcnt lgkmcnt(0)
	v_mfma_f32_32x32x16_bf16 v[0:15], v[56:59], v[52:55], v[0:15]
	v_add_f32_e32 v60, v238, v48
	ds_read_b128 v[48:51], v214
	ds_read_b128 v[52:55], v214 offset:32
	v_add_f32_e32 v61, 0x42800000, v171
	v_add_f32_e32 v62, 0x42820000, v171
	v_cmp_nge_f32_e32 vcc, v61, v168
	s_waitcnt lgkmcnt(1)
	v_mfma_f32_32x32x16_bf16 v[32:47], v[48:51], v[136:139], v[32:47]
	ds_read_b128 v[48:51], v214 offset:64
	ds_read_b128 v[56:59], v214 offset:96
	v_cmp_nle_f32_e64 s[6:7], v61, v169
	v_add_f32_e32 v63, 0x42840000, v171
	v_cmp_nge_f32_e64 s[8:9], v62, v168
	v_cmp_nle_f32_e64 s[10:11], v62, v169
	s_or_b64 vcc, vcc, s[6:7]
	v_add_f32_e32 v136, 0x42860000, v171
	s_waitcnt lgkmcnt(2)
	v_mfma_f32_32x32x16_bf16 v[32:47], v[52:55], v[132:135], v[32:47]
	v_cmp_nge_f32_e64 s[12:13], v63, v168
	v_cmp_nle_f32_e64 s[14:15], v63, v169
	v_add_f32_e32 v52, 0x42900000, v171
	v_cmp_nge_f32_e64 s[16:17], v136, v168
	v_cmp_nle_f32_e64 s[20:21], v136, v169
	v_add_f32_e32 v53, 0x42920000, v171
	v_cmp_nge_f32_e64 s[22:23], v52, v168
	s_waitcnt lgkmcnt(1)
	v_mfma_f32_32x32x16_bf16 v[32:47], v[48:51], v[128:131], v[32:47]
	v_cmp_nle_f32_e64 s[24:25], v52, v169
	v_cmp_nge_f32_e64 s[26:27], v53, v168
	v_cmp_nle_f32_e64 s[28:29], v53, v169
	s_waitcnt lgkmcnt(0)
	v_mfma_f32_32x32x16_bf16 v[32:47], v[56:59], v[140:143], v[32:47]
	s_nop 11
	v_fma_f32 v32, v170, |v61|, v32
	v_fma_f32 v33, v170, |v62|, v33
	v_cndmask_b32_e32 v32, v32, v228, vcc
	s_or_b64 vcc, s[8:9], s[10:11]
	v_fma_f32 v34, v170, |v63|, v34
	v_cndmask_b32_e32 v33, v33, v228, vcc
	s_or_b64 vcc, s[12:13], s[14:15]
	v_fma_f32 v35, v170, |v136|, v35
	v_cndmask_b32_e32 v34, v34, v228, vcc
	s_or_b64 vcc, s[16:17], s[20:21]
	v_fma_f32 v36, v170, |v52|, v36
	v_cndmask_b32_e32 v35, v35, v228, vcc
	s_or_b64 vcc, s[22:23], s[24:25]
	v_fma_f32 v37, v170, |v53|, v37
	v_cndmask_b32_e32 v36, v36, v228, vcc
	s_or_b64 vcc, s[26:27], s[28:29]
	v_exp_f32_e32 v49, v33
	v_cndmask_b32_e32 v33, v37, v228, vcc
	v_exp_f32_e32 v53, v33
	v_add_f32_e32 v33, 0x42940000, v171
	v_cmp_nge_f32_e32 vcc, v33, v168
	v_cmp_nle_f32_e64 s[6:7], v33, v169
	v_exp_f32_e32 v50, v34
	v_fma_f32 v34, v170, |v33|, v38
	s_or_b64 vcc, vcc, s[6:7]
	v_cndmask_b32_e32 v33, v34, v228, vcc
	v_exp_f32_e32 v48, v32
	v_exp_f32_e32 v54, v33
	v_add_f32_e32 v33, 0x42960000, v171
	v_cmp_nge_f32_e32 vcc, v33, v168
	v_cmp_nle_f32_e64 s[6:7], v33, v169
	v_fma_f32 v34, v170, |v33|, v39
	s_or_b64 vcc, vcc, s[6:7]
	v_exp_f32_e32 v51, v35
	v_cndmask_b32_e32 v33, v34, v228, vcc
	v_exp_f32_e32 v52, v36
	v_add_f32_e32 v32, 0, v48
	v_exp_f32_e32 v39, v33
	v_add_f32_e32 v33, 0x42a00000, v171
	v_add_f32_e32 v32, v49, v32
	v_cmp_nge_f32_e32 vcc, v33, v168
	v_cmp_nle_f32_e64 s[6:7], v33, v169
	v_add_f32_e32 v32, v50, v32
	v_fma_f32 v34, v170, |v33|, v40
	s_or_b64 vcc, vcc, s[6:7]
	v_add_f32_e32 v32, v51, v32
	v_cndmask_b32_e32 v33, v34, v228, vcc
	v_add_f32_e32 v32, v52, v32
	v_exp_f32_e32 v55, v33
	v_add_f32_e32 v32, v53, v32
	v_add_f32_e32 v32, v54, v32
	v_add_f32_e32 v32, v39, v32
	v_add_f32_e32 v56, v55, v32
	v_add_f32_e32 v32, 0x42a20000, v171
	v_cmp_nge_f32_e32 vcc, v32, v168
	v_cmp_nle_f32_e64 s[6:7], v32, v169
	v_fma_f32 v33, v170, |v32|, v41
	s_or_b64 vcc, vcc, s[6:7]
	v_cndmask_b32_e32 v32, v33, v228, vcc
	v_exp_f32_e32 v57, v32
	v_add_f32_e32 v32, 0x42a40000, v171
	v_cmp_nge_f32_e32 vcc, v32, v168
	v_cmp_nle_f32_e64 s[6:7], v32, v169
	v_fma_f32 v33, v170, |v32|, v42
	s_or_b64 vcc, vcc, s[6:7]
	v_cndmask_b32_e32 v32, v33, v228, vcc
	v_exp_f32_e32 v58, v32
	v_add_f32_e32 v32, 0x42a60000, v171
	v_cmp_nge_f32_e32 vcc, v32, v168
	v_cmp_nle_f32_e64 s[6:7], v32, v169
	v_fma_f32 v33, v170, |v32|, v43
	s_or_b64 vcc, vcc, s[6:7]
	v_cndmask_b32_e32 v32, v33, v228, vcc
	v_exp_f32_e32 v59, v32
	v_add_f32_e32 v32, 0x42b00000, v171
	v_cmp_nge_f32_e32 vcc, v32, v168
	v_cmp_nle_f32_e64 s[6:7], v32, v169
	v_fma_f32 v33, v170, |v32|, v44
	s_or_b64 vcc, vcc, s[6:7]
	v_cndmask_b32_e32 v32, v33, v228, vcc
	v_exp_f32_e32 v44, v32
	v_add_f32_e32 v32, 0x42b20000, v171
	v_cmp_nge_f32_e32 vcc, v32, v168
	v_cmp_nle_f32_e64 s[6:7], v32, v169
	v_fma_f32 v33, v170, |v32|, v45
	s_or_b64 vcc, vcc, s[6:7]
	v_cndmask_b32_e32 v32, v33, v228, vcc
	v_exp_f32_e32 v45, v32
	v_add_f32_e32 v32, 0x42b40000, v171
	v_cmp_nge_f32_e32 vcc, v32, v168
	v_cmp_nle_f32_e64 s[6:7], v32, v169
	v_fma_f32 v33, v170, |v32|, v46
	s_or_b64 vcc, vcc, s[6:7]
	v_cndmask_b32_e32 v36, v33, v228, vcc
	ds_read_b64_tr_b16 v[32:33], v215 offset:55296
	ds_read_b64_tr_b16 v[34:35], v215 offset:56832
	ds_read_b64_tr_b16 v[42:43], v215 offset:56896
	ds_read_b64_tr_b16 v[40:41], v215 offset:55360
	v_exp_f32_e32 v46, v36
	v_add_f32_e32 v61, 0x42b60000, v171
	v_cvt_pk_bf16_f32 v36, v48, v49
	v_cvt_pk_bf16_f32 v37, v50, v51
	v_cvt_pk_bf16_f32 v38, v52, v53
	v_cvt_pk_bf16_f32 v39, v54, v39
	v_cmp_nge_f32_e32 vcc, v61, v168
	v_cmp_nle_f32_e64 s[6:7], v61, v169
	s_waitcnt lgkmcnt(2)
	v_mfma_f32_32x32x16_bf16 v[16:31], v[32:35], v[36:39], v[16:31]
	v_fma_f32 v32, v170, |v61|, v47
	s_or_b64 vcc, vcc, s[6:7]
	v_cndmask_b32_e32 v47, v32, v228, vcc
	ds_read_b64_tr_b16 v[32:33], v215 offset:58368
	ds_read_b64_tr_b16 v[34:35], v215 offset:59904
	v_exp_f32_e32 v47, v47
	s_waitcnt lgkmcnt(2)
	v_mfma_f32_32x32x16_bf16 v[0:15], v[40:43], v[36:39], v[0:15]
	ds_read_b64_tr_b16 v[42:43], v215 offset:59968
	ds_read_b64_tr_b16 v[40:41], v215 offset:58432
	v_cvt_pk_bf16_f32 v36, v55, v57
	v_cvt_pk_bf16_f32 v37, v58, v59
	v_cvt_pk_bf16_f32 v38, v44, v45
	v_cvt_pk_bf16_f32 v39, v46, v47
	s_waitcnt lgkmcnt(2)
	s_nop 0
	v_mfma_f32_32x32x16_bf16 v[16:31], v[32:35], v[36:39], v[16:31]
	v_add_f32_e32 v32, v57, v56
	v_add_f32_e32 v32, v58, v32
	v_add_f32_e32 v32, v59, v32
	v_add_f32_e32 v32, v44, v32
	v_add_f32_e32 v32, v45, v32
	v_add_f32_e32 v32, v46, v32
	v_add_f32_e32 v32, v47, v32
	s_waitcnt lgkmcnt(0)
	v_mfma_f32_32x32x16_bf16 v[0:15], v[40:43], v[36:39], v[0:15]
	v_add_f32_e32 v236, v60, v32
	ds_bpermute_b32 v237, v151, v236
	s_andn2_b64 vcc, exec, s[44:45]
	s_cbranch_vccnz .LBB0_406
; #define ATTN_QLOAD(W) do { const bf16_t* qr_ = Qb + ((size_t)((W).b * 24 + (W).hd) * SEQ + (size_t)((W).r * (W).L + (W).i0 + 32 * wave + l31)) * 64; \
;         _Pragma("unroll") for (int ks_ = 0; ks_ < 4; ++ks_) qv[ks_] = *(const u32x4*)(qr_ + 16 * ks_ + 8 * h); } while (0)
; template <bool FUSED> __device__ __forceinline__ void attn_phase(const Args& a, LAS unsigned char* lds, int tid, int lane, int wave) {
;     ...
;         if (un < NU) { const AUnit wq = attn_decode(un, HD0, NH); ATTN_QLOAD(wq); }
	s_ashr_i32 s7, s64, 5
	s_lshr_b32 s8, s7, 29
	s_add_i32 s8, s7, s8
	s_and_b32 s8, s8, -8
	s_sub_i32 s7, s7, s8
	s_ashr_i32 s9, s7, 2
	s_ashr_i32 s8, s64, 31
	s_and_b32 s9, s9, -2
	s_lshr_b32 s8, s8, 24
	s_lshr_b32 s10, 32, s9
	s_and_b32 s6, s64, 31
	s_add_i32 s8, s64, s8
	s_lshr_b32 s11, 0x2000, s9
	s_sub_i32 s9, 5, s9
	s_add_i32 s10, s10, -1
	s_ashr_i32 s8, s8, 8
	s_lshr_b32 s9, s6, s9
	s_and_b32 s6, s10, s6
	s_lshl_b32 s10, s6, 8
	s_mul_i32 s6, s8, 24
	s_add_i32 s6, s6, s7
	s_mul_i32 s9, s9, s11
	s_ashr_i32 s7, s6, 31
	s_add_i32 s10, s10, s9
	v_add_u32_e32 v32, s10, v187
	s_lshl_b64 s[6:7], s[6:7], 20
	v_ashrrev_i32_e32 v33, 31, v32
	s_add_u32 s6, s40, s6
	s_addc_u32 s7, s41, s7
	v_lshlrev_b64 v[32:33], 7, v[32:33]
	v_lshl_add_u64 v[32:33], s[6:7], 0, v[32:33]
	v_lshl_add_u64 v[32:33], v[148:149], 1, v[32:33]
	global_load_dwordx4 v[96:99], v[32:33], off
	global_load_dwordx4 v[100:103], v[32:33], off offset:32
	global_load_dwordx4 v[104:107], v[32:33], off offset:64
	global_load_dwordx4 v[108:111], v[32:33], off offset:96
